# GEMM K-loops: mid-segment s_setprio 0/1 flip pair between the two 16-MFMA groups removed (priority stays raised across the 32 MFMAs)
# speedup vs baseline: 1.0067x; 1.0067x over previous
; #define PG8_STAGE(bufoff, gbase, voff) do { _Pragma("unroll") for (int _i = 0; _i < 2; ++_i) \
;         __builtin_amdgcn_global_load_lds((const unsigned*)((const char*)(gbase) + (voff)[_i]), (LAS unsigned*)(lds + (bufoff) + ldsw + _i * 8192), 16, 0, 0); } while (0)
; #define PG8_LDA(dst, b, h) do { _Pragma("unroll") for (int m = 0; m < 4; ++m) _Pragma("unroll") for (int k = 0; k < 2; ++k) dst[m][k] = *(const LAS bf16x8*)(lds + PG8_SA(b, h) + aoff + m * 2048 + k * 1024); } while (0)
; #define PG8_LDB(dst, b, h) do { _Pragma("unroll") for (int n = 0; n < 2; ++n) _Pragma("unroll") for (int k = 0; k < 2; ++k) dst[n][k] = *(const LAS bf16x8*)(lds + PG8_SB(b, h) + boff + n * 2048 + k * 1024); } while (0)
; #define PG8_MMA(ai, bj, At, Bt) do { __builtin_amdgcn_s_setprio(1); _Pragma("unroll") for (int m = 0; m < 4; ++m) _Pragma("unroll") for (int n = 0; n < 2; ++n) _Pragma("unroll") for (int k = 0; k < 2; ++k) \
;         acc[ai][bj][m][n] = __builtin_amdgcn_mfma_f32_16x16x32_bf16(Bt[n][k], At[m][k], acc[ai][bj][m][n], 0, 0, 0); __builtin_amdgcn_s_setprio(0); } while (0)
; #define PG8_WAIT_V(n) asm volatile("s_waitcnt vmcnt(" #n ")" ::: "memory")
; #define PG8_WAIT_L(n) asm volatile("s_waitcnt lgkmcnt(" #n ")" ::: "memory")
; template <class Epi, class Sched, bool ALIGN_EPI, bool LAST_FUSED = false, bool PERM = false, bool CARRY = false>
; __device__ __forceinline__ void gemm_phase(LAS unsigned char* lds, const int tid, const int K, const int lda, const int ldb, const Sched& S, const Epi& E) {
;     ...
;         for (int t = 0; t < nt; t += 2) {
;             const bool last = (t == nt - 2);
;             const char* a1 = cA + (size_t)(t + 1) * kstep;
;             const char* a2 = last ? nA : cA + (size_t)(t + 2) * kstep; const char* b2 = last ? nB : cB + (size_t)(t + 2) * kstep;
;             const char* a3 = a2 + kstep; const char* b3 = b2 + kstep;
;             PG8_LDB(B0, 0, 0); PG8_LDB(B1, 0, 1); PG8_SCHED; PG8_LDA(At, 0, 0); PG8_STAGE(PG8_SA(1, 1), a1 + hstepA, voffA);
;             PG8_WAIT_V(8); PG8_WAIT_L(0); PG8_BAR; PG8_MMA(0, 0, At, B0); PG8_MMA(0, 1, At, B1); PG8_BAR; PG8_SCHED;
;             PG8_LDA(At, 0, 1); PG8_STAGE(PG8_SB(0, 0), b2, voffB); PG8_STAGE(PG8_SB(0, 1), b2 + hstepB, voffB); PG8_STAGE(PG8_SA(0, 0), a2, voffA);
;             PG8_WAIT_V(8); PG8_WAIT_L(0); PG8_BAR; PG8_MMA(1, 0, At, B0); PG8_MMA(1, 1, At, B1); PG8_BAR; PG8_SCHED;
.LBB0_279:
	s_add_u32 s4, s2, 0xfff80080
	s_addc_u32 s5, s3, -1
	s_add_i32 s28, 0, 0x10000
	s_cmp_eq_u32 s27, 28
	s_cselect_b32 s37, s43, s5
	s_cselect_b32 s36, s42, s4
	s_cselect_b32 s5, s71, s23
	s_cselect_b32 s4, s70, s22
	s_add_i32 s31, 0, 0x14000
	v_add_u32_e32 v154, s28, v144
	v_add_u32_e32 v170, s31, v144
	ds_read_b128 v[136:139], v154
	ds_read_b128 v[146:149], v154 offset:1024
	ds_read_b128 v[150:153], v154 offset:2048
	ds_read_b128 v[154:157], v154 offset:3072
	ds_read_b128 v[158:161], v170
	ds_read_b128 v[162:165], v170 offset:1024
	ds_read_b128 v[166:169], v170 offset:2048
	ds_read_b128 v[170:173], v170 offset:3072
	v_lshl_add_u64 v[206:207], s[2:3], 0, v[132:133]
	s_add_i32 m0, s52, 0xc000
	ds_read_b128 v[174:177], v145
	ds_read_b128 v[178:181], v145 offset:1024
	ds_read_b128 v[182:185], v145 offset:2048
	ds_read_b128 v[186:189], v145 offset:3072
	ds_read_b128 v[190:193], v145 offset:4096
	ds_read_b128 v[194:197], v145 offset:5120
	ds_read_b128 v[198:201], v145 offset:6144
	ds_read_b128 v[202:205], v145 offset:7168
	global_load_lds_dwordx4 v[206:207], off
	v_lshl_add_u64 v[206:207], s[2:3], 0, v[134:135]
	s_add_i32 m0, s52, 0xe000
	s_nop 0
	global_load_lds_dwordx4 v[206:207], off
	s_waitcnt vmcnt(8)
	s_waitcnt lgkmcnt(0)
	s_barrier
	s_setprio 1
	s_waitcnt lgkmcnt(0)
	v_mfma_f32_16x16x32_bf16 v[126:129], v[136:139], v[174:177], v[126:129]
	v_mfma_f32_16x16x32_bf16 v[122:125], v[150:153], v[174:177], v[122:125]
	v_mfma_f32_16x16x32_bf16 v[110:113], v[136:139], v[182:185], v[110:113]
	v_mfma_f32_16x16x32_bf16 v[106:109], v[150:153], v[182:185], v[106:109]
	v_mfma_f32_16x16x32_bf16 v[94:97], v[136:139], v[190:193], v[94:97]
	v_mfma_f32_16x16x32_bf16 v[90:93], v[150:153], v[190:193], v[90:93]
	v_mfma_f32_16x16x32_bf16 v[78:81], v[136:139], v[198:201], v[78:81]
	v_mfma_f32_16x16x32_bf16 v[74:77], v[150:153], v[198:201], v[74:77]
	v_mfma_f32_16x16x32_bf16 v[126:129], v[146:149], v[178:181], v[126:129]
	v_mfma_f32_16x16x32_bf16 v[122:125], v[154:157], v[178:181], v[122:125]
	v_mfma_f32_16x16x32_bf16 v[110:113], v[146:149], v[186:189], v[110:113]
	v_mfma_f32_16x16x32_bf16 v[106:109], v[154:157], v[186:189], v[106:109]
	v_mfma_f32_16x16x32_bf16 v[94:97], v[146:149], v[194:197], v[94:97]
	v_mfma_f32_16x16x32_bf16 v[90:93], v[154:157], v[194:197], v[90:93]
	v_mfma_f32_16x16x32_bf16 v[78:81], v[146:149], v[202:205], v[78:81]
	v_mfma_f32_16x16x32_bf16 v[74:77], v[154:157], v[202:205], v[74:77]
	v_mfma_f32_16x16x32_bf16 v[118:121], v[158:161], v[174:177], v[118:121]
	v_mfma_f32_16x16x32_bf16 v[114:117], v[166:169], v[174:177], v[114:117]
	v_mfma_f32_16x16x32_bf16 v[102:105], v[158:161], v[182:185], v[102:105]
	v_mfma_f32_16x16x32_bf16 v[98:101], v[166:169], v[182:185], v[98:101]
	v_mfma_f32_16x16x32_bf16 v[86:89], v[158:161], v[190:193], v[86:89]
	v_mfma_f32_16x16x32_bf16 v[82:85], v[166:169], v[190:193], v[82:85]
	v_mfma_f32_16x16x32_bf16 v[70:73], v[158:161], v[198:201], v[70:73]
	v_mfma_f32_16x16x32_bf16 v[66:69], v[166:169], v[198:201], v[66:69]
	v_mfma_f32_16x16x32_bf16 v[118:121], v[162:165], v[178:181], v[118:121]
	v_mfma_f32_16x16x32_bf16 v[114:117], v[170:173], v[178:181], v[114:117]
	v_mfma_f32_16x16x32_bf16 v[102:105], v[162:165], v[186:189], v[102:105]
	v_mfma_f32_16x16x32_bf16 v[98:101], v[170:173], v[186:189], v[98:101]
	v_mfma_f32_16x16x32_bf16 v[86:89], v[162:165], v[194:197], v[86:89]
	v_mfma_f32_16x16x32_bf16 v[82:85], v[170:173], v[194:197], v[82:85]
	v_mfma_f32_16x16x32_bf16 v[70:73], v[162:165], v[202:205], v[70:73]
	v_mfma_f32_16x16x32_bf16 v[66:69], v[170:173], v[202:205], v[66:69]
	s_setprio 0
	s_barrier
	s_add_i32 s28, s28, s51
	v_lshl_add_u64 v[206:207], s[4:5], 0, v[0:1]
	s_mov_b32 m0, s28
	ds_read_b128 v[174:177], v145 offset:16384
	ds_read_b128 v[178:181], v145 offset:17408
	ds_read_b128 v[182:185], v145 offset:18432
	ds_read_b128 v[186:189], v145 offset:19456
	ds_read_b128 v[190:193], v145 offset:20480
	ds_read_b128 v[194:197], v145 offset:21504
	ds_read_b128 v[198:201], v145 offset:22528
	ds_read_b128 v[202:205], v145 offset:23552
	global_load_lds_dwordx4 v[206:207], off
	s_add_i32 m0, s28, 0x2000
	s_add_u32 s28, s4, 0x80000
	v_lshl_add_u64 v[208:209], s[4:5], 0, v[130:131]
	s_addc_u32 s29, s5, 0
	s_add_i32 s31, s31, s51
	global_load_lds_dwordx4 v[208:209], off
	v_lshl_add_u64 v[210:211], s[28:29], 0, v[0:1]
	s_mov_b32 m0, s31
	v_lshl_add_u64 v[212:213], s[36:37], 0, v[130:131]
	global_load_lds_dwordx4 v[210:211], off
	v_lshl_add_u64 v[210:211], s[28:29], 0, v[130:131]
	s_add_i32 m0, s31, 0x2000
	s_nop 0
	global_load_lds_dwordx4 v[210:211], off
	v_lshl_add_u64 v[210:211], s[36:37], 0, v[0:1]
	s_mov_b32 m0, s52
	s_nop 0
	global_load_lds_dwordx4 v[210:211], off
	s_mov_b32 m0, s53
	s_nop 0
	global_load_lds_dwordx4 v[212:213], off
	s_waitcnt vmcnt(8)
	s_waitcnt lgkmcnt(0)
	s_barrier
; #define PG8_STAGE(bufoff, gbase, voff) do { _Pragma("unroll") for (int _i = 0; _i < 2; ++_i) \
;         __builtin_amdgcn_global_load_lds((const unsigned*)((const char*)(gbase) + (voff)[_i]), (LAS unsigned*)(lds + (bufoff) + ldsw + _i * 8192), 16, 0, 0); } while (0)
; #define PG8_LDA(dst, b, h) do { _Pragma("unroll") for (int m = 0; m < 4; ++m) _Pragma("unroll") for (int k = 0; k < 2; ++k) dst[m][k] = *(const LAS bf16x8*)(lds + PG8_SA(b, h) + aoff + m * 2048 + k * 1024); } while (0)
; #define PG8_LDB(dst, b, h) do { _Pragma("unroll") for (int n = 0; n < 2; ++n) _Pragma("unroll") for (int k = 0; k < 2; ++k) dst[n][k] = *(const LAS bf16x8*)(lds + PG8_SB(b, h) + boff + n * 2048 + k * 1024); } while (0)
; #define PG8_MMA(ai, bj, At, Bt) do { __builtin_amdgcn_s_setprio(1); _Pragma("unroll") for (int m = 0; m < 4; ++m) _Pragma("unroll") for (int n = 0; n < 2; ++n) _Pragma("unroll") for (int k = 0; k < 2; ++k) \
;         acc[ai][bj][m][n] = __builtin_amdgcn_mfma_f32_16x16x32_bf16(Bt[n][k], At[m][k], acc[ai][bj][m][n], 0, 0, 0); __builtin_amdgcn_s_setprio(0); } while (0)
; #define PG8_WAIT_V(n) asm volatile("s_waitcnt vmcnt(" #n ")" ::: "memory")
; #define PG8_WAIT_L(n) asm volatile("s_waitcnt lgkmcnt(" #n ")" ::: "memory")
; #define PG8_BAR __builtin_amdgcn_s_barrier()
; #define PG8_SCHED __builtin_amdgcn_sched_barrier(0)
; template <class Epi, class Sched, bool ALIGN_EPI, bool LAST_FUSED = false, bool PERM = false, bool CARRY = false>
; __device__ __forceinline__ void gemm_phase(LAS unsigned char* lds, const int tid, const int K, const int lda, const int ldb, const Sched& S, const Epi& E) {
;     ...
;             PG8_WAIT_V(8); PG8_WAIT_L(0); PG8_BAR; PG8_MMA(1, 0, At, B0); PG8_MMA(1, 1, At, B1); PG8_BAR; PG8_SCHED;
;             PG8_LDB(B0, 1, 0); PG8_LDB(B1, 1, 1); PG8_SCHED; PG8_LDA(At, 1, 0); PG8_STAGE(PG8_SA(0, 1), a2 + hstepA, voffA);
;             PG8_WAIT_V(8); PG8_WAIT_L(0); PG8_BAR; PG8_MMA(0, 0, At, B0); PG8_MMA(0, 1, At, B1); PG8_BAR; PG8_SCHED;
	s_setprio 1
	s_waitcnt lgkmcnt(0)
	v_mfma_f32_16x16x32_bf16 v[62:65], v[136:139], v[174:177], v[62:65]
	v_mfma_f32_16x16x32_bf16 v[58:61], v[150:153], v[174:177], v[58:61]
	v_mfma_f32_16x16x32_bf16 v[46:49], v[136:139], v[182:185], v[46:49]
	v_mfma_f32_16x16x32_bf16 v[42:45], v[150:153], v[182:185], v[42:45]
	v_mfma_f32_16x16x32_bf16 v[30:33], v[136:139], v[190:193], v[30:33]
	v_mfma_f32_16x16x32_bf16 v[26:29], v[150:153], v[190:193], v[26:29]
	v_mfma_f32_16x16x32_bf16 v[14:17], v[136:139], v[198:201], v[14:17]
	v_mfma_f32_16x16x32_bf16 v[10:13], v[150:153], v[198:201], v[10:13]
	v_mfma_f32_16x16x32_bf16 v[62:65], v[146:149], v[178:181], v[62:65]
	v_mfma_f32_16x16x32_bf16 v[58:61], v[154:157], v[178:181], v[58:61]
	v_mfma_f32_16x16x32_bf16 v[46:49], v[146:149], v[186:189], v[46:49]
	v_mfma_f32_16x16x32_bf16 v[42:45], v[154:157], v[186:189], v[42:45]
	v_mfma_f32_16x16x32_bf16 v[30:33], v[146:149], v[194:197], v[30:33]
	v_mfma_f32_16x16x32_bf16 v[26:29], v[154:157], v[194:197], v[26:29]
	v_mfma_f32_16x16x32_bf16 v[14:17], v[146:149], v[202:205], v[14:17]
	v_mfma_f32_16x16x32_bf16 v[10:13], v[154:157], v[202:205], v[10:13]
	v_mfma_f32_16x16x32_bf16 v[54:57], v[158:161], v[174:177], v[54:57]
	v_mfma_f32_16x16x32_bf16 v[50:53], v[166:169], v[174:177], v[50:53]
	v_mfma_f32_16x16x32_bf16 v[38:41], v[158:161], v[182:185], v[38:41]
	v_mfma_f32_16x16x32_bf16 v[34:37], v[166:169], v[182:185], v[34:37]
	v_mfma_f32_16x16x32_bf16 v[22:25], v[158:161], v[190:193], v[22:25]
	v_mfma_f32_16x16x32_bf16 v[18:21], v[166:169], v[190:193], v[18:21]
	v_mfma_f32_16x16x32_bf16 v[6:9], v[158:161], v[198:201], v[6:9]
	v_mfma_f32_16x16x32_bf16 v[2:5], v[166:169], v[198:201], v[2:5]
	v_mfma_f32_16x16x32_bf16 v[54:57], v[162:165], v[178:181], v[54:57]
	v_mfma_f32_16x16x32_bf16 v[50:53], v[170:173], v[178:181], v[50:53]
	v_mfma_f32_16x16x32_bf16 v[38:41], v[162:165], v[186:189], v[38:41]
	v_mfma_f32_16x16x32_bf16 v[34:37], v[170:173], v[186:189], v[34:37]
	v_mfma_f32_16x16x32_bf16 v[22:25], v[162:165], v[194:197], v[22:25]
	v_mfma_f32_16x16x32_bf16 v[18:21], v[170:173], v[194:197], v[18:21]
	v_mfma_f32_16x16x32_bf16 v[6:9], v[162:165], v[202:205], v[6:9]
	v_mfma_f32_16x16x32_bf16 v[2:5], v[170:173], v[202:205], v[2:5]
	s_setprio 0
	s_barrier
	s_add_i32 s31, 0, 0x18000
	s_add_i32 s35, 0, 0x1c000
	v_add_u32_e32 v154, s31, v144
	v_add_u32_e32 v170, s35, v144
	ds_read_b128 v[136:139], v154
	ds_read_b128 v[146:149], v154 offset:1024
	ds_read_b128 v[150:153], v154 offset:2048
	ds_read_b128 v[154:157], v154 offset:3072
	ds_read_b128 v[158:161], v170
	ds_read_b128 v[162:165], v170 offset:1024
	ds_read_b128 v[166:169], v170 offset:2048
	ds_read_b128 v[170:173], v170 offset:3072
	s_add_u32 s28, s36, 0x80000
	s_addc_u32 s29, s37, 0
	s_mov_b32 m0, s54
	v_lshl_add_u64 v[214:215], s[28:29], 0, v[0:1]
	ds_read_b128 v[174:177], v145 offset:32768
	ds_read_b128 v[178:181], v145 offset:33792
	ds_read_b128 v[182:185], v145 offset:34816
	ds_read_b128 v[186:189], v145 offset:35840
	ds_read_b128 v[190:193], v145 offset:36864
	ds_read_b128 v[194:197], v145 offset:37888
	ds_read_b128 v[198:201], v145 offset:38912
	ds_read_b128 v[202:205], v145 offset:39936
	global_load_lds_dwordx4 v[214:215], off
	v_lshl_add_u64 v[214:215], s[28:29], 0, v[130:131]
	s_mov_b32 m0, s55
	s_nop 0
	global_load_lds_dwordx4 v[214:215], off
	s_waitcnt vmcnt(8)
	s_waitcnt lgkmcnt(0)
	s_barrier
	s_setprio 1
	s_waitcnt lgkmcnt(0)
	v_mfma_f32_16x16x32_bf16 v[126:129], v[136:139], v[174:177], v[126:129]
	v_mfma_f32_16x16x32_bf16 v[122:125], v[150:153], v[174:177], v[122:125]
	v_mfma_f32_16x16x32_bf16 v[110:113], v[136:139], v[182:185], v[110:113]
	v_mfma_f32_16x16x32_bf16 v[106:109], v[150:153], v[182:185], v[106:109]
	v_mfma_f32_16x16x32_bf16 v[94:97], v[136:139], v[190:193], v[94:97]
	v_mfma_f32_16x16x32_bf16 v[90:93], v[150:153], v[190:193], v[90:93]
	v_mfma_f32_16x16x32_bf16 v[78:81], v[136:139], v[198:201], v[78:81]
	v_mfma_f32_16x16x32_bf16 v[74:77], v[150:153], v[198:201], v[74:77]
	v_mfma_f32_16x16x32_bf16 v[126:129], v[146:149], v[178:181], v[126:129]
	v_mfma_f32_16x16x32_bf16 v[122:125], v[154:157], v[178:181], v[122:125]
	v_mfma_f32_16x16x32_bf16 v[110:113], v[146:149], v[186:189], v[110:113]
	v_mfma_f32_16x16x32_bf16 v[106:109], v[154:157], v[186:189], v[106:109]
	v_mfma_f32_16x16x32_bf16 v[94:97], v[146:149], v[194:197], v[94:97]
	v_mfma_f32_16x16x32_bf16 v[90:93], v[154:157], v[194:197], v[90:93]
	v_mfma_f32_16x16x32_bf16 v[78:81], v[146:149], v[202:205], v[78:81]
	v_mfma_f32_16x16x32_bf16 v[74:77], v[154:157], v[202:205], v[74:77]
	v_mfma_f32_16x16x32_bf16 v[118:121], v[158:161], v[174:177], v[118:121]
	v_mfma_f32_16x16x32_bf16 v[114:117], v[166:169], v[174:177], v[114:117]
	v_mfma_f32_16x16x32_bf16 v[102:105], v[158:161], v[182:185], v[102:105]
	v_mfma_f32_16x16x32_bf16 v[98:101], v[166:169], v[182:185], v[98:101]
	v_mfma_f32_16x16x32_bf16 v[86:89], v[158:161], v[190:193], v[86:89]
	v_mfma_f32_16x16x32_bf16 v[82:85], v[166:169], v[190:193], v[82:85]
	v_mfma_f32_16x16x32_bf16 v[70:73], v[158:161], v[198:201], v[70:73]
	v_mfma_f32_16x16x32_bf16 v[66:69], v[166:169], v[198:201], v[66:69]
	v_mfma_f32_16x16x32_bf16 v[118:121], v[162:165], v[178:181], v[118:121]
	v_mfma_f32_16x16x32_bf16 v[114:117], v[170:173], v[178:181], v[114:117]
	v_mfma_f32_16x16x32_bf16 v[102:105], v[162:165], v[186:189], v[102:105]
	v_mfma_f32_16x16x32_bf16 v[98:101], v[170:173], v[186:189], v[98:101]
	v_mfma_f32_16x16x32_bf16 v[86:89], v[162:165], v[194:197], v[86:89]
	v_mfma_f32_16x16x32_bf16 v[82:85], v[170:173], v[194:197], v[82:85]
	v_mfma_f32_16x16x32_bf16 v[70:73], v[162:165], v[202:205], v[70:73]
	v_mfma_f32_16x16x32_bf16 v[66:69], v[170:173], v[202:205], v[66:69]
	s_setprio 0
	s_barrier
; #define PG8_STAGE(bufoff, gbase, voff) do { _Pragma("unroll") for (int _i = 0; _i < 2; ++_i) \
;         __builtin_amdgcn_global_load_lds((const unsigned*)((const char*)(gbase) + (voff)[_i]), (LAS unsigned*)(lds + (bufoff) + ldsw + _i * 8192), 16, 0, 0); } while (0)
; #define PG8_LDA(dst, b, h) do { _Pragma("unroll") for (int m = 0; m < 4; ++m) _Pragma("unroll") for (int k = 0; k < 2; ++k) dst[m][k] = *(const LAS bf16x8*)(lds + PG8_SA(b, h) + aoff + m * 2048 + k * 1024); } while (0)
; #define PG8_MMA(ai, bj, At, Bt) do { __builtin_amdgcn_s_setprio(1); _Pragma("unroll") for (int m = 0; m < 4; ++m) _Pragma("unroll") for (int n = 0; n < 2; ++n) _Pragma("unroll") for (int k = 0; k < 2; ++k) \
;         acc[ai][bj][m][n] = __builtin_amdgcn_mfma_f32_16x16x32_bf16(Bt[n][k], At[m][k], acc[ai][bj][m][n], 0, 0, 0); __builtin_amdgcn_s_setprio(0); } while (0)
; #define PG8_WAIT_V(n) asm volatile("s_waitcnt vmcnt(" #n ")" ::: "memory")
; #define PG8_WAIT_L(n) asm volatile("s_waitcnt lgkmcnt(" #n ")" ::: "memory")
; #define PG8_BAR __builtin_amdgcn_s_barrier()
; #define PG8_SCHED __builtin_amdgcn_sched_barrier(0)
; template <class Epi, class Sched, bool ALIGN_EPI, bool LAST_FUSED = false, bool PERM = false, bool CARRY = false>
; __device__ __forceinline__ void gemm_phase(LAS unsigned char* lds, const int tid, const int K, const int lda, const int ldb, const Sched& S, const Epi& E) {
;     ...
;             PG8_LDA(At, 1, 1); PG8_STAGE(PG8_SB(1, 0), b3, voffB); PG8_STAGE(PG8_SB(1, 1), b3 + hstepB, voffB); PG8_STAGE(PG8_SA(1, 0), a3, voffA);
;             PG8_WAIT_V(8); PG8_WAIT_L(0); PG8_BAR; PG8_MMA(1, 0, At, B0); PG8_MMA(1, 1, At, B1); PG8_BAR; PG8_SCHED;
;         }
;         if constexpr (ALIGN_EPI) { if (wr == 0) PG8_BAR; }
	s_add_i32 s28, s31, s51
	v_lshl_add_u64 v[206:207], v[206:207], 0, s[68:69]
	s_mov_b32 m0, s28
	ds_read_b128 v[174:177], v145 offset:49152
	ds_read_b128 v[178:181], v145 offset:50176
	ds_read_b128 v[182:185], v145 offset:51200
	ds_read_b128 v[186:189], v145 offset:52224
	ds_read_b128 v[190:193], v145 offset:53248
	ds_read_b128 v[194:197], v145 offset:54272
	ds_read_b128 v[198:201], v145 offset:55296
	ds_read_b128 v[202:205], v145 offset:56320
	global_load_lds_dwordx4 v[206:207], off
	s_add_i32 m0, s28, 0x2000
	s_add_u32 s4, s4, 0x80080
	v_lshl_add_u64 v[206:207], v[208:209], 0, s[68:69]
	s_addc_u32 s5, s5, 0
	s_add_i32 s28, s35, s51
	global_load_lds_dwordx4 v[206:207], off
	v_lshl_add_u64 v[206:207], s[4:5], 0, v[0:1]
	s_mov_b32 m0, s28
	s_nop 0
	global_load_lds_dwordx4 v[206:207], off
	v_lshl_add_u64 v[206:207], s[4:5], 0, v[130:131]
	s_add_i32 m0, s28, 0x2000
	s_nop 0
	global_load_lds_dwordx4 v[206:207], off
	v_lshl_add_u64 v[206:207], v[210:211], 0, s[68:69]
	s_mov_b32 m0, s57
	s_nop 0
	global_load_lds_dwordx4 v[206:207], off
	v_lshl_add_u64 v[206:207], v[212:213], 0, s[68:69]
	s_mov_b32 m0, s58
	s_nop 0
	global_load_lds_dwordx4 v[206:207], off
	s_waitcnt vmcnt(8)
	s_waitcnt lgkmcnt(0)
	s_barrier
	s_setprio 1
	s_waitcnt lgkmcnt(0)
	v_mfma_f32_16x16x32_bf16 v[62:65], v[136:139], v[174:177], v[62:65]
	v_mfma_f32_16x16x32_bf16 v[58:61], v[150:153], v[174:177], v[58:61]
	v_mfma_f32_16x16x32_bf16 v[46:49], v[136:139], v[182:185], v[46:49]
	v_mfma_f32_16x16x32_bf16 v[42:45], v[150:153], v[182:185], v[42:45]
	v_mfma_f32_16x16x32_bf16 v[30:33], v[136:139], v[190:193], v[30:33]
	v_mfma_f32_16x16x32_bf16 v[26:29], v[150:153], v[190:193], v[26:29]
	v_mfma_f32_16x16x32_bf16 v[14:17], v[136:139], v[198:201], v[14:17]
	v_mfma_f32_16x16x32_bf16 v[10:13], v[150:153], v[198:201], v[10:13]
	v_mfma_f32_16x16x32_bf16 v[62:65], v[146:149], v[178:181], v[62:65]
	v_mfma_f32_16x16x32_bf16 v[58:61], v[154:157], v[178:181], v[58:61]
	v_mfma_f32_16x16x32_bf16 v[46:49], v[146:149], v[186:189], v[46:49]
	v_mfma_f32_16x16x32_bf16 v[42:45], v[154:157], v[186:189], v[42:45]
	v_mfma_f32_16x16x32_bf16 v[30:33], v[146:149], v[194:197], v[30:33]
	v_mfma_f32_16x16x32_bf16 v[26:29], v[154:157], v[194:197], v[26:29]
	v_mfma_f32_16x16x32_bf16 v[14:17], v[146:149], v[202:205], v[14:17]
	v_mfma_f32_16x16x32_bf16 v[10:13], v[154:157], v[202:205], v[10:13]
	v_mfma_f32_16x16x32_bf16 v[54:57], v[158:161], v[174:177], v[54:57]
	v_mfma_f32_16x16x32_bf16 v[50:53], v[166:169], v[174:177], v[50:53]
	v_mfma_f32_16x16x32_bf16 v[38:41], v[158:161], v[182:185], v[38:41]
	v_mfma_f32_16x16x32_bf16 v[34:37], v[166:169], v[182:185], v[34:37]
	v_mfma_f32_16x16x32_bf16 v[22:25], v[158:161], v[190:193], v[22:25]
	v_mfma_f32_16x16x32_bf16 v[18:21], v[166:169], v[190:193], v[18:21]
	v_mfma_f32_16x16x32_bf16 v[6:9], v[158:161], v[198:201], v[6:9]
	v_mfma_f32_16x16x32_bf16 v[2:5], v[166:169], v[198:201], v[2:5]
	v_mfma_f32_16x16x32_bf16 v[54:57], v[162:165], v[178:181], v[54:57]
	v_mfma_f32_16x16x32_bf16 v[50:53], v[170:173], v[178:181], v[50:53]
	v_mfma_f32_16x16x32_bf16 v[38:41], v[162:165], v[186:189], v[38:41]
	v_mfma_f32_16x16x32_bf16 v[34:37], v[170:173], v[186:189], v[34:37]
	v_mfma_f32_16x16x32_bf16 v[22:25], v[162:165], v[194:197], v[22:25]
	v_mfma_f32_16x16x32_bf16 v[18:21], v[170:173], v[194:197], v[18:21]
	v_mfma_f32_16x16x32_bf16 v[6:9], v[162:165], v[202:205], v[6:9]
	v_mfma_f32_16x16x32_bf16 v[2:5], v[170:173], v[202:205], v[2:5]
	s_setprio 0
	s_barrier
	s_add_i32 s27, s27, 2
	s_add_u32 s2, s2, 0x100
	s_addc_u32 s3, s3, 0
	s_add_u32 s22, s22, 0x100
	s_addc_u32 s23, s23, 0
	s_cmp_gt_u32 s27, 29
	s_cbranch_scc0 .LBB0_279
	s_and_b64 vcc, exec, s[18:19]
	s_cbranch_vccz .LBB0_282
	s_barrier

; #define PG8_STAGE(bufoff, gbase, voff) do { _Pragma("unroll") for (int _i = 0; _i < 2; ++_i) \
;         __builtin_amdgcn_global_load_lds((const unsigned*)((const char*)(gbase) + (voff)[_i]), (LAS unsigned*)(lds + (bufoff) + ldsw + _i * 8192), 16, 0, 0); } while (0)
; #define PG8_LDA(dst, b, h) do { _Pragma("unroll") for (int m = 0; m < 4; ++m) _Pragma("unroll") for (int k = 0; k < 2; ++k) dst[m][k] = *(const LAS bf16x8*)(lds + PG8_SA(b, h) + aoff + m * 2048 + k * 1024); } while (0)
; #define PG8_LDB(dst, b, h) do { _Pragma("unroll") for (int n = 0; n < 2; ++n) _Pragma("unroll") for (int k = 0; k < 2; ++k) dst[n][k] = *(const LAS bf16x8*)(lds + PG8_SB(b, h) + boff + n * 2048 + k * 1024); } while (0)
; #define PG8_MMA(ai, bj, At, Bt) do { __builtin_amdgcn_s_setprio(1); _Pragma("unroll") for (int m = 0; m < 4; ++m) _Pragma("unroll") for (int n = 0; n < 2; ++n) _Pragma("unroll") for (int k = 0; k < 2; ++k) \
;         acc[ai][bj][m][n] = __builtin_amdgcn_mfma_f32_16x16x32_bf16(Bt[n][k], At[m][k], acc[ai][bj][m][n], 0, 0, 0); __builtin_amdgcn_s_setprio(0); } while (0)
; #define PG8_WAIT_V(n) asm volatile("s_waitcnt vmcnt(" #n ")" ::: "memory")
; #define PG8_WAIT_L(n) asm volatile("s_waitcnt lgkmcnt(" #n ")" ::: "memory")
; template <class Epi, class Sched, bool ALIGN_EPI, bool LAST_FUSED = false, bool PERM = false, bool CARRY = false>
; __device__ __forceinline__ void gemm_phase(LAS unsigned char* lds, const int tid, const int K, const int lda, const int ldb, const Sched& S, const Epi& E) {
;     ...
;         for (int t = 0; t < nt; t += 2) {
;             const bool last = (t == nt - 2);
;             const char* a1 = cA + (size_t)(t + 1) * kstep;
;             const char* a2 = last ? nA : cA + (size_t)(t + 2) * kstep; const char* b2 = last ? nB : cB + (size_t)(t + 2) * kstep;
;             const char* a3 = a2 + kstep; const char* b3 = b2 + kstep;
;             PG8_LDB(B0, 0, 0); PG8_LDB(B1, 0, 1); PG8_SCHED; PG8_LDA(At, 0, 0); PG8_STAGE(PG8_SA(1, 1), a1 + hstepA, voffA);
;             PG8_WAIT_V(8); PG8_WAIT_L(0); PG8_BAR; PG8_MMA(0, 0, At, B0); PG8_MMA(0, 1, At, B1); PG8_BAR; PG8_SCHED;
;             PG8_LDA(At, 0, 1); PG8_STAGE(PG8_SB(0, 0), b2, voffB); PG8_STAGE(PG8_SB(0, 1), b2 + hstepB, voffB); PG8_STAGE(PG8_SA(0, 0), a2, voffA);
;             PG8_WAIT_V(8); PG8_WAIT_L(0); PG8_BAR; PG8_MMA(1, 0, At, B0); PG8_MMA(1, 1, At, B1); PG8_BAR; PG8_SCHED;
.LBB0_512:
	s_add_u32 s28, s4, 0xfff80080
	s_addc_u32 s29, s5, -1
	s_add_i32 s31, 0, 0x10000
	s_cmp_eq_u32 s24, 28
	s_cselect_b32 s41, s87, s29
	s_cselect_b32 s40, s86, s28
	v_add_u32_e32 v148, s31, v160
	s_cselect_b32 s37, s39, s23
	s_cselect_b32 s36, s38, s22
	s_add_i32 s35, 0, 0x14000
	ds_read_b128 v[140:143], v148
	ds_read_b128 v[144:147], v148 offset:1024
	ds_read_b128 v[162:165], v148 offset:2048
	ds_read_b128 v[166:169], v148 offset:3072
	v_add_u32_e32 v148, s35, v160
	ds_read_b128 v[170:173], v148
	ds_read_b128 v[174:177], v148 offset:1024
	ds_read_b128 v[178:181], v148 offset:2048
	ds_read_b128 v[182:185], v148 offset:3072
	v_lshl_add_u64 v[148:149], s[4:5], 0, v[136:137]
	s_add_i32 m0, s54, 0xc000
	ds_read_b128 v[186:189], v161
	ds_read_b128 v[190:193], v161 offset:1024
	ds_read_b128 v[194:197], v161 offset:2048
	ds_read_b128 v[198:201], v161 offset:3072
	ds_read_b128 v[202:205], v161 offset:4096
	ds_read_b128 v[206:209], v161 offset:5120
	ds_read_b128 v[210:213], v161 offset:6144
	ds_read_b128 v[214:217], v161 offset:7168
	global_load_lds_dwordx4 v[148:149], off
	v_lshl_add_u64 v[148:149], s[4:5], 0, v[138:139]
	s_add_i32 m0, s54, 0xe000
	s_nop 0
	global_load_lds_dwordx4 v[148:149], off
	s_waitcnt vmcnt(8)
	s_waitcnt lgkmcnt(0)
	s_barrier
	s_setprio 1
	s_waitcnt lgkmcnt(0)
	v_mfma_f32_16x16x32_bf16 v[126:129], v[140:143], v[186:189], v[126:129]
	v_mfma_f32_16x16x32_bf16 v[122:125], v[162:165], v[186:189], v[122:125]
	v_mfma_f32_16x16x32_bf16 v[110:113], v[140:143], v[194:197], v[110:113]
	v_mfma_f32_16x16x32_bf16 v[106:109], v[162:165], v[194:197], v[106:109]
	v_mfma_f32_16x16x32_bf16 v[94:97], v[140:143], v[202:205], v[94:97]
	v_mfma_f32_16x16x32_bf16 v[90:93], v[162:165], v[202:205], v[90:93]
	v_mfma_f32_16x16x32_bf16 v[78:81], v[140:143], v[210:213], v[78:81]
	v_mfma_f32_16x16x32_bf16 v[74:77], v[162:165], v[210:213], v[74:77]
	v_mfma_f32_16x16x32_bf16 v[126:129], v[144:147], v[190:193], v[126:129]
	v_mfma_f32_16x16x32_bf16 v[122:125], v[166:169], v[190:193], v[122:125]
	v_mfma_f32_16x16x32_bf16 v[110:113], v[144:147], v[198:201], v[110:113]
	v_mfma_f32_16x16x32_bf16 v[106:109], v[166:169], v[198:201], v[106:109]
	v_mfma_f32_16x16x32_bf16 v[94:97], v[144:147], v[206:209], v[94:97]
	v_mfma_f32_16x16x32_bf16 v[90:93], v[166:169], v[206:209], v[90:93]
	v_mfma_f32_16x16x32_bf16 v[78:81], v[144:147], v[214:217], v[78:81]
	v_mfma_f32_16x16x32_bf16 v[74:77], v[166:169], v[214:217], v[74:77]
	v_mfma_f32_16x16x32_bf16 v[118:121], v[170:173], v[186:189], v[118:121]
	v_mfma_f32_16x16x32_bf16 v[114:117], v[178:181], v[186:189], v[114:117]
	v_mfma_f32_16x16x32_bf16 v[102:105], v[170:173], v[194:197], v[102:105]
	v_mfma_f32_16x16x32_bf16 v[98:101], v[178:181], v[194:197], v[98:101]
	v_mfma_f32_16x16x32_bf16 v[86:89], v[170:173], v[202:205], v[86:89]
	v_mfma_f32_16x16x32_bf16 v[82:85], v[178:181], v[202:205], v[82:85]
	v_mfma_f32_16x16x32_bf16 v[70:73], v[170:173], v[210:213], v[70:73]
	v_mfma_f32_16x16x32_bf16 v[66:69], v[178:181], v[210:213], v[66:69]
	v_mfma_f32_16x16x32_bf16 v[118:121], v[174:177], v[190:193], v[118:121]
	v_mfma_f32_16x16x32_bf16 v[114:117], v[182:185], v[190:193], v[114:117]
	v_mfma_f32_16x16x32_bf16 v[102:105], v[174:177], v[198:201], v[102:105]
	v_mfma_f32_16x16x32_bf16 v[98:101], v[182:185], v[198:201], v[98:101]
	v_mfma_f32_16x16x32_bf16 v[86:89], v[174:177], v[206:209], v[86:89]
	v_mfma_f32_16x16x32_bf16 v[82:85], v[182:185], v[206:209], v[82:85]
	v_mfma_f32_16x16x32_bf16 v[70:73], v[174:177], v[214:217], v[70:73]
	v_mfma_f32_16x16x32_bf16 v[66:69], v[182:185], v[214:217], v[66:69]
	s_setprio 0
	s_barrier
	s_add_i32 s28, s31, s52
	v_lshl_add_u64 v[148:149], s[36:37], 0, v[0:1]
	s_mov_b32 m0, s28
	ds_read_b128 v[186:189], v161 offset:16384
	ds_read_b128 v[190:193], v161 offset:17408
	ds_read_b128 v[194:197], v161 offset:18432
	ds_read_b128 v[198:201], v161 offset:19456
	ds_read_b128 v[202:205], v161 offset:20480
	ds_read_b128 v[206:209], v161 offset:21504
	ds_read_b128 v[210:213], v161 offset:22528
	ds_read_b128 v[214:217], v161 offset:23552
	global_load_lds_dwordx4 v[148:149], off
	s_add_i32 m0, s28, 0x2000
	s_add_u32 s28, s36, 0x80000
	v_lshl_add_u64 v[152:153], s[36:37], 0, v[130:131]
	s_addc_u32 s29, s37, 0
	s_add_i32 s31, s35, s52
	global_load_lds_dwordx4 v[152:153], off
	v_lshl_add_u64 v[156:157], s[28:29], 0, v[0:1]
	s_mov_b32 m0, s31
	v_lshl_add_u64 v[218:219], s[40:41], 0, v[132:133]
	global_load_lds_dwordx4 v[156:157], off
	v_lshl_add_u64 v[156:157], s[28:29], 0, v[130:131]
	s_add_i32 m0, s31, 0x2000
	s_nop 0
	global_load_lds_dwordx4 v[156:157], off
	v_lshl_add_u64 v[156:157], s[40:41], 0, v[134:135]
	s_mov_b32 m0, s54
	s_nop 0
	global_load_lds_dwordx4 v[156:157], off
	s_mov_b32 m0, s55
	s_nop 0
	global_load_lds_dwordx4 v[218:219], off
	s_waitcnt vmcnt(8)
	s_waitcnt lgkmcnt(0)
	s_barrier
; #define PG8_STAGE(bufoff, gbase, voff) do { _Pragma("unroll") for (int _i = 0; _i < 2; ++_i) \
;         __builtin_amdgcn_global_load_lds((const unsigned*)((const char*)(gbase) + (voff)[_i]), (LAS unsigned*)(lds + (bufoff) + ldsw + _i * 8192), 16, 0, 0); } while (0)
; #define PG8_LDA(dst, b, h) do { _Pragma("unroll") for (int m = 0; m < 4; ++m) _Pragma("unroll") for (int k = 0; k < 2; ++k) dst[m][k] = *(const LAS bf16x8*)(lds + PG8_SA(b, h) + aoff + m * 2048 + k * 1024); } while (0)
; #define PG8_LDB(dst, b, h) do { _Pragma("unroll") for (int n = 0; n < 2; ++n) _Pragma("unroll") for (int k = 0; k < 2; ++k) dst[n][k] = *(const LAS bf16x8*)(lds + PG8_SB(b, h) + boff + n * 2048 + k * 1024); } while (0)
; #define PG8_MMA(ai, bj, At, Bt) do { __builtin_amdgcn_s_setprio(1); _Pragma("unroll") for (int m = 0; m < 4; ++m) _Pragma("unroll") for (int n = 0; n < 2; ++n) _Pragma("unroll") for (int k = 0; k < 2; ++k) \
;         acc[ai][bj][m][n] = __builtin_amdgcn_mfma_f32_16x16x32_bf16(Bt[n][k], At[m][k], acc[ai][bj][m][n], 0, 0, 0); __builtin_amdgcn_s_setprio(0); } while (0)
; #define PG8_WAIT_V(n) asm volatile("s_waitcnt vmcnt(" #n ")" ::: "memory")
; #define PG8_WAIT_L(n) asm volatile("s_waitcnt lgkmcnt(" #n ")" ::: "memory")
; #define PG8_BAR __builtin_amdgcn_s_barrier()
; #define PG8_SCHED __builtin_amdgcn_sched_barrier(0)
; template <class Epi, class Sched, bool ALIGN_EPI, bool LAST_FUSED = false, bool PERM = false, bool CARRY = false>
; __device__ __forceinline__ void gemm_phase(LAS unsigned char* lds, const int tid, const int K, const int lda, const int ldb, const Sched& S, const Epi& E) {
;     ...
;             PG8_WAIT_V(8); PG8_WAIT_L(0); PG8_BAR; PG8_MMA(1, 0, At, B0); PG8_MMA(1, 1, At, B1); PG8_BAR; PG8_SCHED;
;             PG8_LDB(B0, 1, 0); PG8_LDB(B1, 1, 1); PG8_SCHED; PG8_LDA(At, 1, 0); PG8_STAGE(PG8_SA(0, 1), a2 + hstepA, voffA);
;             PG8_WAIT_V(8); PG8_WAIT_L(0); PG8_BAR; PG8_MMA(0, 0, At, B0); PG8_MMA(0, 1, At, B1); PG8_BAR; PG8_SCHED;
	s_setprio 1
	s_waitcnt lgkmcnt(0)
	v_mfma_f32_16x16x32_bf16 v[62:65], v[140:143], v[186:189], v[62:65]
	v_mfma_f32_16x16x32_bf16 v[58:61], v[162:165], v[186:189], v[58:61]
	v_mfma_f32_16x16x32_bf16 v[46:49], v[140:143], v[194:197], v[46:49]
	v_mfma_f32_16x16x32_bf16 v[42:45], v[162:165], v[194:197], v[42:45]
	v_mfma_f32_16x16x32_bf16 v[30:33], v[140:143], v[202:205], v[30:33]
	v_mfma_f32_16x16x32_bf16 v[26:29], v[162:165], v[202:205], v[26:29]
	v_mfma_f32_16x16x32_bf16 v[14:17], v[140:143], v[210:213], v[14:17]
	v_mfma_f32_16x16x32_bf16 v[10:13], v[162:165], v[210:213], v[10:13]
	v_mfma_f32_16x16x32_bf16 v[62:65], v[144:147], v[190:193], v[62:65]
	v_mfma_f32_16x16x32_bf16 v[58:61], v[166:169], v[190:193], v[58:61]
	v_mfma_f32_16x16x32_bf16 v[46:49], v[144:147], v[198:201], v[46:49]
	v_mfma_f32_16x16x32_bf16 v[42:45], v[166:169], v[198:201], v[42:45]
	v_mfma_f32_16x16x32_bf16 v[30:33], v[144:147], v[206:209], v[30:33]
	v_mfma_f32_16x16x32_bf16 v[26:29], v[166:169], v[206:209], v[26:29]
	v_mfma_f32_16x16x32_bf16 v[14:17], v[144:147], v[214:217], v[14:17]
	v_mfma_f32_16x16x32_bf16 v[10:13], v[166:169], v[214:217], v[10:13]
	v_mfma_f32_16x16x32_bf16 v[54:57], v[170:173], v[186:189], v[54:57]
	v_mfma_f32_16x16x32_bf16 v[50:53], v[178:181], v[186:189], v[50:53]
	v_mfma_f32_16x16x32_bf16 v[38:41], v[170:173], v[194:197], v[38:41]
	v_mfma_f32_16x16x32_bf16 v[34:37], v[178:181], v[194:197], v[34:37]
	v_mfma_f32_16x16x32_bf16 v[22:25], v[170:173], v[202:205], v[22:25]
	v_mfma_f32_16x16x32_bf16 v[18:21], v[178:181], v[202:205], v[18:21]
	v_mfma_f32_16x16x32_bf16 v[6:9], v[170:173], v[210:213], v[6:9]
	v_mfma_f32_16x16x32_bf16 v[2:5], v[178:181], v[210:213], v[2:5]
	v_mfma_f32_16x16x32_bf16 v[54:57], v[174:177], v[190:193], v[54:57]
	v_mfma_f32_16x16x32_bf16 v[50:53], v[182:185], v[190:193], v[50:53]
	v_mfma_f32_16x16x32_bf16 v[38:41], v[174:177], v[198:201], v[38:41]
	v_mfma_f32_16x16x32_bf16 v[34:37], v[182:185], v[198:201], v[34:37]
	v_mfma_f32_16x16x32_bf16 v[22:25], v[174:177], v[206:209], v[22:25]
	v_mfma_f32_16x16x32_bf16 v[18:21], v[182:185], v[206:209], v[18:21]
	v_mfma_f32_16x16x32_bf16 v[6:9], v[174:177], v[214:217], v[6:9]
	v_mfma_f32_16x16x32_bf16 v[2:5], v[182:185], v[214:217], v[2:5]
	s_setprio 0
	s_barrier
	s_add_i32 s31, 0, 0x18000
	v_add_u32_e32 v150, s31, v160
	s_add_i32 s35, 0, 0x1c000
	ds_read_b128 v[140:143], v150
	ds_read_b128 v[144:147], v150 offset:1024
	ds_read_b128 v[162:165], v150 offset:2048
	ds_read_b128 v[166:169], v150 offset:3072
	v_add_u32_e32 v150, s35, v160
	ds_read_b128 v[170:173], v150
	ds_read_b128 v[174:177], v150 offset:1024
	ds_read_b128 v[178:181], v150 offset:2048
	ds_read_b128 v[182:185], v150 offset:3072
	s_add_u32 s28, s40, 0x80000
	s_addc_u32 s29, s41, 0
	s_mov_b32 m0, s56
	v_lshl_add_u64 v[220:221], s[28:29], 0, v[134:135]
	ds_read_b128 v[186:189], v161 offset:32768
	ds_read_b128 v[190:193], v161 offset:33792
	ds_read_b128 v[194:197], v161 offset:34816
	ds_read_b128 v[198:201], v161 offset:35840
	ds_read_b128 v[202:205], v161 offset:36864
	ds_read_b128 v[206:209], v161 offset:37888
	ds_read_b128 v[210:213], v161 offset:38912
	ds_read_b128 v[214:217], v161 offset:39936
	global_load_lds_dwordx4 v[220:221], off
	v_lshl_add_u64 v[220:221], s[28:29], 0, v[132:133]
	s_mov_b32 m0, s57
	s_nop 0
	global_load_lds_dwordx4 v[220:221], off
	s_waitcnt vmcnt(8)
	s_waitcnt lgkmcnt(0)
	s_barrier
	s_setprio 1
	s_waitcnt lgkmcnt(0)
	v_mfma_f32_16x16x32_bf16 v[126:129], v[140:143], v[186:189], v[126:129]
	v_mfma_f32_16x16x32_bf16 v[122:125], v[162:165], v[186:189], v[122:125]
	v_mfma_f32_16x16x32_bf16 v[110:113], v[140:143], v[194:197], v[110:113]
	v_mfma_f32_16x16x32_bf16 v[106:109], v[162:165], v[194:197], v[106:109]
	v_mfma_f32_16x16x32_bf16 v[94:97], v[140:143], v[202:205], v[94:97]
	v_mfma_f32_16x16x32_bf16 v[90:93], v[162:165], v[202:205], v[90:93]
	v_mfma_f32_16x16x32_bf16 v[78:81], v[140:143], v[210:213], v[78:81]
	v_mfma_f32_16x16x32_bf16 v[74:77], v[162:165], v[210:213], v[74:77]
	v_mfma_f32_16x16x32_bf16 v[126:129], v[144:147], v[190:193], v[126:129]
	v_mfma_f32_16x16x32_bf16 v[122:125], v[166:169], v[190:193], v[122:125]
	v_mfma_f32_16x16x32_bf16 v[110:113], v[144:147], v[198:201], v[110:113]
	v_mfma_f32_16x16x32_bf16 v[106:109], v[166:169], v[198:201], v[106:109]
	v_mfma_f32_16x16x32_bf16 v[94:97], v[144:147], v[206:209], v[94:97]
	v_mfma_f32_16x16x32_bf16 v[90:93], v[166:169], v[206:209], v[90:93]
	v_mfma_f32_16x16x32_bf16 v[78:81], v[144:147], v[214:217], v[78:81]
	v_mfma_f32_16x16x32_bf16 v[74:77], v[166:169], v[214:217], v[74:77]
	v_mfma_f32_16x16x32_bf16 v[118:121], v[170:173], v[186:189], v[118:121]
	v_mfma_f32_16x16x32_bf16 v[114:117], v[178:181], v[186:189], v[114:117]
	v_mfma_f32_16x16x32_bf16 v[102:105], v[170:173], v[194:197], v[102:105]
	v_mfma_f32_16x16x32_bf16 v[98:101], v[178:181], v[194:197], v[98:101]
	v_mfma_f32_16x16x32_bf16 v[86:89], v[170:173], v[202:205], v[86:89]
	v_mfma_f32_16x16x32_bf16 v[82:85], v[178:181], v[202:205], v[82:85]
	v_mfma_f32_16x16x32_bf16 v[70:73], v[170:173], v[210:213], v[70:73]
	v_mfma_f32_16x16x32_bf16 v[66:69], v[178:181], v[210:213], v[66:69]
	v_mfma_f32_16x16x32_bf16 v[118:121], v[174:177], v[190:193], v[118:121]
	v_mfma_f32_16x16x32_bf16 v[114:117], v[182:185], v[190:193], v[114:117]
	v_mfma_f32_16x16x32_bf16 v[102:105], v[174:177], v[198:201], v[102:105]
	v_mfma_f32_16x16x32_bf16 v[98:101], v[182:185], v[198:201], v[98:101]
	v_mfma_f32_16x16x32_bf16 v[86:89], v[174:177], v[206:209], v[86:89]
	v_mfma_f32_16x16x32_bf16 v[82:85], v[182:185], v[206:209], v[82:85]
	v_mfma_f32_16x16x32_bf16 v[70:73], v[174:177], v[214:217], v[70:73]
	v_mfma_f32_16x16x32_bf16 v[66:69], v[182:185], v[214:217], v[66:69]
	s_setprio 0
	s_barrier
; #define PG8_STAGE(bufoff, gbase, voff) do { _Pragma("unroll") for (int _i = 0; _i < 2; ++_i) \
;         __builtin_amdgcn_global_load_lds((const unsigned*)((const char*)(gbase) + (voff)[_i]), (LAS unsigned*)(lds + (bufoff) + ldsw + _i * 8192), 16, 0, 0); } while (0)
; #define PG8_LDA(dst, b, h) do { _Pragma("unroll") for (int m = 0; m < 4; ++m) _Pragma("unroll") for (int k = 0; k < 2; ++k) dst[m][k] = *(const LAS bf16x8*)(lds + PG8_SA(b, h) + aoff + m * 2048 + k * 1024); } while (0)
; #define PG8_MMA(ai, bj, At, Bt) do { __builtin_amdgcn_s_setprio(1); _Pragma("unroll") for (int m = 0; m < 4; ++m) _Pragma("unroll") for (int n = 0; n < 2; ++n) _Pragma("unroll") for (int k = 0; k < 2; ++k) \
;         acc[ai][bj][m][n] = __builtin_amdgcn_mfma_f32_16x16x32_bf16(Bt[n][k], At[m][k], acc[ai][bj][m][n], 0, 0, 0); __builtin_amdgcn_s_setprio(0); } while (0)
; #define PG8_WAIT_V(n) asm volatile("s_waitcnt vmcnt(" #n ")" ::: "memory")
; #define PG8_WAIT_L(n) asm volatile("s_waitcnt lgkmcnt(" #n ")" ::: "memory")
; #define PG8_BAR __builtin_amdgcn_s_barrier()
; #define PG8_SCHED __builtin_amdgcn_sched_barrier(0)
; template <class Epi, class Sched, bool ALIGN_EPI, bool LAST_FUSED = false, bool PERM = false, bool CARRY = false>
; __device__ __forceinline__ void gemm_phase(LAS unsigned char* lds, const int tid, const int K, const int lda, const int ldb, const Sched& S, const Epi& E) {
;     ...
;             PG8_LDA(At, 1, 1); PG8_STAGE(PG8_SB(1, 0), b3, voffB); PG8_STAGE(PG8_SB(1, 1), b3 + hstepB, voffB); PG8_STAGE(PG8_SA(1, 0), a3, voffA);
;             PG8_WAIT_V(8); PG8_WAIT_L(0); PG8_BAR; PG8_MMA(1, 0, At, B0); PG8_MMA(1, 1, At, B1); PG8_BAR; PG8_SCHED;
;         }
;         if constexpr (ALIGN_EPI) { if (wr == 0) PG8_BAR; }
	s_add_i32 s28, s31, s52
	v_lshl_add_u64 v[148:149], v[148:149], 0, s[68:69]
	s_mov_b32 m0, s28
	ds_read_b128 v[186:189], v161 offset:49152
	ds_read_b128 v[190:193], v161 offset:50176
	ds_read_b128 v[194:197], v161 offset:51200
	ds_read_b128 v[198:201], v161 offset:52224
	ds_read_b128 v[202:205], v161 offset:53248
	ds_read_b128 v[206:209], v161 offset:54272
	ds_read_b128 v[210:213], v161 offset:55296
	ds_read_b128 v[214:217], v161 offset:56320
	global_load_lds_dwordx4 v[148:149], off
	s_add_i32 m0, s28, 0x2000
	s_add_u32 s28, s36, 0x80080
	v_lshl_add_u64 v[148:149], v[152:153], 0, s[68:69]
	s_addc_u32 s29, s37, 0
	s_add_i32 s31, s35, s52
	global_load_lds_dwordx4 v[148:149], off
	v_lshl_add_u64 v[148:149], s[28:29], 0, v[0:1]
	s_mov_b32 m0, s31
	s_nop 0
	global_load_lds_dwordx4 v[148:149], off
	v_lshl_add_u64 v[148:149], s[28:29], 0, v[130:131]
	s_add_i32 m0, s31, 0x2000
	s_nop 0
	global_load_lds_dwordx4 v[148:149], off
	v_lshl_add_u64 v[148:149], v[156:157], 0, s[68:69]
	s_mov_b32 m0, s59
	s_nop 0
	global_load_lds_dwordx4 v[148:149], off
	v_lshl_add_u64 v[148:149], v[218:219], 0, s[68:69]
	s_mov_b32 m0, s60
	s_nop 0
	global_load_lds_dwordx4 v[148:149], off
	s_waitcnt vmcnt(8)
	s_waitcnt lgkmcnt(0)
	s_barrier
	s_setprio 1
	s_waitcnt lgkmcnt(0)
	v_mfma_f32_16x16x32_bf16 v[62:65], v[140:143], v[186:189], v[62:65]
	v_mfma_f32_16x16x32_bf16 v[58:61], v[162:165], v[186:189], v[58:61]
	v_mfma_f32_16x16x32_bf16 v[46:49], v[140:143], v[194:197], v[46:49]
	v_mfma_f32_16x16x32_bf16 v[42:45], v[162:165], v[194:197], v[42:45]
	v_mfma_f32_16x16x32_bf16 v[30:33], v[140:143], v[202:205], v[30:33]
	v_mfma_f32_16x16x32_bf16 v[26:29], v[162:165], v[202:205], v[26:29]
	v_mfma_f32_16x16x32_bf16 v[14:17], v[140:143], v[210:213], v[14:17]
	v_mfma_f32_16x16x32_bf16 v[10:13], v[162:165], v[210:213], v[10:13]
	v_mfma_f32_16x16x32_bf16 v[62:65], v[144:147], v[190:193], v[62:65]
	v_mfma_f32_16x16x32_bf16 v[58:61], v[166:169], v[190:193], v[58:61]
	v_mfma_f32_16x16x32_bf16 v[46:49], v[144:147], v[198:201], v[46:49]
	v_mfma_f32_16x16x32_bf16 v[42:45], v[166:169], v[198:201], v[42:45]
	v_mfma_f32_16x16x32_bf16 v[30:33], v[144:147], v[206:209], v[30:33]
	v_mfma_f32_16x16x32_bf16 v[26:29], v[166:169], v[206:209], v[26:29]
	v_mfma_f32_16x16x32_bf16 v[14:17], v[144:147], v[214:217], v[14:17]
	v_mfma_f32_16x16x32_bf16 v[10:13], v[166:169], v[214:217], v[10:13]
	v_mfma_f32_16x16x32_bf16 v[54:57], v[170:173], v[186:189], v[54:57]
	v_mfma_f32_16x16x32_bf16 v[50:53], v[178:181], v[186:189], v[50:53]
	v_mfma_f32_16x16x32_bf16 v[38:41], v[170:173], v[194:197], v[38:41]
	v_mfma_f32_16x16x32_bf16 v[34:37], v[178:181], v[194:197], v[34:37]
	v_mfma_f32_16x16x32_bf16 v[22:25], v[170:173], v[202:205], v[22:25]
	v_mfma_f32_16x16x32_bf16 v[18:21], v[178:181], v[202:205], v[18:21]
	v_mfma_f32_16x16x32_bf16 v[6:9], v[170:173], v[210:213], v[6:9]
	v_mfma_f32_16x16x32_bf16 v[2:5], v[178:181], v[210:213], v[2:5]
	v_mfma_f32_16x16x32_bf16 v[54:57], v[174:177], v[190:193], v[54:57]
	v_mfma_f32_16x16x32_bf16 v[50:53], v[182:185], v[190:193], v[50:53]
	v_mfma_f32_16x16x32_bf16 v[38:41], v[174:177], v[198:201], v[38:41]
	v_mfma_f32_16x16x32_bf16 v[34:37], v[182:185], v[198:201], v[34:37]
	v_mfma_f32_16x16x32_bf16 v[22:25], v[174:177], v[206:209], v[22:25]
	v_mfma_f32_16x16x32_bf16 v[18:21], v[182:185], v[206:209], v[18:21]
	v_mfma_f32_16x16x32_bf16 v[6:9], v[174:177], v[214:217], v[6:9]
	v_mfma_f32_16x16x32_bf16 v[2:5], v[182:185], v[214:217], v[2:5]
	s_setprio 0
	s_barrier
	s_add_i32 s24, s24, 2
	s_add_u32 s4, s4, 0x100
	s_addc_u32 s5, s5, 0
	s_add_u32 s22, s22, 0x100
	s_addc_u32 s23, s23, 0
	s_cmp_gt_u32 s24, 29
	s_cbranch_scc0 .LBB0_512
	s_and_b64 vcc, exec, s[78:79]
	s_cbranch_vccz .LBB0_515
	s_barrier

; #define PG8_STAGE(bufoff, gbase, voff) do { _Pragma("unroll") for (int _i = 0; _i < 2; ++_i) \
;         __builtin_amdgcn_global_load_lds((const unsigned*)((const char*)(gbase) + (voff)[_i]), (LAS unsigned*)(lds + (bufoff) + ldsw + _i * 8192), 16, 0, 0); } while (0)
; #define PG8_LDA(dst, b, h) do { _Pragma("unroll") for (int m = 0; m < 4; ++m) _Pragma("unroll") for (int k = 0; k < 2; ++k) dst[m][k] = *(const LAS bf16x8*)(lds + PG8_SA(b, h) + aoff + m * 2048 + k * 1024); } while (0)
; #define PG8_LDB(dst, b, h) do { _Pragma("unroll") for (int n = 0; n < 2; ++n) _Pragma("unroll") for (int k = 0; k < 2; ++k) dst[n][k] = *(const LAS bf16x8*)(lds + PG8_SB(b, h) + boff + n * 2048 + k * 1024); } while (0)
; #define PG8_MMA(ai, bj, At, Bt) do { __builtin_amdgcn_s_setprio(1); _Pragma("unroll") for (int m = 0; m < 4; ++m) _Pragma("unroll") for (int n = 0; n < 2; ++n) _Pragma("unroll") for (int k = 0; k < 2; ++k) \
;         acc[ai][bj][m][n] = __builtin_amdgcn_mfma_f32_16x16x32_bf16(Bt[n][k], At[m][k], acc[ai][bj][m][n], 0, 0, 0); __builtin_amdgcn_s_setprio(0); } while (0)
; #define PG8_WAIT_V(n) asm volatile("s_waitcnt vmcnt(" #n ")" ::: "memory")
; #define PG8_WAIT_L(n) asm volatile("s_waitcnt lgkmcnt(" #n ")" ::: "memory")
; template <class Epi, class Sched, bool ALIGN_EPI, bool LAST_FUSED = false, bool PERM = false, bool CARRY = false>
; __device__ __forceinline__ void gemm_phase(LAS unsigned char* lds, const int tid, const int K, const int lda, const int ldb, const Sched& S, const Epi& E) {
;     ...
;         for (int t = 0; t < nt; t += 2) {
;             const bool last = (t == nt - 2);
;             const char* a1 = cA + (size_t)(t + 1) * kstep;
;             const char* a2 = last ? nA : cA + (size_t)(t + 2) * kstep; const char* b2 = last ? nB : cB + (size_t)(t + 2) * kstep;
;             const char* a3 = a2 + kstep; const char* b3 = b2 + kstep;
;             PG8_LDB(B0, 0, 0); PG8_LDB(B1, 0, 1); PG8_SCHED; PG8_LDA(At, 0, 0); PG8_STAGE(PG8_SA(1, 1), a1 + hstepA, voffA);
;             PG8_WAIT_V(8); PG8_WAIT_L(0); PG8_BAR; PG8_MMA(0, 0, At, B0); PG8_MMA(0, 1, At, B1); PG8_BAR; PG8_SCHED;
;             PG8_LDA(At, 0, 1); PG8_STAGE(PG8_SB(0, 0), b2, voffB); PG8_STAGE(PG8_SB(0, 1), b2 + hstepB, voffB); PG8_STAGE(PG8_SA(0, 0), a2, voffA);
;             PG8_WAIT_V(8); PG8_WAIT_L(0); PG8_BAR; PG8_MMA(1, 0, At, B0); PG8_MMA(1, 1, At, B1); PG8_BAR; PG8_SCHED;
.LBB0_601:
	s_add_u32 s23, s30, s15
	s_addc_u32 s27, s31, 0
	s_add_u32 s35, s23, 0x100
	s_addc_u32 s42, s27, 0
	s_and_b64 s[28:29], s[40:41], exec
	s_cselect_b32 s47, s17, s42
	s_cselect_b32 s46, s16, s35
	s_add_u32 s15, s36, s15
	s_addc_u32 s28, s37, 0
	s_add_u32 s15, s15, 0x100
	s_addc_u32 s35, s28, 0
	s_add_i32 s75, 0, 0x10000
	s_and_b64 s[28:29], s[40:41], exec
	s_cselect_b32 s49, s19, s35
	s_cselect_b32 s48, s18, s15
	s_add_i32 s41, 0, 0x14000
	s_add_u32 s52, s23, 0x80080
	s_addc_u32 s53, s27, 0
	s_add_i32 s45, s75, s59
	s_add_i32 m0, s60, 0xc000
	s_add_i32 s77, s60, 0xe000
	s_add_i32 s29, s45, 0x2000
	s_add_u32 s50, s48, 0x80000
	v_add_u32_e32 v154, s75, v144
	v_add_u32_e32 v170, s41, v144
	s_addc_u32 s51, s49, 0
	s_add_i32 s44, s41, s59
	ds_read_b128 v[136:139], v154
	ds_read_b128 v[146:149], v154 offset:1024
	ds_read_b128 v[150:153], v154 offset:2048
	ds_read_b128 v[154:157], v154 offset:3072
	ds_read_b128 v[158:161], v170
	ds_read_b128 v[162:165], v170 offset:1024
	ds_read_b128 v[166:169], v170 offset:2048
	ds_read_b128 v[170:173], v170 offset:3072
	s_add_i32 s35, s44, 0x2000
	s_add_i32 s28, 0, 0x18000
	s_add_i32 s27, 0, 0x1c000
	s_add_u32 s42, s46, 0x80000
	s_addc_u32 s43, s47, 0
	s_add_i32 s23, s28, s59
	s_add_i32 s15, s23, 0x2000
	s_add_u32 s40, s48, 0x80080
	s_addc_u32 s41, s49, 0
	s_add_i32 s76, s27, s59
	s_add_i32 s75, s76, 0x2000
	v_lshl_add_u64 v[206:207], s[52:53], 0, v[134:135]
	ds_read_b128 v[174:177], v145
	ds_read_b128 v[178:181], v145 offset:1024
	ds_read_b128 v[182:185], v145 offset:2048
	ds_read_b128 v[186:189], v145 offset:3072
	ds_read_b128 v[190:193], v145 offset:4096
	ds_read_b128 v[194:197], v145 offset:5120
	ds_read_b128 v[198:201], v145 offset:6144
	ds_read_b128 v[202:205], v145 offset:7168
	global_load_lds_dwordx4 v[206:207], off
	v_lshl_add_u64 v[206:207], s[52:53], 0, v[132:133]
	s_mov_b32 m0, s77
	s_nop 0
	global_load_lds_dwordx4 v[206:207], off
	s_waitcnt vmcnt(8)
	s_waitcnt lgkmcnt(0)
	s_barrier
	s_setprio 1
	s_waitcnt lgkmcnt(0)
	v_mfma_f32_16x16x32_bf16 v[126:129], v[136:139], v[174:177], v[126:129]
	v_mfma_f32_16x16x32_bf16 v[122:125], v[150:153], v[174:177], v[122:125]
	v_mfma_f32_16x16x32_bf16 v[110:113], v[136:139], v[182:185], v[110:113]
	v_mfma_f32_16x16x32_bf16 v[106:109], v[150:153], v[182:185], v[106:109]
	v_mfma_f32_16x16x32_bf16 v[94:97], v[136:139], v[190:193], v[94:97]
	v_mfma_f32_16x16x32_bf16 v[90:93], v[150:153], v[190:193], v[90:93]
	v_mfma_f32_16x16x32_bf16 v[78:81], v[136:139], v[198:201], v[78:81]
	v_mfma_f32_16x16x32_bf16 v[74:77], v[150:153], v[198:201], v[74:77]
	v_mfma_f32_16x16x32_bf16 v[126:129], v[146:149], v[178:181], v[126:129]
	v_mfma_f32_16x16x32_bf16 v[122:125], v[154:157], v[178:181], v[122:125]
	v_mfma_f32_16x16x32_bf16 v[110:113], v[146:149], v[186:189], v[110:113]
	v_mfma_f32_16x16x32_bf16 v[106:109], v[154:157], v[186:189], v[106:109]
	v_mfma_f32_16x16x32_bf16 v[94:97], v[146:149], v[194:197], v[94:97]
	v_mfma_f32_16x16x32_bf16 v[90:93], v[154:157], v[194:197], v[90:93]
	v_mfma_f32_16x16x32_bf16 v[78:81], v[146:149], v[202:205], v[78:81]
	v_mfma_f32_16x16x32_bf16 v[74:77], v[154:157], v[202:205], v[74:77]
	v_mfma_f32_16x16x32_bf16 v[118:121], v[158:161], v[174:177], v[118:121]
	v_mfma_f32_16x16x32_bf16 v[114:117], v[166:169], v[174:177], v[114:117]
	v_mfma_f32_16x16x32_bf16 v[102:105], v[158:161], v[182:185], v[102:105]
	v_mfma_f32_16x16x32_bf16 v[98:101], v[166:169], v[182:185], v[98:101]
	v_mfma_f32_16x16x32_bf16 v[86:89], v[158:161], v[190:193], v[86:89]
	v_mfma_f32_16x16x32_bf16 v[82:85], v[166:169], v[190:193], v[82:85]
	v_mfma_f32_16x16x32_bf16 v[70:73], v[158:161], v[198:201], v[70:73]
	v_mfma_f32_16x16x32_bf16 v[66:69], v[166:169], v[198:201], v[66:69]
	v_mfma_f32_16x16x32_bf16 v[118:121], v[162:165], v[178:181], v[118:121]
	v_mfma_f32_16x16x32_bf16 v[114:117], v[170:173], v[178:181], v[114:117]
	v_mfma_f32_16x16x32_bf16 v[102:105], v[162:165], v[186:189], v[102:105]
	v_mfma_f32_16x16x32_bf16 v[98:101], v[170:173], v[186:189], v[98:101]
	v_mfma_f32_16x16x32_bf16 v[86:89], v[162:165], v[194:197], v[86:89]
	v_mfma_f32_16x16x32_bf16 v[82:85], v[170:173], v[194:197], v[82:85]
	v_mfma_f32_16x16x32_bf16 v[70:73], v[162:165], v[202:205], v[70:73]
	v_mfma_f32_16x16x32_bf16 v[66:69], v[170:173], v[202:205], v[66:69]
	s_setprio 0
	s_barrier
	s_mov_b32 m0, s45
	v_lshl_add_u64 v[206:207], s[48:49], 0, v[0:1]
	ds_read_b128 v[174:177], v145 offset:16384
	ds_read_b128 v[178:181], v145 offset:17408
	ds_read_b128 v[182:185], v145 offset:18432
	ds_read_b128 v[186:189], v145 offset:19456
	ds_read_b128 v[190:193], v145 offset:20480
	ds_read_b128 v[194:197], v145 offset:21504
	ds_read_b128 v[198:201], v145 offset:22528
	ds_read_b128 v[202:205], v145 offset:23552
	global_load_lds_dwordx4 v[206:207], off
	v_lshl_add_u64 v[208:209], s[48:49], 0, v[130:131]
	s_mov_b32 m0, s29
	v_lshl_add_u64 v[210:211], s[50:51], 0, v[0:1]
	global_load_lds_dwordx4 v[208:209], off
	s_mov_b32 m0, s44
	v_lshl_add_u64 v[212:213], s[46:47], 0, v[132:133]
	global_load_lds_dwordx4 v[210:211], off
	v_lshl_add_u64 v[210:211], s[50:51], 0, v[130:131]
	s_mov_b32 m0, s35
	s_nop 0
	global_load_lds_dwordx4 v[210:211], off
	v_lshl_add_u64 v[210:211], s[46:47], 0, v[134:135]
	s_mov_b32 m0, s60
	s_nop 0
	global_load_lds_dwordx4 v[210:211], off
	s_mov_b32 m0, s61
	s_nop 0
	global_load_lds_dwordx4 v[212:213], off
	s_waitcnt vmcnt(8)
	s_waitcnt lgkmcnt(0)
	s_barrier
; #define PG8_STAGE(bufoff, gbase, voff) do { _Pragma("unroll") for (int _i = 0; _i < 2; ++_i) \
;         __builtin_amdgcn_global_load_lds((const unsigned*)((const char*)(gbase) + (voff)[_i]), (LAS unsigned*)(lds + (bufoff) + ldsw + _i * 8192), 16, 0, 0); } while (0)
; #define PG8_LDA(dst, b, h) do { _Pragma("unroll") for (int m = 0; m < 4; ++m) _Pragma("unroll") for (int k = 0; k < 2; ++k) dst[m][k] = *(const LAS bf16x8*)(lds + PG8_SA(b, h) + aoff + m * 2048 + k * 1024); } while (0)
; #define PG8_LDB(dst, b, h) do { _Pragma("unroll") for (int n = 0; n < 2; ++n) _Pragma("unroll") for (int k = 0; k < 2; ++k) dst[n][k] = *(const LAS bf16x8*)(lds + PG8_SB(b, h) + boff + n * 2048 + k * 1024); } while (0)
; #define PG8_MMA(ai, bj, At, Bt) do { __builtin_amdgcn_s_setprio(1); _Pragma("unroll") for (int m = 0; m < 4; ++m) _Pragma("unroll") for (int n = 0; n < 2; ++n) _Pragma("unroll") for (int k = 0; k < 2; ++k) \
;         acc[ai][bj][m][n] = __builtin_amdgcn_mfma_f32_16x16x32_bf16(Bt[n][k], At[m][k], acc[ai][bj][m][n], 0, 0, 0); __builtin_amdgcn_s_setprio(0); } while (0)
; #define PG8_WAIT_V(n) asm volatile("s_waitcnt vmcnt(" #n ")" ::: "memory")
; #define PG8_WAIT_L(n) asm volatile("s_waitcnt lgkmcnt(" #n ")" ::: "memory")
; #define PG8_BAR __builtin_amdgcn_s_barrier()
; #define PG8_SCHED __builtin_amdgcn_sched_barrier(0)
; template <class Epi, class Sched, bool ALIGN_EPI, bool LAST_FUSED = false, bool PERM = false, bool CARRY = false>
; __device__ __forceinline__ void gemm_phase(LAS unsigned char* lds, const int tid, const int K, const int lda, const int ldb, const Sched& S, const Epi& E) {
;     ...
;             PG8_WAIT_V(8); PG8_WAIT_L(0); PG8_BAR; PG8_MMA(1, 0, At, B0); PG8_MMA(1, 1, At, B1); PG8_BAR; PG8_SCHED;
;             PG8_LDB(B0, 1, 0); PG8_LDB(B1, 1, 1); PG8_SCHED; PG8_LDA(At, 1, 0); PG8_STAGE(PG8_SA(0, 1), a2 + hstepA, voffA);
;             PG8_WAIT_V(8); PG8_WAIT_L(0); PG8_BAR; PG8_MMA(0, 0, At, B0); PG8_MMA(0, 1, At, B1); PG8_BAR; PG8_SCHED;
	s_setprio 1
	s_waitcnt lgkmcnt(0)
	v_mfma_f32_16x16x32_bf16 v[62:65], v[136:139], v[174:177], v[62:65]
	v_mfma_f32_16x16x32_bf16 v[58:61], v[150:153], v[174:177], v[58:61]
	v_mfma_f32_16x16x32_bf16 v[46:49], v[136:139], v[182:185], v[46:49]
	v_mfma_f32_16x16x32_bf16 v[42:45], v[150:153], v[182:185], v[42:45]
	v_mfma_f32_16x16x32_bf16 v[30:33], v[136:139], v[190:193], v[30:33]
	v_mfma_f32_16x16x32_bf16 v[26:29], v[150:153], v[190:193], v[26:29]
	v_mfma_f32_16x16x32_bf16 v[14:17], v[136:139], v[198:201], v[14:17]
	v_mfma_f32_16x16x32_bf16 v[10:13], v[150:153], v[198:201], v[10:13]
	v_mfma_f32_16x16x32_bf16 v[62:65], v[146:149], v[178:181], v[62:65]
	v_mfma_f32_16x16x32_bf16 v[58:61], v[154:157], v[178:181], v[58:61]
	v_mfma_f32_16x16x32_bf16 v[46:49], v[146:149], v[186:189], v[46:49]
	v_mfma_f32_16x16x32_bf16 v[42:45], v[154:157], v[186:189], v[42:45]
	v_mfma_f32_16x16x32_bf16 v[30:33], v[146:149], v[194:197], v[30:33]
	v_mfma_f32_16x16x32_bf16 v[26:29], v[154:157], v[194:197], v[26:29]
	v_mfma_f32_16x16x32_bf16 v[14:17], v[146:149], v[202:205], v[14:17]
	v_mfma_f32_16x16x32_bf16 v[10:13], v[154:157], v[202:205], v[10:13]
	v_mfma_f32_16x16x32_bf16 v[54:57], v[158:161], v[174:177], v[54:57]
	v_mfma_f32_16x16x32_bf16 v[50:53], v[166:169], v[174:177], v[50:53]
	v_mfma_f32_16x16x32_bf16 v[38:41], v[158:161], v[182:185], v[38:41]
	v_mfma_f32_16x16x32_bf16 v[34:37], v[166:169], v[182:185], v[34:37]
	v_mfma_f32_16x16x32_bf16 v[22:25], v[158:161], v[190:193], v[22:25]
	v_mfma_f32_16x16x32_bf16 v[18:21], v[166:169], v[190:193], v[18:21]
	v_mfma_f32_16x16x32_bf16 v[6:9], v[158:161], v[198:201], v[6:9]
	v_mfma_f32_16x16x32_bf16 v[2:5], v[166:169], v[198:201], v[2:5]
	v_mfma_f32_16x16x32_bf16 v[54:57], v[162:165], v[178:181], v[54:57]
	v_mfma_f32_16x16x32_bf16 v[50:53], v[170:173], v[178:181], v[50:53]
	v_mfma_f32_16x16x32_bf16 v[38:41], v[162:165], v[186:189], v[38:41]
	v_mfma_f32_16x16x32_bf16 v[34:37], v[170:173], v[186:189], v[34:37]
	v_mfma_f32_16x16x32_bf16 v[22:25], v[162:165], v[194:197], v[22:25]
	v_mfma_f32_16x16x32_bf16 v[18:21], v[170:173], v[194:197], v[18:21]
	v_mfma_f32_16x16x32_bf16 v[6:9], v[162:165], v[202:205], v[6:9]
	v_mfma_f32_16x16x32_bf16 v[2:5], v[170:173], v[202:205], v[2:5]
	s_setprio 0
	s_barrier
	v_add_u32_e32 v154, s28, v144
	v_add_u32_e32 v170, s27, v144
	ds_read_b128 v[136:139], v154
	ds_read_b128 v[146:149], v154 offset:1024
	ds_read_b128 v[150:153], v154 offset:2048
	ds_read_b128 v[154:157], v154 offset:3072
	ds_read_b128 v[158:161], v170
	ds_read_b128 v[162:165], v170 offset:1024
	ds_read_b128 v[166:169], v170 offset:2048
	ds_read_b128 v[170:173], v170 offset:3072
	s_mov_b32 m0, s62
	v_lshl_add_u64 v[214:215], s[42:43], 0, v[134:135]
	ds_read_b128 v[174:177], v145 offset:32768
	ds_read_b128 v[178:181], v145 offset:33792
	ds_read_b128 v[182:185], v145 offset:34816
	ds_read_b128 v[186:189], v145 offset:35840
	ds_read_b128 v[190:193], v145 offset:36864
	ds_read_b128 v[194:197], v145 offset:37888
	ds_read_b128 v[198:201], v145 offset:38912
	ds_read_b128 v[202:205], v145 offset:39936
	global_load_lds_dwordx4 v[214:215], off
	v_lshl_add_u64 v[214:215], s[42:43], 0, v[132:133]
	s_mov_b32 m0, s63
	s_nop 0
	global_load_lds_dwordx4 v[214:215], off
	s_waitcnt vmcnt(8)
	s_waitcnt lgkmcnt(0)
	s_barrier
	s_setprio 1
	s_waitcnt lgkmcnt(0)
	v_mfma_f32_16x16x32_bf16 v[126:129], v[136:139], v[174:177], v[126:129]
	v_mfma_f32_16x16x32_bf16 v[122:125], v[150:153], v[174:177], v[122:125]
	v_mfma_f32_16x16x32_bf16 v[110:113], v[136:139], v[182:185], v[110:113]
	v_mfma_f32_16x16x32_bf16 v[106:109], v[150:153], v[182:185], v[106:109]
	v_mfma_f32_16x16x32_bf16 v[94:97], v[136:139], v[190:193], v[94:97]
	v_mfma_f32_16x16x32_bf16 v[90:93], v[150:153], v[190:193], v[90:93]
	v_mfma_f32_16x16x32_bf16 v[78:81], v[136:139], v[198:201], v[78:81]
	v_mfma_f32_16x16x32_bf16 v[74:77], v[150:153], v[198:201], v[74:77]
	v_mfma_f32_16x16x32_bf16 v[126:129], v[146:149], v[178:181], v[126:129]
	v_mfma_f32_16x16x32_bf16 v[122:125], v[154:157], v[178:181], v[122:125]
	v_mfma_f32_16x16x32_bf16 v[110:113], v[146:149], v[186:189], v[110:113]
	v_mfma_f32_16x16x32_bf16 v[106:109], v[154:157], v[186:189], v[106:109]
	v_mfma_f32_16x16x32_bf16 v[94:97], v[146:149], v[194:197], v[94:97]
	v_mfma_f32_16x16x32_bf16 v[90:93], v[154:157], v[194:197], v[90:93]
	v_mfma_f32_16x16x32_bf16 v[78:81], v[146:149], v[202:205], v[78:81]
	v_mfma_f32_16x16x32_bf16 v[74:77], v[154:157], v[202:205], v[74:77]
	v_mfma_f32_16x16x32_bf16 v[118:121], v[158:161], v[174:177], v[118:121]
	v_mfma_f32_16x16x32_bf16 v[114:117], v[166:169], v[174:177], v[114:117]
	v_mfma_f32_16x16x32_bf16 v[102:105], v[158:161], v[182:185], v[102:105]
	v_mfma_f32_16x16x32_bf16 v[98:101], v[166:169], v[182:185], v[98:101]
	v_mfma_f32_16x16x32_bf16 v[86:89], v[158:161], v[190:193], v[86:89]
	v_mfma_f32_16x16x32_bf16 v[82:85], v[166:169], v[190:193], v[82:85]
	v_mfma_f32_16x16x32_bf16 v[70:73], v[158:161], v[198:201], v[70:73]
	v_mfma_f32_16x16x32_bf16 v[66:69], v[166:169], v[198:201], v[66:69]
	v_mfma_f32_16x16x32_bf16 v[118:121], v[162:165], v[178:181], v[118:121]
	v_mfma_f32_16x16x32_bf16 v[114:117], v[170:173], v[178:181], v[114:117]
	v_mfma_f32_16x16x32_bf16 v[102:105], v[162:165], v[186:189], v[102:105]
	v_mfma_f32_16x16x32_bf16 v[98:101], v[170:173], v[186:189], v[98:101]
	v_mfma_f32_16x16x32_bf16 v[86:89], v[162:165], v[194:197], v[86:89]
	v_mfma_f32_16x16x32_bf16 v[82:85], v[170:173], v[194:197], v[82:85]
	v_mfma_f32_16x16x32_bf16 v[70:73], v[162:165], v[202:205], v[70:73]
	v_mfma_f32_16x16x32_bf16 v[66:69], v[170:173], v[202:205], v[66:69]
	s_setprio 0
	s_barrier
; #define PG8_STAGE(bufoff, gbase, voff) do { _Pragma("unroll") for (int _i = 0; _i < 2; ++_i) \
;         __builtin_amdgcn_global_load_lds((const unsigned*)((const char*)(gbase) + (voff)[_i]), (LAS unsigned*)(lds + (bufoff) + ldsw + _i * 8192), 16, 0, 0); } while (0)
; #define PG8_LDA(dst, b, h) do { _Pragma("unroll") for (int m = 0; m < 4; ++m) _Pragma("unroll") for (int k = 0; k < 2; ++k) dst[m][k] = *(const LAS bf16x8*)(lds + PG8_SA(b, h) + aoff + m * 2048 + k * 1024); } while (0)
; #define PG8_MMA(ai, bj, At, Bt) do { __builtin_amdgcn_s_setprio(1); _Pragma("unroll") for (int m = 0; m < 4; ++m) _Pragma("unroll") for (int n = 0; n < 2; ++n) _Pragma("unroll") for (int k = 0; k < 2; ++k) \
;         acc[ai][bj][m][n] = __builtin_amdgcn_mfma_f32_16x16x32_bf16(Bt[n][k], At[m][k], acc[ai][bj][m][n], 0, 0, 0); __builtin_amdgcn_s_setprio(0); } while (0)
; #define PG8_WAIT_V(n) asm volatile("s_waitcnt vmcnt(" #n ")" ::: "memory")
; #define PG8_WAIT_L(n) asm volatile("s_waitcnt lgkmcnt(" #n ")" ::: "memory")
; #define PG8_BAR __builtin_amdgcn_s_barrier()
; #define PG8_SCHED __builtin_amdgcn_sched_barrier(0)
; template <class Epi, class Sched, bool ALIGN_EPI, bool LAST_FUSED = false, bool PERM = false, bool CARRY = false>
; __device__ __forceinline__ void gemm_phase(LAS unsigned char* lds, const int tid, const int K, const int lda, const int ldb, const Sched& S, const Epi& E) {
;     ...
;             PG8_LDA(At, 1, 1); PG8_STAGE(PG8_SB(1, 0), b3, voffB); PG8_STAGE(PG8_SB(1, 1), b3 + hstepB, voffB); PG8_STAGE(PG8_SA(1, 0), a3, voffA);
;             PG8_WAIT_V(8); PG8_WAIT_L(0); PG8_BAR; PG8_MMA(1, 0, At, B0); PG8_MMA(1, 1, At, B1); PG8_BAR; PG8_SCHED;
;         }
;         if constexpr (ALIGN_EPI) { if (wr == 0) PG8_BAR; }
	s_mov_b32 m0, s23
	v_lshl_add_u64 v[206:207], v[206:207], 0, s[68:69]
	ds_read_b128 v[174:177], v145 offset:49152
	ds_read_b128 v[178:181], v145 offset:50176
	ds_read_b128 v[182:185], v145 offset:51200
	ds_read_b128 v[186:189], v145 offset:52224
	ds_read_b128 v[190:193], v145 offset:53248
	ds_read_b128 v[194:197], v145 offset:54272
	ds_read_b128 v[198:201], v145 offset:55296
	ds_read_b128 v[202:205], v145 offset:56320
	global_load_lds_dwordx4 v[206:207], off
	v_lshl_add_u64 v[206:207], v[208:209], 0, s[68:69]
	s_mov_b32 m0, s15
	s_nop 0
	global_load_lds_dwordx4 v[206:207], off
	v_lshl_add_u64 v[206:207], s[40:41], 0, v[0:1]
	s_mov_b32 m0, s76
	s_nop 0
	global_load_lds_dwordx4 v[206:207], off
	v_lshl_add_u64 v[206:207], s[40:41], 0, v[130:131]
	s_mov_b32 m0, s75
	s_nop 0
	global_load_lds_dwordx4 v[206:207], off
	v_lshl_add_u64 v[206:207], v[210:211], 0, s[68:69]
	s_mov_b32 m0, s66
	s_nop 0
	global_load_lds_dwordx4 v[206:207], off
	v_lshl_add_u64 v[206:207], v[212:213], 0, s[68:69]
	s_mov_b32 m0, s67
	s_nop 0
	global_load_lds_dwordx4 v[206:207], off
	s_waitcnt vmcnt(8)
	s_waitcnt lgkmcnt(0)
	s_barrier
	s_setprio 1
	s_waitcnt lgkmcnt(0)
	v_mfma_f32_16x16x32_bf16 v[62:65], v[136:139], v[174:177], v[62:65]
	v_mfma_f32_16x16x32_bf16 v[58:61], v[150:153], v[174:177], v[58:61]
	v_mfma_f32_16x16x32_bf16 v[46:49], v[136:139], v[182:185], v[46:49]
	v_mfma_f32_16x16x32_bf16 v[42:45], v[150:153], v[182:185], v[42:45]
	v_mfma_f32_16x16x32_bf16 v[30:33], v[136:139], v[190:193], v[30:33]
	v_mfma_f32_16x16x32_bf16 v[26:29], v[150:153], v[190:193], v[26:29]
	v_mfma_f32_16x16x32_bf16 v[14:17], v[136:139], v[198:201], v[14:17]
	v_mfma_f32_16x16x32_bf16 v[10:13], v[150:153], v[198:201], v[10:13]
	v_mfma_f32_16x16x32_bf16 v[62:65], v[146:149], v[178:181], v[62:65]
	v_mfma_f32_16x16x32_bf16 v[58:61], v[154:157], v[178:181], v[58:61]
	v_mfma_f32_16x16x32_bf16 v[46:49], v[146:149], v[186:189], v[46:49]
	v_mfma_f32_16x16x32_bf16 v[42:45], v[154:157], v[186:189], v[42:45]
	v_mfma_f32_16x16x32_bf16 v[30:33], v[146:149], v[194:197], v[30:33]
	v_mfma_f32_16x16x32_bf16 v[26:29], v[154:157], v[194:197], v[26:29]
	v_mfma_f32_16x16x32_bf16 v[14:17], v[146:149], v[202:205], v[14:17]
	v_mfma_f32_16x16x32_bf16 v[10:13], v[154:157], v[202:205], v[10:13]
	v_mfma_f32_16x16x32_bf16 v[54:57], v[158:161], v[174:177], v[54:57]
	v_mfma_f32_16x16x32_bf16 v[50:53], v[166:169], v[174:177], v[50:53]
	v_mfma_f32_16x16x32_bf16 v[38:41], v[158:161], v[182:185], v[38:41]
	v_mfma_f32_16x16x32_bf16 v[34:37], v[166:169], v[182:185], v[34:37]
	v_mfma_f32_16x16x32_bf16 v[22:25], v[158:161], v[190:193], v[22:25]
	v_mfma_f32_16x16x32_bf16 v[18:21], v[166:169], v[190:193], v[18:21]
	v_mfma_f32_16x16x32_bf16 v[6:9], v[158:161], v[198:201], v[6:9]
	v_mfma_f32_16x16x32_bf16 v[2:5], v[166:169], v[198:201], v[2:5]
	v_mfma_f32_16x16x32_bf16 v[54:57], v[162:165], v[178:181], v[54:57]
	v_mfma_f32_16x16x32_bf16 v[50:53], v[170:173], v[178:181], v[50:53]
	v_mfma_f32_16x16x32_bf16 v[38:41], v[162:165], v[186:189], v[38:41]
	v_mfma_f32_16x16x32_bf16 v[34:37], v[170:173], v[186:189], v[34:37]
	v_mfma_f32_16x16x32_bf16 v[22:25], v[162:165], v[194:197], v[22:25]
	v_mfma_f32_16x16x32_bf16 v[18:21], v[170:173], v[194:197], v[18:21]
	v_mfma_f32_16x16x32_bf16 v[6:9], v[162:165], v[202:205], v[6:9]
	v_mfma_f32_16x16x32_bf16 v[2:5], v[170:173], v[202:205], v[2:5]
	s_setprio 0
	s_barrier
	s_movk_i32 s15, 0x100
	s_andn2_b64 vcc, exec, s[38:39]
	s_mov_b64 s[40:41], -1
	s_mov_b64 s[38:39], 0
	s_cbranch_vccz .LBB0_601
	s_and_b64 vcc, exec, s[12:13]
	s_cbranch_vccz .LBB0_604
	s_barrier

; #define PG8_STAGE(bufoff, gbase, voff) do { _Pragma("unroll") for (int _i = 0; _i < 2; ++_i) \
;         __builtin_amdgcn_global_load_lds((const unsigned*)((const char*)(gbase) + (voff)[_i]), (LAS unsigned*)(lds + (bufoff) + ldsw + _i * 8192), 16, 0, 0); } while (0)
; #define PG8_LDA(dst, b, h) do { _Pragma("unroll") for (int m = 0; m < 4; ++m) _Pragma("unroll") for (int k = 0; k < 2; ++k) dst[m][k] = *(const LAS bf16x8*)(lds + PG8_SA(b, h) + aoff + m * 2048 + k * 1024); } while (0)
; #define PG8_LDB(dst, b, h) do { _Pragma("unroll") for (int n = 0; n < 2; ++n) _Pragma("unroll") for (int k = 0; k < 2; ++k) dst[n][k] = *(const LAS bf16x8*)(lds + PG8_SB(b, h) + boff + n * 2048 + k * 1024); } while (0)
; #define PG8_MMA(ai, bj, At, Bt) do { __builtin_amdgcn_s_setprio(1); _Pragma("unroll") for (int m = 0; m < 4; ++m) _Pragma("unroll") for (int n = 0; n < 2; ++n) _Pragma("unroll") for (int k = 0; k < 2; ++k) \
;         acc[ai][bj][m][n] = __builtin_amdgcn_mfma_f32_16x16x32_bf16(Bt[n][k], At[m][k], acc[ai][bj][m][n], 0, 0, 0); __builtin_amdgcn_s_setprio(0); } while (0)
; #define PG8_WAIT_V(n) asm volatile("s_waitcnt vmcnt(" #n ")" ::: "memory")
; #define PG8_WAIT_L(n) asm volatile("s_waitcnt lgkmcnt(" #n ")" ::: "memory")
; template <class Epi, class Sched, bool ALIGN_EPI, bool LAST_FUSED = false, bool PERM = false, bool CARRY = false>
; __device__ __forceinline__ void gemm_phase(LAS unsigned char* lds, const int tid, const int K, const int lda, const int ldb, const Sched& S, const Epi& E) {
;     ...
;         for (int t = 0; t < nt; t += 2) {
;             const bool last = (t == nt - 2);
;             const char* a1 = cA + (size_t)(t + 1) * kstep;
;             const char* a2 = last ? nA : cA + (size_t)(t + 2) * kstep; const char* b2 = last ? nB : cB + (size_t)(t + 2) * kstep;
;             const char* a3 = a2 + kstep; const char* b3 = b2 + kstep;
;             PG8_LDB(B0, 0, 0); PG8_LDB(B1, 0, 1); PG8_SCHED; PG8_LDA(At, 0, 0); PG8_STAGE(PG8_SA(1, 1), a1 + hstepA, voffA);
;             PG8_WAIT_V(8); PG8_WAIT_L(0); PG8_BAR; PG8_MMA(0, 0, At, B0); PG8_MMA(0, 1, At, B1); PG8_BAR; PG8_SCHED;
;             PG8_LDA(At, 0, 1); PG8_STAGE(PG8_SB(0, 0), b2, voffB); PG8_STAGE(PG8_SB(0, 1), b2 + hstepB, voffB); PG8_STAGE(PG8_SA(0, 0), a2, voffA);
;             PG8_WAIT_V(8); PG8_WAIT_L(0); PG8_BAR; PG8_MMA(1, 0, At, B0); PG8_MMA(1, 1, At, B1); PG8_BAR; PG8_SCHED;
.LBB0_622:
	s_add_u32 s48, s30, s24
	s_addc_u32 s49, s31, 0
	s_add_u32 s42, s48, 0x100
	s_addc_u32 s43, s49, 0
	s_and_b64 s[40:41], s[38:39], exec
	s_cselect_b32 s43, s15, s43
	s_cselect_b32 s42, s14, s42
	s_add_u32 s24, s26, s24
	s_addc_u32 s40, s27, 0
	s_add_u32 s24, s24, 0x100
	s_addc_u32 s40, s40, 0
	s_add_i32 s62, 0, 0x10000
	s_and_b64 s[38:39], s[38:39], exec
	s_cselect_b32 s47, s17, s40
	s_cselect_b32 s46, s16, s24
	s_add_i32 s39, 0, 0x14000
	s_add_u32 s64, s48, 0x30080
	s_addc_u32 s65, s49, 0
	s_add_i32 s67, s62, s29
	s_add_i32 m0, s45, 0xc000
	s_add_i32 s66, s45, 0xe000
	s_add_i32 s70, s67, 0x2000
	s_add_u32 s48, s46, 0x10000
	v_add_u32_e32 v152, s62, v140
	v_add_u32_e32 v168, s39, v140
	s_addc_u32 s49, s47, 0
	s_add_i32 s71, s39, s29
	ds_read_b128 v[136:139], v152
	ds_read_b128 v[144:147], v152 offset:1024
	ds_read_b128 v[148:151], v152 offset:2048
	ds_read_b128 v[152:155], v152 offset:3072
	ds_read_b128 v[156:159], v168
	ds_read_b128 v[160:163], v168 offset:1024
	ds_read_b128 v[164:167], v168 offset:2048
	ds_read_b128 v[168:171], v168 offset:3072
	s_add_i32 s74, s71, 0x2000
	s_add_i32 s75, 0, 0x18000
	s_add_i32 s76, 0, 0x1c000
	s_add_u32 s40, s42, 0x30000
	s_addc_u32 s41, s43, 0
	s_add_i32 s61, s75, s29
	s_add_i32 s24, s61, 0x2000
	s_add_u32 s38, s46, 0x10080
	s_addc_u32 s39, s47, 0
	s_add_i32 s63, s76, s29
	s_add_i32 s62, s63, 0x2000
	v_lshl_add_u64 v[204:205], s[64:65], 0, v[130:131]
	ds_read_b128 v[172:175], v143
	ds_read_b128 v[176:179], v143 offset:1024
	ds_read_b128 v[180:183], v143 offset:2048
	ds_read_b128 v[184:187], v143 offset:3072
	ds_read_b128 v[188:191], v143 offset:4096
	ds_read_b128 v[192:195], v143 offset:5120
	ds_read_b128 v[196:199], v143 offset:6144
	ds_read_b128 v[200:203], v143 offset:7168
	global_load_lds_dwordx4 v[204:205], off
	v_lshl_add_u64 v[204:205], s[64:65], 0, v[132:133]
	s_mov_b32 m0, s66
	s_nop 0
	global_load_lds_dwordx4 v[204:205], off
	s_waitcnt vmcnt(8)
	s_waitcnt lgkmcnt(0)
	s_barrier
	s_setprio 1
	s_waitcnt lgkmcnt(0)
	v_mfma_f32_16x16x32_bf16 v[126:129], v[136:139], v[172:175], v[126:129]
	v_mfma_f32_16x16x32_bf16 v[122:125], v[148:151], v[172:175], v[122:125]
	v_mfma_f32_16x16x32_bf16 v[118:121], v[136:139], v[180:183], v[118:121]
	v_mfma_f32_16x16x32_bf16 v[114:117], v[148:151], v[180:183], v[114:117]
	v_mfma_f32_16x16x32_bf16 v[110:113], v[136:139], v[188:191], v[110:113]
	v_mfma_f32_16x16x32_bf16 v[106:109], v[148:151], v[188:191], v[106:109]
	v_mfma_f32_16x16x32_bf16 v[102:105], v[136:139], v[196:199], v[102:105]
	v_mfma_f32_16x16x32_bf16 v[98:101], v[148:151], v[196:199], v[98:101]
	v_mfma_f32_16x16x32_bf16 v[126:129], v[144:147], v[176:179], v[126:129]
	v_mfma_f32_16x16x32_bf16 v[122:125], v[152:155], v[176:179], v[122:125]
	v_mfma_f32_16x16x32_bf16 v[118:121], v[144:147], v[184:187], v[118:121]
	v_mfma_f32_16x16x32_bf16 v[114:117], v[152:155], v[184:187], v[114:117]
	v_mfma_f32_16x16x32_bf16 v[110:113], v[144:147], v[192:195], v[110:113]
	v_mfma_f32_16x16x32_bf16 v[106:109], v[152:155], v[192:195], v[106:109]
	v_mfma_f32_16x16x32_bf16 v[102:105], v[144:147], v[200:203], v[102:105]
	v_mfma_f32_16x16x32_bf16 v[98:101], v[152:155], v[200:203], v[98:101]
	v_mfma_f32_16x16x32_bf16 v[94:97], v[156:159], v[172:175], v[94:97]
	v_mfma_f32_16x16x32_bf16 v[90:93], v[164:167], v[172:175], v[90:93]
	v_mfma_f32_16x16x32_bf16 v[86:89], v[156:159], v[180:183], v[86:89]
	v_mfma_f32_16x16x32_bf16 v[82:85], v[164:167], v[180:183], v[82:85]
	v_mfma_f32_16x16x32_bf16 v[78:81], v[156:159], v[188:191], v[78:81]
	v_mfma_f32_16x16x32_bf16 v[74:77], v[164:167], v[188:191], v[74:77]
	v_mfma_f32_16x16x32_bf16 v[70:73], v[156:159], v[196:199], v[70:73]
	v_mfma_f32_16x16x32_bf16 v[66:69], v[164:167], v[196:199], v[66:69]
	v_mfma_f32_16x16x32_bf16 v[94:97], v[160:163], v[176:179], v[94:97]
	v_mfma_f32_16x16x32_bf16 v[90:93], v[168:171], v[176:179], v[90:93]
	v_mfma_f32_16x16x32_bf16 v[86:89], v[160:163], v[184:187], v[86:89]
	v_mfma_f32_16x16x32_bf16 v[82:85], v[168:171], v[184:187], v[82:85]
	v_mfma_f32_16x16x32_bf16 v[78:81], v[160:163], v[192:195], v[78:81]
	v_mfma_f32_16x16x32_bf16 v[74:77], v[168:171], v[192:195], v[74:77]
	v_mfma_f32_16x16x32_bf16 v[70:73], v[160:163], v[200:203], v[70:73]
	v_mfma_f32_16x16x32_bf16 v[66:69], v[168:171], v[200:203], v[66:69]
	s_setprio 0
	s_barrier
	s_mov_b32 m0, s67
	v_lshl_add_u64 v[204:205], s[46:47], 0, v[0:1]
	ds_read_b128 v[172:175], v143 offset:16384
	ds_read_b128 v[176:179], v143 offset:17408
	ds_read_b128 v[180:183], v143 offset:18432
	ds_read_b128 v[184:187], v143 offset:19456
	ds_read_b128 v[188:191], v143 offset:20480
	ds_read_b128 v[192:195], v143 offset:21504
	ds_read_b128 v[196:199], v143 offset:22528
	ds_read_b128 v[200:203], v143 offset:23552
	global_load_lds_dwordx4 v[204:205], off
	v_lshl_add_u64 v[206:207], s[46:47], 0, v[134:135]
	s_mov_b32 m0, s70
	v_lshl_add_u64 v[208:209], s[48:49], 0, v[0:1]
	global_load_lds_dwordx4 v[206:207], off
	s_mov_b32 m0, s71
	v_lshl_add_u64 v[210:211], s[42:43], 0, v[132:133]
	global_load_lds_dwordx4 v[208:209], off
	v_lshl_add_u64 v[208:209], s[48:49], 0, v[134:135]
	s_mov_b32 m0, s74
	s_nop 0
	global_load_lds_dwordx4 v[208:209], off
	v_lshl_add_u64 v[208:209], s[42:43], 0, v[130:131]
	s_mov_b32 m0, s45
	s_nop 0
	global_load_lds_dwordx4 v[208:209], off
	s_mov_b32 m0, s50
	s_nop 0
	global_load_lds_dwordx4 v[210:211], off
	s_waitcnt vmcnt(8)
	s_waitcnt lgkmcnt(0)
	s_barrier
; #define PG8_STAGE(bufoff, gbase, voff) do { _Pragma("unroll") for (int _i = 0; _i < 2; ++_i) \
;         __builtin_amdgcn_global_load_lds((const unsigned*)((const char*)(gbase) + (voff)[_i]), (LAS unsigned*)(lds + (bufoff) + ldsw + _i * 8192), 16, 0, 0); } while (0)
; #define PG8_LDA(dst, b, h) do { _Pragma("unroll") for (int m = 0; m < 4; ++m) _Pragma("unroll") for (int k = 0; k < 2; ++k) dst[m][k] = *(const LAS bf16x8*)(lds + PG8_SA(b, h) + aoff + m * 2048 + k * 1024); } while (0)
; #define PG8_LDB(dst, b, h) do { _Pragma("unroll") for (int n = 0; n < 2; ++n) _Pragma("unroll") for (int k = 0; k < 2; ++k) dst[n][k] = *(const LAS bf16x8*)(lds + PG8_SB(b, h) + boff + n * 2048 + k * 1024); } while (0)
; #define PG8_MMA(ai, bj, At, Bt) do { __builtin_amdgcn_s_setprio(1); _Pragma("unroll") for (int m = 0; m < 4; ++m) _Pragma("unroll") for (int n = 0; n < 2; ++n) _Pragma("unroll") for (int k = 0; k < 2; ++k) \
;         acc[ai][bj][m][n] = __builtin_amdgcn_mfma_f32_16x16x32_bf16(Bt[n][k], At[m][k], acc[ai][bj][m][n], 0, 0, 0); __builtin_amdgcn_s_setprio(0); } while (0)
; #define PG8_WAIT_V(n) asm volatile("s_waitcnt vmcnt(" #n ")" ::: "memory")
; #define PG8_WAIT_L(n) asm volatile("s_waitcnt lgkmcnt(" #n ")" ::: "memory")
; #define PG8_BAR __builtin_amdgcn_s_barrier()
; #define PG8_SCHED __builtin_amdgcn_sched_barrier(0)
; template <class Epi, class Sched, bool ALIGN_EPI, bool LAST_FUSED = false, bool PERM = false, bool CARRY = false>
; __device__ __forceinline__ void gemm_phase(LAS unsigned char* lds, const int tid, const int K, const int lda, const int ldb, const Sched& S, const Epi& E) {
;     ...
;             PG8_WAIT_V(8); PG8_WAIT_L(0); PG8_BAR; PG8_MMA(1, 0, At, B0); PG8_MMA(1, 1, At, B1); PG8_BAR; PG8_SCHED;
;             PG8_LDB(B0, 1, 0); PG8_LDB(B1, 1, 1); PG8_SCHED; PG8_LDA(At, 1, 0); PG8_STAGE(PG8_SA(0, 1), a2 + hstepA, voffA);
;             PG8_WAIT_V(8); PG8_WAIT_L(0); PG8_BAR; PG8_MMA(0, 0, At, B0); PG8_MMA(0, 1, At, B1); PG8_BAR; PG8_SCHED;
	s_setprio 1
	s_waitcnt lgkmcnt(0)
	v_mfma_f32_16x16x32_bf16 v[62:65], v[136:139], v[172:175], v[62:65]
	v_mfma_f32_16x16x32_bf16 v[58:61], v[148:151], v[172:175], v[58:61]
	v_mfma_f32_16x16x32_bf16 v[54:57], v[136:139], v[180:183], v[54:57]
	v_mfma_f32_16x16x32_bf16 v[50:53], v[148:151], v[180:183], v[50:53]
	v_mfma_f32_16x16x32_bf16 v[46:49], v[136:139], v[188:191], v[46:49]
	v_mfma_f32_16x16x32_bf16 v[42:45], v[148:151], v[188:191], v[42:45]
	v_mfma_f32_16x16x32_bf16 v[38:41], v[136:139], v[196:199], v[38:41]
	v_mfma_f32_16x16x32_bf16 v[34:37], v[148:151], v[196:199], v[34:37]
	v_mfma_f32_16x16x32_bf16 v[62:65], v[144:147], v[176:179], v[62:65]
	v_mfma_f32_16x16x32_bf16 v[58:61], v[152:155], v[176:179], v[58:61]
	v_mfma_f32_16x16x32_bf16 v[54:57], v[144:147], v[184:187], v[54:57]
	v_mfma_f32_16x16x32_bf16 v[50:53], v[152:155], v[184:187], v[50:53]
	v_mfma_f32_16x16x32_bf16 v[46:49], v[144:147], v[192:195], v[46:49]
	v_mfma_f32_16x16x32_bf16 v[42:45], v[152:155], v[192:195], v[42:45]
	v_mfma_f32_16x16x32_bf16 v[38:41], v[144:147], v[200:203], v[38:41]
	v_mfma_f32_16x16x32_bf16 v[34:37], v[152:155], v[200:203], v[34:37]
	v_mfma_f32_16x16x32_bf16 v[30:33], v[156:159], v[172:175], v[30:33]
	v_mfma_f32_16x16x32_bf16 v[26:29], v[164:167], v[172:175], v[26:29]
	v_mfma_f32_16x16x32_bf16 v[22:25], v[156:159], v[180:183], v[22:25]
	v_mfma_f32_16x16x32_bf16 v[18:21], v[164:167], v[180:183], v[18:21]
	v_mfma_f32_16x16x32_bf16 v[14:17], v[156:159], v[188:191], v[14:17]
	v_mfma_f32_16x16x32_bf16 v[10:13], v[164:167], v[188:191], v[10:13]
	v_mfma_f32_16x16x32_bf16 v[6:9], v[156:159], v[196:199], v[6:9]
	v_mfma_f32_16x16x32_bf16 v[2:5], v[164:167], v[196:199], v[2:5]
	v_mfma_f32_16x16x32_bf16 v[30:33], v[160:163], v[176:179], v[30:33]
	v_mfma_f32_16x16x32_bf16 v[26:29], v[168:171], v[176:179], v[26:29]
	v_mfma_f32_16x16x32_bf16 v[22:25], v[160:163], v[184:187], v[22:25]
	v_mfma_f32_16x16x32_bf16 v[18:21], v[168:171], v[184:187], v[18:21]
	v_mfma_f32_16x16x32_bf16 v[14:17], v[160:163], v[192:195], v[14:17]
	v_mfma_f32_16x16x32_bf16 v[10:13], v[168:171], v[192:195], v[10:13]
	v_mfma_f32_16x16x32_bf16 v[6:9], v[160:163], v[200:203], v[6:9]
	v_mfma_f32_16x16x32_bf16 v[2:5], v[168:171], v[200:203], v[2:5]
	s_setprio 0
	s_barrier
	v_add_u32_e32 v152, s75, v140
	v_add_u32_e32 v168, s76, v140
	ds_read_b128 v[136:139], v152
	ds_read_b128 v[144:147], v152 offset:1024
	ds_read_b128 v[148:151], v152 offset:2048
	ds_read_b128 v[152:155], v152 offset:3072
	ds_read_b128 v[156:159], v168
	ds_read_b128 v[160:163], v168 offset:1024
	ds_read_b128 v[164:167], v168 offset:2048
	ds_read_b128 v[168:171], v168 offset:3072
	s_mov_b32 m0, s51
	v_lshl_add_u64 v[212:213], s[40:41], 0, v[130:131]
	ds_read_b128 v[172:175], v143 offset:32768
	ds_read_b128 v[176:179], v143 offset:33792
	ds_read_b128 v[180:183], v143 offset:34816
	ds_read_b128 v[184:187], v143 offset:35840
	ds_read_b128 v[188:191], v143 offset:36864
	ds_read_b128 v[192:195], v143 offset:37888
	ds_read_b128 v[196:199], v143 offset:38912
	ds_read_b128 v[200:203], v143 offset:39936
	global_load_lds_dwordx4 v[212:213], off
	v_lshl_add_u64 v[212:213], s[40:41], 0, v[132:133]
	s_mov_b32 m0, s52
	s_nop 0
	global_load_lds_dwordx4 v[212:213], off
	s_waitcnt vmcnt(8)
	s_waitcnt lgkmcnt(0)
	s_barrier
	s_setprio 1
	s_waitcnt lgkmcnt(0)
	v_mfma_f32_16x16x32_bf16 v[126:129], v[136:139], v[172:175], v[126:129]
	v_mfma_f32_16x16x32_bf16 v[122:125], v[148:151], v[172:175], v[122:125]
	v_mfma_f32_16x16x32_bf16 v[118:121], v[136:139], v[180:183], v[118:121]
	v_mfma_f32_16x16x32_bf16 v[114:117], v[148:151], v[180:183], v[114:117]
	v_mfma_f32_16x16x32_bf16 v[110:113], v[136:139], v[188:191], v[110:113]
	v_mfma_f32_16x16x32_bf16 v[106:109], v[148:151], v[188:191], v[106:109]
	v_mfma_f32_16x16x32_bf16 v[102:105], v[136:139], v[196:199], v[102:105]
	v_mfma_f32_16x16x32_bf16 v[98:101], v[148:151], v[196:199], v[98:101]
	v_mfma_f32_16x16x32_bf16 v[126:129], v[144:147], v[176:179], v[126:129]
	v_mfma_f32_16x16x32_bf16 v[122:125], v[152:155], v[176:179], v[122:125]
	v_mfma_f32_16x16x32_bf16 v[118:121], v[144:147], v[184:187], v[118:121]
	v_mfma_f32_16x16x32_bf16 v[114:117], v[152:155], v[184:187], v[114:117]
	v_mfma_f32_16x16x32_bf16 v[110:113], v[144:147], v[192:195], v[110:113]
	v_mfma_f32_16x16x32_bf16 v[106:109], v[152:155], v[192:195], v[106:109]
	v_mfma_f32_16x16x32_bf16 v[102:105], v[144:147], v[200:203], v[102:105]
	v_mfma_f32_16x16x32_bf16 v[98:101], v[152:155], v[200:203], v[98:101]
	v_mfma_f32_16x16x32_bf16 v[94:97], v[156:159], v[172:175], v[94:97]
	v_mfma_f32_16x16x32_bf16 v[90:93], v[164:167], v[172:175], v[90:93]
	v_mfma_f32_16x16x32_bf16 v[86:89], v[156:159], v[180:183], v[86:89]
	v_mfma_f32_16x16x32_bf16 v[82:85], v[164:167], v[180:183], v[82:85]
	v_mfma_f32_16x16x32_bf16 v[78:81], v[156:159], v[188:191], v[78:81]
	v_mfma_f32_16x16x32_bf16 v[74:77], v[164:167], v[188:191], v[74:77]
	v_mfma_f32_16x16x32_bf16 v[70:73], v[156:159], v[196:199], v[70:73]
	v_mfma_f32_16x16x32_bf16 v[66:69], v[164:167], v[196:199], v[66:69]
	v_mfma_f32_16x16x32_bf16 v[94:97], v[160:163], v[176:179], v[94:97]
	v_mfma_f32_16x16x32_bf16 v[90:93], v[168:171], v[176:179], v[90:93]
	v_mfma_f32_16x16x32_bf16 v[86:89], v[160:163], v[184:187], v[86:89]
	v_mfma_f32_16x16x32_bf16 v[82:85], v[168:171], v[184:187], v[82:85]
	v_mfma_f32_16x16x32_bf16 v[78:81], v[160:163], v[192:195], v[78:81]
	v_mfma_f32_16x16x32_bf16 v[74:77], v[168:171], v[192:195], v[74:77]
	v_mfma_f32_16x16x32_bf16 v[70:73], v[160:163], v[200:203], v[70:73]
	v_mfma_f32_16x16x32_bf16 v[66:69], v[168:171], v[200:203], v[66:69]
	s_setprio 0
	s_barrier
; #define PG8_STAGE(bufoff, gbase, voff) do { _Pragma("unroll") for (int _i = 0; _i < 2; ++_i) \
;         __builtin_amdgcn_global_load_lds((const unsigned*)((const char*)(gbase) + (voff)[_i]), (LAS unsigned*)(lds + (bufoff) + ldsw + _i * 8192), 16, 0, 0); } while (0)
; #define PG8_LDA(dst, b, h) do { _Pragma("unroll") for (int m = 0; m < 4; ++m) _Pragma("unroll") for (int k = 0; k < 2; ++k) dst[m][k] = *(const LAS bf16x8*)(lds + PG8_SA(b, h) + aoff + m * 2048 + k * 1024); } while (0)
; #define PG8_MMA(ai, bj, At, Bt) do { __builtin_amdgcn_s_setprio(1); _Pragma("unroll") for (int m = 0; m < 4; ++m) _Pragma("unroll") for (int n = 0; n < 2; ++n) _Pragma("unroll") for (int k = 0; k < 2; ++k) \
;         acc[ai][bj][m][n] = __builtin_amdgcn_mfma_f32_16x16x32_bf16(Bt[n][k], At[m][k], acc[ai][bj][m][n], 0, 0, 0); __builtin_amdgcn_s_setprio(0); } while (0)
; #define PG8_WAIT_V(n) asm volatile("s_waitcnt vmcnt(" #n ")" ::: "memory")
; #define PG8_WAIT_L(n) asm volatile("s_waitcnt lgkmcnt(" #n ")" ::: "memory")
; #define PG8_BAR __builtin_amdgcn_s_barrier()
; #define PG8_SCHED __builtin_amdgcn_sched_barrier(0)
; template <class Epi, class Sched, bool ALIGN_EPI, bool LAST_FUSED = false, bool PERM = false, bool CARRY = false>
; __device__ __forceinline__ void gemm_phase(LAS unsigned char* lds, const int tid, const int K, const int lda, const int ldb, const Sched& S, const Epi& E) {
;     ...
;             PG8_LDA(At, 1, 1); PG8_STAGE(PG8_SB(1, 0), b3, voffB); PG8_STAGE(PG8_SB(1, 1), b3 + hstepB, voffB); PG8_STAGE(PG8_SA(1, 0), a3, voffA);
;             PG8_WAIT_V(8); PG8_WAIT_L(0); PG8_BAR; PG8_MMA(1, 0, At, B0); PG8_MMA(1, 1, At, B1); PG8_BAR; PG8_SCHED;
;         }
;         if constexpr (ALIGN_EPI) { if (wr == 0) PG8_BAR; }
	s_mov_b32 m0, s61
	v_lshl_add_u64 v[204:205], v[204:205], 0, s[68:69]
	ds_read_b128 v[172:175], v143 offset:49152
	ds_read_b128 v[176:179], v143 offset:50176
	ds_read_b128 v[180:183], v143 offset:51200
	ds_read_b128 v[184:187], v143 offset:52224
	ds_read_b128 v[188:191], v143 offset:53248
	ds_read_b128 v[192:195], v143 offset:54272
	ds_read_b128 v[196:199], v143 offset:55296
	ds_read_b128 v[200:203], v143 offset:56320
	global_load_lds_dwordx4 v[204:205], off
	v_lshl_add_u64 v[204:205], v[206:207], 0, s[68:69]
	s_mov_b32 m0, s24
	s_nop 0
	global_load_lds_dwordx4 v[204:205], off
	v_lshl_add_u64 v[204:205], s[38:39], 0, v[0:1]
	s_mov_b32 m0, s63
	s_nop 0
	global_load_lds_dwordx4 v[204:205], off
	v_lshl_add_u64 v[204:205], s[38:39], 0, v[134:135]
	s_mov_b32 m0, s62
	s_nop 0
	global_load_lds_dwordx4 v[204:205], off
	v_lshl_add_u64 v[204:205], v[208:209], 0, s[68:69]
	s_mov_b32 m0, s55
	s_nop 0
	global_load_lds_dwordx4 v[204:205], off
	v_lshl_add_u64 v[204:205], v[210:211], 0, s[68:69]
	s_mov_b32 m0, s56
	s_nop 0
	global_load_lds_dwordx4 v[204:205], off
	s_waitcnt vmcnt(8)
	s_waitcnt lgkmcnt(0)
	s_barrier
	s_setprio 1
	s_waitcnt lgkmcnt(0)
	v_mfma_f32_16x16x32_bf16 v[62:65], v[136:139], v[172:175], v[62:65]
	v_mfma_f32_16x16x32_bf16 v[58:61], v[148:151], v[172:175], v[58:61]
	v_mfma_f32_16x16x32_bf16 v[54:57], v[136:139], v[180:183], v[54:57]
	v_mfma_f32_16x16x32_bf16 v[50:53], v[148:151], v[180:183], v[50:53]
	v_mfma_f32_16x16x32_bf16 v[46:49], v[136:139], v[188:191], v[46:49]
	v_mfma_f32_16x16x32_bf16 v[42:45], v[148:151], v[188:191], v[42:45]
	v_mfma_f32_16x16x32_bf16 v[38:41], v[136:139], v[196:199], v[38:41]
	v_mfma_f32_16x16x32_bf16 v[34:37], v[148:151], v[196:199], v[34:37]
	v_mfma_f32_16x16x32_bf16 v[62:65], v[144:147], v[176:179], v[62:65]
	v_mfma_f32_16x16x32_bf16 v[58:61], v[152:155], v[176:179], v[58:61]
	v_mfma_f32_16x16x32_bf16 v[54:57], v[144:147], v[184:187], v[54:57]
	v_mfma_f32_16x16x32_bf16 v[50:53], v[152:155], v[184:187], v[50:53]
	v_mfma_f32_16x16x32_bf16 v[46:49], v[144:147], v[192:195], v[46:49]
	v_mfma_f32_16x16x32_bf16 v[42:45], v[152:155], v[192:195], v[42:45]
	v_mfma_f32_16x16x32_bf16 v[38:41], v[144:147], v[200:203], v[38:41]
	v_mfma_f32_16x16x32_bf16 v[34:37], v[152:155], v[200:203], v[34:37]
	v_mfma_f32_16x16x32_bf16 v[30:33], v[156:159], v[172:175], v[30:33]
	v_mfma_f32_16x16x32_bf16 v[26:29], v[164:167], v[172:175], v[26:29]
	v_mfma_f32_16x16x32_bf16 v[22:25], v[156:159], v[180:183], v[22:25]
	v_mfma_f32_16x16x32_bf16 v[18:21], v[164:167], v[180:183], v[18:21]
	v_mfma_f32_16x16x32_bf16 v[14:17], v[156:159], v[188:191], v[14:17]
	v_mfma_f32_16x16x32_bf16 v[10:13], v[164:167], v[188:191], v[10:13]
	v_mfma_f32_16x16x32_bf16 v[6:9], v[156:159], v[196:199], v[6:9]
	v_mfma_f32_16x16x32_bf16 v[2:5], v[164:167], v[196:199], v[2:5]
	v_mfma_f32_16x16x32_bf16 v[30:33], v[160:163], v[176:179], v[30:33]
	v_mfma_f32_16x16x32_bf16 v[26:29], v[168:171], v[176:179], v[26:29]
	v_mfma_f32_16x16x32_bf16 v[22:25], v[160:163], v[184:187], v[22:25]
	v_mfma_f32_16x16x32_bf16 v[18:21], v[168:171], v[184:187], v[18:21]
	v_mfma_f32_16x16x32_bf16 v[14:17], v[160:163], v[192:195], v[14:17]
	v_mfma_f32_16x16x32_bf16 v[10:13], v[168:171], v[192:195], v[10:13]
	v_mfma_f32_16x16x32_bf16 v[6:9], v[160:163], v[200:203], v[6:9]
	v_mfma_f32_16x16x32_bf16 v[2:5], v[168:171], v[200:203], v[2:5]
	s_setprio 0
	s_barrier
	s_movk_i32 s24, 0x100
	s_andn2_b64 vcc, exec, s[36:37]
	s_mov_b64 s[38:39], -1
	s_mov_b64 s[36:37], 0
	s_cbranch_vccz .LBB0_622
	s_and_b64 vcc, exec, s[10:11]
	s_cbranch_vccz .LBB0_625
	s_barrier

; #define PG8_STAGE(bufoff, gbase, voff) do { _Pragma("unroll") for (int _i = 0; _i < 2; ++_i) \
;         __builtin_amdgcn_global_load_lds((const unsigned*)((const char*)(gbase) + (voff)[_i]), (LAS unsigned*)(lds + (bufoff) + ldsw + _i * 8192), 16, 0, 0); } while (0)
; #define PG8_LDA(dst, b, h) do { _Pragma("unroll") for (int m = 0; m < 4; ++m) _Pragma("unroll") for (int k = 0; k < 2; ++k) dst[m][k] = *(const LAS bf16x8*)(lds + PG8_SA(b, h) + aoff + m * 2048 + k * 1024); } while (0)
; #define PG8_LDB(dst, b, h) do { _Pragma("unroll") for (int n = 0; n < 2; ++n) _Pragma("unroll") for (int k = 0; k < 2; ++k) dst[n][k] = *(const LAS bf16x8*)(lds + PG8_SB(b, h) + boff + n * 2048 + k * 1024); } while (0)
; #define PG8_MMA(ai, bj, At, Bt) do { __builtin_amdgcn_s_setprio(1); _Pragma("unroll") for (int m = 0; m < 4; ++m) _Pragma("unroll") for (int n = 0; n < 2; ++n) _Pragma("unroll") for (int k = 0; k < 2; ++k) \
;         acc[ai][bj][m][n] = __builtin_amdgcn_mfma_f32_16x16x32_bf16(Bt[n][k], At[m][k], acc[ai][bj][m][n], 0, 0, 0); __builtin_amdgcn_s_setprio(0); } while (0)
; #define PG8_WAIT_V(n) asm volatile("s_waitcnt vmcnt(" #n ")" ::: "memory")
; #define PG8_WAIT_L(n) asm volatile("s_waitcnt lgkmcnt(" #n ")" ::: "memory")
; template <class Epi, class Sched, bool ALIGN_EPI, bool LAST_FUSED = false, bool PERM = false, bool CARRY = false>
; __device__ __forceinline__ void gemm_phase(LAS unsigned char* lds, const int tid, const int K, const int lda, const int ldb, const Sched& S, const Epi& E) {
;     ...
;         for (int t = 0; t < nt; t += 2) {
;             const bool last = (t == nt - 2);
;             const char* a1 = cA + (size_t)(t + 1) * kstep;
;             const char* a2 = last ? nA : cA + (size_t)(t + 2) * kstep; const char* b2 = last ? nB : cB + (size_t)(t + 2) * kstep;
;             const char* a3 = a2 + kstep; const char* b3 = b2 + kstep;
;             PG8_LDB(B0, 0, 0); PG8_LDB(B1, 0, 1); PG8_SCHED; PG8_LDA(At, 0, 0); PG8_STAGE(PG8_SA(1, 1), a1 + hstepA, voffA);
;             PG8_WAIT_V(8); PG8_WAIT_L(0); PG8_BAR; PG8_MMA(0, 0, At, B0); PG8_MMA(0, 1, At, B1); PG8_BAR; PG8_SCHED;
;             PG8_LDA(At, 0, 1); PG8_STAGE(PG8_SB(0, 0), b2, voffB); PG8_STAGE(PG8_SB(0, 1), b2 + hstepB, voffB); PG8_STAGE(PG8_SA(0, 0), a2, voffA);
;             PG8_WAIT_V(8); PG8_WAIT_L(0); PG8_BAR; PG8_MMA(1, 0, At, B0); PG8_MMA(1, 1, At, B1); PG8_BAR; PG8_SCHED;
.LBB0_705:
	s_add_u32 s30, s26, 0x100
	s_addc_u32 s31, s27, 0
	s_add_i32 s54, 0, 0x10000
	s_cmp_eq_u32 s53, 8
	s_cselect_b32 s39, s15, s31
	s_cselect_b32 s38, s14, s30
	v_add_u32_e32 v140, s54, v144
	s_cselect_b32 s37, s17, s52
	s_cselect_b32 s36, s16, s13
	s_add_i32 s55, 0, 0x14000
	ds_read_b128 v[146:149], v140
	ds_read_b128 v[150:153], v140 offset:1024
	ds_read_b128 v[154:157], v140 offset:2048
	ds_read_b128 v[158:161], v140 offset:3072
	v_add_u32_e32 v140, s55, v144
	ds_read_b128 v[162:165], v140
	ds_read_b128 v[166:169], v140 offset:1024
	ds_read_b128 v[170:173], v140 offset:2048
	ds_read_b128 v[174:177], v140 offset:3072
	v_lshl_add_u64 v[140:141], s[26:27], 0, v[136:137]
	s_add_i32 m0, s19, 0xc000
	ds_read_b128 v[178:181], v145
	ds_read_b128 v[182:185], v145 offset:1024
	ds_read_b128 v[186:189], v145 offset:2048
	ds_read_b128 v[190:193], v145 offset:3072
	ds_read_b128 v[194:197], v145 offset:4096
	ds_read_b128 v[198:201], v145 offset:5120
	ds_read_b128 v[202:205], v145 offset:6144
	ds_read_b128 v[206:209], v145 offset:7168
	global_load_lds_dwordx4 v[140:141], off
	v_lshl_add_u64 v[140:141], s[26:27], 0, v[138:139]
	s_add_i32 m0, s19, 0xe000
	s_nop 0
	global_load_lds_dwordx4 v[140:141], off
	s_waitcnt vmcnt(8)
	s_waitcnt lgkmcnt(0)
	s_barrier
	s_setprio 1
	s_waitcnt lgkmcnt(0)
	v_mfma_f32_16x16x32_bf16 v[126:129], v[146:149], v[178:181], v[126:129]
	v_mfma_f32_16x16x32_bf16 v[122:125], v[154:157], v[178:181], v[122:125]
	v_mfma_f32_16x16x32_bf16 v[118:121], v[146:149], v[186:189], v[118:121]
	v_mfma_f32_16x16x32_bf16 v[110:113], v[154:157], v[186:189], v[110:113]
	v_mfma_f32_16x16x32_bf16 v[102:105], v[146:149], v[194:197], v[102:105]
	v_mfma_f32_16x16x32_bf16 v[94:97], v[154:157], v[194:197], v[94:97]
	v_mfma_f32_16x16x32_bf16 v[86:89], v[146:149], v[202:205], v[86:89]
	v_mfma_f32_16x16x32_bf16 v[78:81], v[154:157], v[202:205], v[78:81]
	v_mfma_f32_16x16x32_bf16 v[126:129], v[150:153], v[182:185], v[126:129]
	v_mfma_f32_16x16x32_bf16 v[122:125], v[158:161], v[182:185], v[122:125]
	v_mfma_f32_16x16x32_bf16 v[118:121], v[150:153], v[190:193], v[118:121]
	v_mfma_f32_16x16x32_bf16 v[110:113], v[158:161], v[190:193], v[110:113]
	v_mfma_f32_16x16x32_bf16 v[102:105], v[150:153], v[198:201], v[102:105]
	v_mfma_f32_16x16x32_bf16 v[94:97], v[158:161], v[198:201], v[94:97]
	v_mfma_f32_16x16x32_bf16 v[86:89], v[150:153], v[206:209], v[86:89]
	v_mfma_f32_16x16x32_bf16 v[78:81], v[158:161], v[206:209], v[78:81]
	v_mfma_f32_16x16x32_bf16 v[114:117], v[162:165], v[178:181], v[114:117]
	v_mfma_f32_16x16x32_bf16 v[106:109], v[170:173], v[178:181], v[106:109]
	v_mfma_f32_16x16x32_bf16 v[98:101], v[162:165], v[186:189], v[98:101]
	v_mfma_f32_16x16x32_bf16 v[90:93], v[170:173], v[186:189], v[90:93]
	v_mfma_f32_16x16x32_bf16 v[82:85], v[162:165], v[194:197], v[82:85]
	v_mfma_f32_16x16x32_bf16 v[74:77], v[170:173], v[194:197], v[74:77]
	v_mfma_f32_16x16x32_bf16 v[70:73], v[162:165], v[202:205], v[70:73]
	v_mfma_f32_16x16x32_bf16 v[66:69], v[170:173], v[202:205], v[66:69]
	v_mfma_f32_16x16x32_bf16 v[114:117], v[166:169], v[182:185], v[114:117]
	v_mfma_f32_16x16x32_bf16 v[106:109], v[174:177], v[182:185], v[106:109]
	v_mfma_f32_16x16x32_bf16 v[98:101], v[166:169], v[190:193], v[98:101]
	v_mfma_f32_16x16x32_bf16 v[90:93], v[174:177], v[190:193], v[90:93]
	v_mfma_f32_16x16x32_bf16 v[82:85], v[166:169], v[198:201], v[82:85]
	v_mfma_f32_16x16x32_bf16 v[74:77], v[174:177], v[198:201], v[74:77]
	v_mfma_f32_16x16x32_bf16 v[70:73], v[166:169], v[206:209], v[70:73]
	v_mfma_f32_16x16x32_bf16 v[66:69], v[174:177], v[206:209], v[66:69]
	s_setprio 0
	s_barrier
	s_add_i32 s26, s54, s40
	v_lshl_add_u64 v[140:141], s[36:37], 0, v[0:1]
	s_mov_b32 m0, s26
	ds_read_b128 v[178:181], v145 offset:16384
	ds_read_b128 v[182:185], v145 offset:17408
	ds_read_b128 v[186:189], v145 offset:18432
	ds_read_b128 v[190:193], v145 offset:19456
	ds_read_b128 v[194:197], v145 offset:20480
	ds_read_b128 v[198:201], v145 offset:21504
	ds_read_b128 v[202:205], v145 offset:22528
	ds_read_b128 v[206:209], v145 offset:23552
	global_load_lds_dwordx4 v[140:141], off
	s_add_i32 m0, s26, 0x2000
	s_add_u32 s26, s36, 0x30000
	v_lshl_add_u64 v[210:211], s[36:37], 0, v[130:131]
	s_addc_u32 s27, s37, 0
	s_add_i32 s54, s55, s40
	global_load_lds_dwordx4 v[210:211], off
	v_lshl_add_u64 v[212:213], s[26:27], 0, v[0:1]
	s_mov_b32 m0, s54
	v_lshl_add_u64 v[214:215], s[38:39], 0, v[132:133]
	global_load_lds_dwordx4 v[212:213], off
	v_lshl_add_u64 v[212:213], s[26:27], 0, v[130:131]
	s_add_i32 m0, s54, 0x2000
	s_nop 0
	global_load_lds_dwordx4 v[212:213], off
	v_lshl_add_u64 v[212:213], s[38:39], 0, v[134:135]
	s_mov_b32 m0, s19
	s_nop 0
	global_load_lds_dwordx4 v[212:213], off
	s_mov_b32 m0, s42
	s_nop 0
	global_load_lds_dwordx4 v[214:215], off
	s_waitcnt vmcnt(8)
	s_waitcnt lgkmcnt(0)
	s_barrier
; #define PG8_STAGE(bufoff, gbase, voff) do { _Pragma("unroll") for (int _i = 0; _i < 2; ++_i) \
;         __builtin_amdgcn_global_load_lds((const unsigned*)((const char*)(gbase) + (voff)[_i]), (LAS unsigned*)(lds + (bufoff) + ldsw + _i * 8192), 16, 0, 0); } while (0)
; #define PG8_LDA(dst, b, h) do { _Pragma("unroll") for (int m = 0; m < 4; ++m) _Pragma("unroll") for (int k = 0; k < 2; ++k) dst[m][k] = *(const LAS bf16x8*)(lds + PG8_SA(b, h) + aoff + m * 2048 + k * 1024); } while (0)
; #define PG8_LDB(dst, b, h) do { _Pragma("unroll") for (int n = 0; n < 2; ++n) _Pragma("unroll") for (int k = 0; k < 2; ++k) dst[n][k] = *(const LAS bf16x8*)(lds + PG8_SB(b, h) + boff + n * 2048 + k * 1024); } while (0)
; #define PG8_MMA(ai, bj, At, Bt) do { __builtin_amdgcn_s_setprio(1); _Pragma("unroll") for (int m = 0; m < 4; ++m) _Pragma("unroll") for (int n = 0; n < 2; ++n) _Pragma("unroll") for (int k = 0; k < 2; ++k) \
;         acc[ai][bj][m][n] = __builtin_amdgcn_mfma_f32_16x16x32_bf16(Bt[n][k], At[m][k], acc[ai][bj][m][n], 0, 0, 0); __builtin_amdgcn_s_setprio(0); } while (0)
; #define PG8_WAIT_V(n) asm volatile("s_waitcnt vmcnt(" #n ")" ::: "memory")
; #define PG8_WAIT_L(n) asm volatile("s_waitcnt lgkmcnt(" #n ")" ::: "memory")
; #define PG8_BAR __builtin_amdgcn_s_barrier()
; #define PG8_SCHED __builtin_amdgcn_sched_barrier(0)
; template <class Epi, class Sched, bool ALIGN_EPI, bool LAST_FUSED = false, bool PERM = false, bool CARRY = false>
; __device__ __forceinline__ void gemm_phase(LAS unsigned char* lds, const int tid, const int K, const int lda, const int ldb, const Sched& S, const Epi& E) {
;     ...
;             PG8_WAIT_V(8); PG8_WAIT_L(0); PG8_BAR; PG8_MMA(1, 0, At, B0); PG8_MMA(1, 1, At, B1); PG8_BAR; PG8_SCHED;
;             PG8_LDB(B0, 1, 0); PG8_LDB(B1, 1, 1); PG8_SCHED; PG8_LDA(At, 1, 0); PG8_STAGE(PG8_SA(0, 1), a2 + hstepA, voffA);
;             PG8_WAIT_V(8); PG8_WAIT_L(0); PG8_BAR; PG8_MMA(0, 0, At, B0); PG8_MMA(0, 1, At, B1); PG8_BAR; PG8_SCHED;
	s_setprio 1
	s_waitcnt lgkmcnt(0)
	v_mfma_f32_16x16x32_bf16 v[62:65], v[146:149], v[178:181], v[62:65]
	v_mfma_f32_16x16x32_bf16 v[58:61], v[154:157], v[178:181], v[58:61]
	v_mfma_f32_16x16x32_bf16 v[54:57], v[146:149], v[186:189], v[54:57]
	v_mfma_f32_16x16x32_bf16 v[46:49], v[154:157], v[186:189], v[46:49]
	v_mfma_f32_16x16x32_bf16 v[38:41], v[146:149], v[194:197], v[38:41]
	v_mfma_f32_16x16x32_bf16 v[30:33], v[154:157], v[194:197], v[30:33]
	v_mfma_f32_16x16x32_bf16 v[22:25], v[146:149], v[202:205], v[22:25]
	v_mfma_f32_16x16x32_bf16 v[14:17], v[154:157], v[202:205], v[14:17]
	v_mfma_f32_16x16x32_bf16 v[62:65], v[150:153], v[182:185], v[62:65]
	v_mfma_f32_16x16x32_bf16 v[58:61], v[158:161], v[182:185], v[58:61]
	v_mfma_f32_16x16x32_bf16 v[54:57], v[150:153], v[190:193], v[54:57]
	v_mfma_f32_16x16x32_bf16 v[46:49], v[158:161], v[190:193], v[46:49]
	v_mfma_f32_16x16x32_bf16 v[38:41], v[150:153], v[198:201], v[38:41]
	v_mfma_f32_16x16x32_bf16 v[30:33], v[158:161], v[198:201], v[30:33]
	v_mfma_f32_16x16x32_bf16 v[22:25], v[150:153], v[206:209], v[22:25]
	v_mfma_f32_16x16x32_bf16 v[14:17], v[158:161], v[206:209], v[14:17]
	v_mfma_f32_16x16x32_bf16 v[50:53], v[162:165], v[178:181], v[50:53]
	v_mfma_f32_16x16x32_bf16 v[42:45], v[170:173], v[178:181], v[42:45]
	v_mfma_f32_16x16x32_bf16 v[34:37], v[162:165], v[186:189], v[34:37]
	v_mfma_f32_16x16x32_bf16 v[26:29], v[170:173], v[186:189], v[26:29]
	v_mfma_f32_16x16x32_bf16 v[18:21], v[162:165], v[194:197], v[18:21]
	v_mfma_f32_16x16x32_bf16 v[10:13], v[170:173], v[194:197], v[10:13]
	v_mfma_f32_16x16x32_bf16 v[6:9], v[162:165], v[202:205], v[6:9]
	v_mfma_f32_16x16x32_bf16 v[2:5], v[170:173], v[202:205], v[2:5]
	v_mfma_f32_16x16x32_bf16 v[50:53], v[166:169], v[182:185], v[50:53]
	v_mfma_f32_16x16x32_bf16 v[42:45], v[174:177], v[182:185], v[42:45]
	v_mfma_f32_16x16x32_bf16 v[34:37], v[166:169], v[190:193], v[34:37]
	v_mfma_f32_16x16x32_bf16 v[26:29], v[174:177], v[190:193], v[26:29]
	v_mfma_f32_16x16x32_bf16 v[18:21], v[166:169], v[198:201], v[18:21]
	v_mfma_f32_16x16x32_bf16 v[10:13], v[174:177], v[198:201], v[10:13]
	v_mfma_f32_16x16x32_bf16 v[6:9], v[166:169], v[206:209], v[6:9]
	v_mfma_f32_16x16x32_bf16 v[2:5], v[174:177], v[206:209], v[2:5]
	s_setprio 0
	s_barrier
	s_add_i32 s54, 0, 0x18000
	s_add_i32 s55, 0, 0x1c000
	v_add_u32_e32 v158, s54, v144
	v_add_u32_e32 v174, s55, v144
	ds_read_b128 v[146:149], v158
	ds_read_b128 v[150:153], v158 offset:1024
	ds_read_b128 v[154:157], v158 offset:2048
	ds_read_b128 v[158:161], v158 offset:3072
	ds_read_b128 v[162:165], v174
	ds_read_b128 v[166:169], v174 offset:1024
	ds_read_b128 v[170:173], v174 offset:2048
	ds_read_b128 v[174:177], v174 offset:3072
	s_add_u32 s26, s38, 0x180000
	s_addc_u32 s27, s39, 0
	s_mov_b32 m0, s43
	v_lshl_add_u64 v[216:217], s[26:27], 0, v[134:135]
	ds_read_b128 v[178:181], v145 offset:32768
	ds_read_b128 v[182:185], v145 offset:33792
	ds_read_b128 v[186:189], v145 offset:34816
	ds_read_b128 v[190:193], v145 offset:35840
	ds_read_b128 v[194:197], v145 offset:36864
	ds_read_b128 v[198:201], v145 offset:37888
	ds_read_b128 v[202:205], v145 offset:38912
	ds_read_b128 v[206:209], v145 offset:39936
	global_load_lds_dwordx4 v[216:217], off
	v_lshl_add_u64 v[216:217], s[26:27], 0, v[132:133]
	s_mov_b32 m0, s44
	s_nop 0
	global_load_lds_dwordx4 v[216:217], off
	s_waitcnt vmcnt(8)
	s_waitcnt lgkmcnt(0)
	s_barrier
	s_setprio 1
	s_waitcnt lgkmcnt(0)
	v_mfma_f32_16x16x32_bf16 v[126:129], v[146:149], v[178:181], v[126:129]
	v_mfma_f32_16x16x32_bf16 v[122:125], v[154:157], v[178:181], v[122:125]
	v_mfma_f32_16x16x32_bf16 v[118:121], v[146:149], v[186:189], v[118:121]
	v_mfma_f32_16x16x32_bf16 v[110:113], v[154:157], v[186:189], v[110:113]
	v_mfma_f32_16x16x32_bf16 v[102:105], v[146:149], v[194:197], v[102:105]
	v_mfma_f32_16x16x32_bf16 v[94:97], v[154:157], v[194:197], v[94:97]
	v_mfma_f32_16x16x32_bf16 v[86:89], v[146:149], v[202:205], v[86:89]
	v_mfma_f32_16x16x32_bf16 v[78:81], v[154:157], v[202:205], v[78:81]
	v_mfma_f32_16x16x32_bf16 v[126:129], v[150:153], v[182:185], v[126:129]
	v_mfma_f32_16x16x32_bf16 v[122:125], v[158:161], v[182:185], v[122:125]
	v_mfma_f32_16x16x32_bf16 v[118:121], v[150:153], v[190:193], v[118:121]
	v_mfma_f32_16x16x32_bf16 v[110:113], v[158:161], v[190:193], v[110:113]
	v_mfma_f32_16x16x32_bf16 v[102:105], v[150:153], v[198:201], v[102:105]
	v_mfma_f32_16x16x32_bf16 v[94:97], v[158:161], v[198:201], v[94:97]
	v_mfma_f32_16x16x32_bf16 v[86:89], v[150:153], v[206:209], v[86:89]
	v_mfma_f32_16x16x32_bf16 v[78:81], v[158:161], v[206:209], v[78:81]
	v_mfma_f32_16x16x32_bf16 v[114:117], v[162:165], v[178:181], v[114:117]
	v_mfma_f32_16x16x32_bf16 v[106:109], v[170:173], v[178:181], v[106:109]
	v_mfma_f32_16x16x32_bf16 v[98:101], v[162:165], v[186:189], v[98:101]
	v_mfma_f32_16x16x32_bf16 v[90:93], v[170:173], v[186:189], v[90:93]
	v_mfma_f32_16x16x32_bf16 v[82:85], v[162:165], v[194:197], v[82:85]
	v_mfma_f32_16x16x32_bf16 v[74:77], v[170:173], v[194:197], v[74:77]
	v_mfma_f32_16x16x32_bf16 v[70:73], v[162:165], v[202:205], v[70:73]
	v_mfma_f32_16x16x32_bf16 v[66:69], v[170:173], v[202:205], v[66:69]
	v_mfma_f32_16x16x32_bf16 v[114:117], v[166:169], v[182:185], v[114:117]
	v_mfma_f32_16x16x32_bf16 v[106:109], v[174:177], v[182:185], v[106:109]
	v_mfma_f32_16x16x32_bf16 v[98:101], v[166:169], v[190:193], v[98:101]
	v_mfma_f32_16x16x32_bf16 v[90:93], v[174:177], v[190:193], v[90:93]
	v_mfma_f32_16x16x32_bf16 v[82:85], v[166:169], v[198:201], v[82:85]
	v_mfma_f32_16x16x32_bf16 v[74:77], v[174:177], v[198:201], v[74:77]
	v_mfma_f32_16x16x32_bf16 v[70:73], v[166:169], v[206:209], v[70:73]
	v_mfma_f32_16x16x32_bf16 v[66:69], v[174:177], v[206:209], v[66:69]
	s_setprio 0
	s_barrier
; #define PG8_STAGE(bufoff, gbase, voff) do { _Pragma("unroll") for (int _i = 0; _i < 2; ++_i) \
;         __builtin_amdgcn_global_load_lds((const unsigned*)((const char*)(gbase) + (voff)[_i]), (LAS unsigned*)(lds + (bufoff) + ldsw + _i * 8192), 16, 0, 0); } while (0)
; #define PG8_LDA(dst, b, h) do { _Pragma("unroll") for (int m = 0; m < 4; ++m) _Pragma("unroll") for (int k = 0; k < 2; ++k) dst[m][k] = *(const LAS bf16x8*)(lds + PG8_SA(b, h) + aoff + m * 2048 + k * 1024); } while (0)
; #define PG8_MMA(ai, bj, At, Bt) do { __builtin_amdgcn_s_setprio(1); _Pragma("unroll") for (int m = 0; m < 4; ++m) _Pragma("unroll") for (int n = 0; n < 2; ++n) _Pragma("unroll") for (int k = 0; k < 2; ++k) \
;         acc[ai][bj][m][n] = __builtin_amdgcn_mfma_f32_16x16x32_bf16(Bt[n][k], At[m][k], acc[ai][bj][m][n], 0, 0, 0); __builtin_amdgcn_s_setprio(0); } while (0)
; #define PG8_WAIT_V(n) asm volatile("s_waitcnt vmcnt(" #n ")" ::: "memory")
; #define PG8_WAIT_L(n) asm volatile("s_waitcnt lgkmcnt(" #n ")" ::: "memory")
; #define PG8_BAR __builtin_amdgcn_s_barrier()
; #define PG8_SCHED __builtin_amdgcn_sched_barrier(0)
; template <class Epi, class Sched, bool ALIGN_EPI, bool LAST_FUSED = false, bool PERM = false, bool CARRY = false>
; __device__ __forceinline__ void gemm_phase(LAS unsigned char* lds, const int tid, const int K, const int lda, const int ldb, const Sched& S, const Epi& E) {
;     ...
;             PG8_LDA(At, 1, 1); PG8_STAGE(PG8_SB(1, 0), b3, voffB); PG8_STAGE(PG8_SB(1, 1), b3 + hstepB, voffB); PG8_STAGE(PG8_SA(1, 0), a3, voffA);
;             PG8_WAIT_V(8); PG8_WAIT_L(0); PG8_BAR; PG8_MMA(1, 0, At, B0); PG8_MMA(1, 1, At, B1); PG8_BAR; PG8_SCHED;
;         }
;         if constexpr (ALIGN_EPI) { if (wr == 0) PG8_BAR; }
	s_add_i32 s26, s54, s40
	v_lshl_add_u64 v[140:141], v[140:141], 0, s[68:69]
	s_mov_b32 m0, s26
	ds_read_b128 v[178:181], v145 offset:49152
	ds_read_b128 v[182:185], v145 offset:50176
	ds_read_b128 v[186:189], v145 offset:51200
	ds_read_b128 v[190:193], v145 offset:52224
	ds_read_b128 v[194:197], v145 offset:53248
	ds_read_b128 v[198:201], v145 offset:54272
	ds_read_b128 v[202:205], v145 offset:55296
	ds_read_b128 v[206:209], v145 offset:56320
	global_load_lds_dwordx4 v[140:141], off
	s_add_i32 m0, s26, 0x2000
	s_add_u32 s26, s36, 0x30080
	v_lshl_add_u64 v[140:141], v[210:211], 0, s[68:69]
	s_addc_u32 s27, s37, 0
	s_add_i32 s36, s55, s40
	global_load_lds_dwordx4 v[140:141], off
	v_lshl_add_u64 v[140:141], s[26:27], 0, v[0:1]
	s_mov_b32 m0, s36
	s_nop 0
	global_load_lds_dwordx4 v[140:141], off
	v_lshl_add_u64 v[140:141], s[26:27], 0, v[130:131]
	s_add_i32 m0, s36, 0x2000
	s_nop 0
	global_load_lds_dwordx4 v[140:141], off
	v_lshl_add_u64 v[140:141], v[212:213], 0, s[68:69]
	s_mov_b32 m0, s46
	s_nop 0
	global_load_lds_dwordx4 v[140:141], off
	v_lshl_add_u64 v[140:141], v[214:215], 0, s[68:69]
	s_mov_b32 m0, s47
	s_nop 0
	global_load_lds_dwordx4 v[140:141], off
	s_waitcnt vmcnt(8)
	s_waitcnt lgkmcnt(0)
	s_barrier
	s_setprio 1
	s_waitcnt lgkmcnt(0)
	v_mfma_f32_16x16x32_bf16 v[62:65], v[146:149], v[178:181], v[62:65]
	v_mfma_f32_16x16x32_bf16 v[58:61], v[154:157], v[178:181], v[58:61]
	v_mfma_f32_16x16x32_bf16 v[54:57], v[146:149], v[186:189], v[54:57]
	v_mfma_f32_16x16x32_bf16 v[46:49], v[154:157], v[186:189], v[46:49]
	v_mfma_f32_16x16x32_bf16 v[38:41], v[146:149], v[194:197], v[38:41]
	v_mfma_f32_16x16x32_bf16 v[30:33], v[154:157], v[194:197], v[30:33]
	v_mfma_f32_16x16x32_bf16 v[22:25], v[146:149], v[202:205], v[22:25]
	v_mfma_f32_16x16x32_bf16 v[14:17], v[154:157], v[202:205], v[14:17]
	v_mfma_f32_16x16x32_bf16 v[62:65], v[150:153], v[182:185], v[62:65]
	v_mfma_f32_16x16x32_bf16 v[58:61], v[158:161], v[182:185], v[58:61]
	v_mfma_f32_16x16x32_bf16 v[54:57], v[150:153], v[190:193], v[54:57]
	v_mfma_f32_16x16x32_bf16 v[46:49], v[158:161], v[190:193], v[46:49]
	v_mfma_f32_16x16x32_bf16 v[38:41], v[150:153], v[198:201], v[38:41]
	v_mfma_f32_16x16x32_bf16 v[30:33], v[158:161], v[198:201], v[30:33]
	v_mfma_f32_16x16x32_bf16 v[22:25], v[150:153], v[206:209], v[22:25]
	v_mfma_f32_16x16x32_bf16 v[14:17], v[158:161], v[206:209], v[14:17]
	v_mfma_f32_16x16x32_bf16 v[50:53], v[162:165], v[178:181], v[50:53]
	v_mfma_f32_16x16x32_bf16 v[42:45], v[170:173], v[178:181], v[42:45]
	v_mfma_f32_16x16x32_bf16 v[34:37], v[162:165], v[186:189], v[34:37]
	v_mfma_f32_16x16x32_bf16 v[26:29], v[170:173], v[186:189], v[26:29]
	v_mfma_f32_16x16x32_bf16 v[18:21], v[162:165], v[194:197], v[18:21]
	v_mfma_f32_16x16x32_bf16 v[10:13], v[170:173], v[194:197], v[10:13]
	v_mfma_f32_16x16x32_bf16 v[6:9], v[162:165], v[202:205], v[6:9]
	v_mfma_f32_16x16x32_bf16 v[2:5], v[170:173], v[202:205], v[2:5]
	v_mfma_f32_16x16x32_bf16 v[50:53], v[166:169], v[182:185], v[50:53]
	v_mfma_f32_16x16x32_bf16 v[42:45], v[174:177], v[182:185], v[42:45]
	v_mfma_f32_16x16x32_bf16 v[34:37], v[166:169], v[190:193], v[34:37]
	v_mfma_f32_16x16x32_bf16 v[26:29], v[174:177], v[190:193], v[26:29]
	v_mfma_f32_16x16x32_bf16 v[18:21], v[166:169], v[198:201], v[18:21]
	v_mfma_f32_16x16x32_bf16 v[10:13], v[174:177], v[198:201], v[10:13]
	v_mfma_f32_16x16x32_bf16 v[6:9], v[166:169], v[206:209], v[6:9]
	v_mfma_f32_16x16x32_bf16 v[2:5], v[174:177], v[206:209], v[2:5]
	s_setprio 0
	s_barrier
	s_add_i32 s53, s53, 2
	s_add_u32 s13, s13, 0x100
	s_addc_u32 s52, s52, 0
	s_cmp_gt_u32 s53, 9
	s_mov_b64 s[26:27], s[30:31]
	s_cbranch_scc0 .LBB0_705
	s_and_b64 vcc, exec, s[10:11]
	s_cbranch_vccz .LBB0_708
	s_barrier

; #define PG8_STAGE(bufoff, gbase, voff) do { _Pragma("unroll") for (int _i = 0; _i < 2; ++_i) \
;         __builtin_amdgcn_global_load_lds((const unsigned*)((const char*)(gbase) + (voff)[_i]), (LAS unsigned*)(lds + (bufoff) + ldsw + _i * 8192), 16, 0, 0); } while (0)
; #define PG8_LDA(dst, b, h) do { _Pragma("unroll") for (int m = 0; m < 4; ++m) _Pragma("unroll") for (int k = 0; k < 2; ++k) dst[m][k] = *(const LAS bf16x8*)(lds + PG8_SA(b, h) + aoff + m * 2048 + k * 1024); } while (0)
; #define PG8_LDB(dst, b, h) do { _Pragma("unroll") for (int n = 0; n < 2; ++n) _Pragma("unroll") for (int k = 0; k < 2; ++k) dst[n][k] = *(const LAS bf16x8*)(lds + PG8_SB(b, h) + boff + n * 2048 + k * 1024); } while (0)
; #define PG8_MMA(ai, bj, At, Bt) do { __builtin_amdgcn_s_setprio(1); _Pragma("unroll") for (int m = 0; m < 4; ++m) _Pragma("unroll") for (int n = 0; n < 2; ++n) _Pragma("unroll") for (int k = 0; k < 2; ++k) \
;         acc[ai][bj][m][n] = __builtin_amdgcn_mfma_f32_16x16x32_bf16(Bt[n][k], At[m][k], acc[ai][bj][m][n], 0, 0, 0); __builtin_amdgcn_s_setprio(0); } while (0)
; #define PG8_WAIT_V(n) asm volatile("s_waitcnt vmcnt(" #n ")" ::: "memory")
; #define PG8_WAIT_L(n) asm volatile("s_waitcnt lgkmcnt(" #n ")" ::: "memory")
; template <class Epi, class Sched, bool ALIGN_EPI, bool LAST_FUSED = false, bool PERM = false, bool CARRY = false>
; __device__ __forceinline__ void gemm_phase(LAS unsigned char* lds, const int tid, const int K, const int lda, const int ldb, const Sched& S, const Epi& E) {
;     ...
;         for (int t = 0; t < nt; t += 2) {
;             const bool last = (t == nt - 2);
;             const char* a1 = cA + (size_t)(t + 1) * kstep;
;             const char* a2 = last ? nA : cA + (size_t)(t + 2) * kstep; const char* b2 = last ? nB : cB + (size_t)(t + 2) * kstep;
;             const char* a3 = a2 + kstep; const char* b3 = b2 + kstep;
;             PG8_LDB(B0, 0, 0); PG8_LDB(B1, 0, 1); PG8_SCHED; PG8_LDA(At, 0, 0); PG8_STAGE(PG8_SA(1, 1), a1 + hstepA, voffA);
;             PG8_WAIT_V(8); PG8_WAIT_L(0); PG8_BAR; PG8_MMA(0, 0, At, B0); PG8_MMA(0, 1, At, B1); PG8_BAR; PG8_SCHED;
;             PG8_LDA(At, 0, 1); PG8_STAGE(PG8_SB(0, 0), b2, voffB); PG8_STAGE(PG8_SB(0, 1), b2 + hstepB, voffB); PG8_STAGE(PG8_SA(0, 0), a2, voffA);
;             PG8_WAIT_V(8); PG8_WAIT_L(0); PG8_BAR; PG8_MMA(1, 0, At, B0); PG8_MMA(1, 1, At, B1); PG8_BAR; PG8_SCHED;
.LBB0_838:
	s_add_u32 s6, s4, 0xfff80080
	s_addc_u32 s7, s5, -1
	s_add_i32 s29, 0, 0x10000
	s_cmp_eq_u32 s28, 28
	s_cselect_b32 s37, s43, s7
	s_cselect_b32 s36, s42, s6
	v_add_u32_e32 v140, s29, v146
	s_cselect_b32 s7, s71, s23
	s_cselect_b32 s6, s70, s22
	s_add_i32 s31, 0, 0x14000
	ds_read_b128 v[136:139], v140
	ds_read_b128 v[148:151], v140 offset:1024
	ds_read_b128 v[152:155], v140 offset:2048
	ds_read_b128 v[156:159], v140 offset:3072
	v_add_u32_e32 v140, s31, v146
	ds_read_b128 v[160:163], v140
	ds_read_b128 v[164:167], v140 offset:1024
	ds_read_b128 v[168:171], v140 offset:2048
	ds_read_b128 v[172:175], v140 offset:3072
	v_lshl_add_u64 v[140:141], s[4:5], 0, v[132:133]
	s_add_i32 m0, s50, 0xc000
	ds_read_b128 v[176:179], v147
	ds_read_b128 v[180:183], v147 offset:1024
	ds_read_b128 v[184:187], v147 offset:2048
	ds_read_b128 v[188:191], v147 offset:3072
	ds_read_b128 v[192:195], v147 offset:4096
	ds_read_b128 v[196:199], v147 offset:5120
	ds_read_b128 v[200:203], v147 offset:6144
	ds_read_b128 v[204:207], v147 offset:7168
	global_load_lds_dwordx4 v[140:141], off
	v_lshl_add_u64 v[140:141], s[4:5], 0, v[134:135]
	s_add_i32 m0, s50, 0xe000
	s_nop 0
	global_load_lds_dwordx4 v[140:141], off
	s_waitcnt vmcnt(8)
	s_waitcnt lgkmcnt(0)
	s_barrier
	s_setprio 1
	s_waitcnt lgkmcnt(0)
	v_mfma_f32_16x16x32_bf16 v[126:129], v[136:139], v[176:179], v[126:129]
	v_mfma_f32_16x16x32_bf16 v[122:125], v[152:155], v[176:179], v[122:125]
	v_mfma_f32_16x16x32_bf16 v[110:113], v[136:139], v[184:187], v[110:113]
	v_mfma_f32_16x16x32_bf16 v[106:109], v[152:155], v[184:187], v[106:109]
	v_mfma_f32_16x16x32_bf16 v[94:97], v[136:139], v[192:195], v[94:97]
	v_mfma_f32_16x16x32_bf16 v[90:93], v[152:155], v[192:195], v[90:93]
	v_mfma_f32_16x16x32_bf16 v[78:81], v[136:139], v[200:203], v[78:81]
	v_mfma_f32_16x16x32_bf16 v[74:77], v[152:155], v[200:203], v[74:77]
	v_mfma_f32_16x16x32_bf16 v[126:129], v[148:151], v[180:183], v[126:129]
	v_mfma_f32_16x16x32_bf16 v[122:125], v[156:159], v[180:183], v[122:125]
	v_mfma_f32_16x16x32_bf16 v[110:113], v[148:151], v[188:191], v[110:113]
	v_mfma_f32_16x16x32_bf16 v[106:109], v[156:159], v[188:191], v[106:109]
	v_mfma_f32_16x16x32_bf16 v[94:97], v[148:151], v[196:199], v[94:97]
	v_mfma_f32_16x16x32_bf16 v[90:93], v[156:159], v[196:199], v[90:93]
	v_mfma_f32_16x16x32_bf16 v[78:81], v[148:151], v[204:207], v[78:81]
	v_mfma_f32_16x16x32_bf16 v[74:77], v[156:159], v[204:207], v[74:77]
	v_mfma_f32_16x16x32_bf16 v[118:121], v[160:163], v[176:179], v[118:121]
	v_mfma_f32_16x16x32_bf16 v[114:117], v[168:171], v[176:179], v[114:117]
	v_mfma_f32_16x16x32_bf16 v[102:105], v[160:163], v[184:187], v[102:105]
	v_mfma_f32_16x16x32_bf16 v[98:101], v[168:171], v[184:187], v[98:101]
	v_mfma_f32_16x16x32_bf16 v[86:89], v[160:163], v[192:195], v[86:89]
	v_mfma_f32_16x16x32_bf16 v[82:85], v[168:171], v[192:195], v[82:85]
	v_mfma_f32_16x16x32_bf16 v[70:73], v[160:163], v[200:203], v[70:73]
	v_mfma_f32_16x16x32_bf16 v[66:69], v[168:171], v[200:203], v[66:69]
	v_mfma_f32_16x16x32_bf16 v[118:121], v[164:167], v[180:183], v[118:121]
	v_mfma_f32_16x16x32_bf16 v[114:117], v[172:175], v[180:183], v[114:117]
	v_mfma_f32_16x16x32_bf16 v[102:105], v[164:167], v[188:191], v[102:105]
	v_mfma_f32_16x16x32_bf16 v[98:101], v[172:175], v[188:191], v[98:101]
	v_mfma_f32_16x16x32_bf16 v[86:89], v[164:167], v[196:199], v[86:89]
	v_mfma_f32_16x16x32_bf16 v[82:85], v[172:175], v[196:199], v[82:85]
	v_mfma_f32_16x16x32_bf16 v[70:73], v[164:167], v[204:207], v[70:73]
	v_mfma_f32_16x16x32_bf16 v[66:69], v[172:175], v[204:207], v[66:69]
	s_setprio 0
	s_barrier
	s_add_i32 s29, s29, s49
	v_lshl_add_u64 v[140:141], s[6:7], 0, v[0:1]
	s_mov_b32 m0, s29
	ds_read_b128 v[176:179], v147 offset:16384
	ds_read_b128 v[180:183], v147 offset:17408
	ds_read_b128 v[184:187], v147 offset:18432
	ds_read_b128 v[188:191], v147 offset:19456
	ds_read_b128 v[192:195], v147 offset:20480
	ds_read_b128 v[196:199], v147 offset:21504
	ds_read_b128 v[200:203], v147 offset:22528
	ds_read_b128 v[204:207], v147 offset:23552
	global_load_lds_dwordx4 v[140:141], off
	s_add_i32 m0, s29, 0x2000
	s_add_u32 s44, s6, 0x80000
	v_lshl_add_u64 v[208:209], s[6:7], 0, v[130:131]
	s_addc_u32 s45, s7, 0
	s_add_i32 s29, s31, s49
	global_load_lds_dwordx4 v[208:209], off
	v_lshl_add_u64 v[210:211], s[44:45], 0, v[0:1]
	s_mov_b32 m0, s29
	v_lshl_add_u64 v[212:213], s[36:37], 0, v[130:131]
	global_load_lds_dwordx4 v[210:211], off
	v_lshl_add_u64 v[210:211], s[44:45], 0, v[130:131]
	s_add_i32 m0, s29, 0x2000
	s_nop 0
	global_load_lds_dwordx4 v[210:211], off
	v_lshl_add_u64 v[210:211], s[36:37], 0, v[0:1]
	s_mov_b32 m0, s50
	s_nop 0
	global_load_lds_dwordx4 v[210:211], off
	s_mov_b32 m0, s51
	s_nop 0
	global_load_lds_dwordx4 v[212:213], off
	s_waitcnt vmcnt(8)
	s_waitcnt lgkmcnt(0)
	s_barrier
; #define PG8_STAGE(bufoff, gbase, voff) do { _Pragma("unroll") for (int _i = 0; _i < 2; ++_i) \
;         __builtin_amdgcn_global_load_lds((const unsigned*)((const char*)(gbase) + (voff)[_i]), (LAS unsigned*)(lds + (bufoff) + ldsw + _i * 8192), 16, 0, 0); } while (0)
; #define PG8_LDA(dst, b, h) do { _Pragma("unroll") for (int m = 0; m < 4; ++m) _Pragma("unroll") for (int k = 0; k < 2; ++k) dst[m][k] = *(const LAS bf16x8*)(lds + PG8_SA(b, h) + aoff + m * 2048 + k * 1024); } while (0)
; #define PG8_LDB(dst, b, h) do { _Pragma("unroll") for (int n = 0; n < 2; ++n) _Pragma("unroll") for (int k = 0; k < 2; ++k) dst[n][k] = *(const LAS bf16x8*)(lds + PG8_SB(b, h) + boff + n * 2048 + k * 1024); } while (0)
; #define PG8_MMA(ai, bj, At, Bt) do { __builtin_amdgcn_s_setprio(1); _Pragma("unroll") for (int m = 0; m < 4; ++m) _Pragma("unroll") for (int n = 0; n < 2; ++n) _Pragma("unroll") for (int k = 0; k < 2; ++k) \
;         acc[ai][bj][m][n] = __builtin_amdgcn_mfma_f32_16x16x32_bf16(Bt[n][k], At[m][k], acc[ai][bj][m][n], 0, 0, 0); __builtin_amdgcn_s_setprio(0); } while (0)
; #define PG8_WAIT_V(n) asm volatile("s_waitcnt vmcnt(" #n ")" ::: "memory")
; #define PG8_WAIT_L(n) asm volatile("s_waitcnt lgkmcnt(" #n ")" ::: "memory")
; #define PG8_BAR __builtin_amdgcn_s_barrier()
; #define PG8_SCHED __builtin_amdgcn_sched_barrier(0)
; template <class Epi, class Sched, bool ALIGN_EPI, bool LAST_FUSED = false, bool PERM = false, bool CARRY = false>
; __device__ __forceinline__ void gemm_phase(LAS unsigned char* lds, const int tid, const int K, const int lda, const int ldb, const Sched& S, const Epi& E) {
;     ...
;             PG8_WAIT_V(8); PG8_WAIT_L(0); PG8_BAR; PG8_MMA(1, 0, At, B0); PG8_MMA(1, 1, At, B1); PG8_BAR; PG8_SCHED;
;             PG8_LDB(B0, 1, 0); PG8_LDB(B1, 1, 1); PG8_SCHED; PG8_LDA(At, 1, 0); PG8_STAGE(PG8_SA(0, 1), a2 + hstepA, voffA);
;             PG8_WAIT_V(8); PG8_WAIT_L(0); PG8_BAR; PG8_MMA(0, 0, At, B0); PG8_MMA(0, 1, At, B1); PG8_BAR; PG8_SCHED;
	s_setprio 1
	s_waitcnt lgkmcnt(0)
	v_mfma_f32_16x16x32_bf16 v[62:65], v[136:139], v[176:179], v[62:65]
	v_mfma_f32_16x16x32_bf16 v[58:61], v[152:155], v[176:179], v[58:61]
	v_mfma_f32_16x16x32_bf16 v[46:49], v[136:139], v[184:187], v[46:49]
	v_mfma_f32_16x16x32_bf16 v[42:45], v[152:155], v[184:187], v[42:45]
	v_mfma_f32_16x16x32_bf16 v[30:33], v[136:139], v[192:195], v[30:33]
	v_mfma_f32_16x16x32_bf16 v[26:29], v[152:155], v[192:195], v[26:29]
	v_mfma_f32_16x16x32_bf16 v[14:17], v[136:139], v[200:203], v[14:17]
	v_mfma_f32_16x16x32_bf16 v[10:13], v[152:155], v[200:203], v[10:13]
	v_mfma_f32_16x16x32_bf16 v[62:65], v[148:151], v[180:183], v[62:65]
	v_mfma_f32_16x16x32_bf16 v[58:61], v[156:159], v[180:183], v[58:61]
	v_mfma_f32_16x16x32_bf16 v[46:49], v[148:151], v[188:191], v[46:49]
	v_mfma_f32_16x16x32_bf16 v[42:45], v[156:159], v[188:191], v[42:45]
	v_mfma_f32_16x16x32_bf16 v[30:33], v[148:151], v[196:199], v[30:33]
	v_mfma_f32_16x16x32_bf16 v[26:29], v[156:159], v[196:199], v[26:29]
	v_mfma_f32_16x16x32_bf16 v[14:17], v[148:151], v[204:207], v[14:17]
	v_mfma_f32_16x16x32_bf16 v[10:13], v[156:159], v[204:207], v[10:13]
	v_mfma_f32_16x16x32_bf16 v[54:57], v[160:163], v[176:179], v[54:57]
	v_mfma_f32_16x16x32_bf16 v[50:53], v[168:171], v[176:179], v[50:53]
	v_mfma_f32_16x16x32_bf16 v[38:41], v[160:163], v[184:187], v[38:41]
	v_mfma_f32_16x16x32_bf16 v[34:37], v[168:171], v[184:187], v[34:37]
	v_mfma_f32_16x16x32_bf16 v[22:25], v[160:163], v[192:195], v[22:25]
	v_mfma_f32_16x16x32_bf16 v[18:21], v[168:171], v[192:195], v[18:21]
	v_mfma_f32_16x16x32_bf16 v[6:9], v[160:163], v[200:203], v[6:9]
	v_mfma_f32_16x16x32_bf16 v[2:5], v[168:171], v[200:203], v[2:5]
	v_mfma_f32_16x16x32_bf16 v[54:57], v[164:167], v[180:183], v[54:57]
	v_mfma_f32_16x16x32_bf16 v[50:53], v[172:175], v[180:183], v[50:53]
	v_mfma_f32_16x16x32_bf16 v[38:41], v[164:167], v[188:191], v[38:41]
	v_mfma_f32_16x16x32_bf16 v[34:37], v[172:175], v[188:191], v[34:37]
	v_mfma_f32_16x16x32_bf16 v[22:25], v[164:167], v[196:199], v[22:25]
	v_mfma_f32_16x16x32_bf16 v[18:21], v[172:175], v[196:199], v[18:21]
	v_mfma_f32_16x16x32_bf16 v[6:9], v[164:167], v[204:207], v[6:9]
	v_mfma_f32_16x16x32_bf16 v[2:5], v[172:175], v[204:207], v[2:5]
	s_setprio 0
	s_barrier
	s_add_i32 s29, 0, 0x18000
	s_add_i32 s31, 0, 0x1c000
	v_add_u32_e32 v156, s29, v146
	v_add_u32_e32 v172, s31, v146
	ds_read_b128 v[136:139], v156
	ds_read_b128 v[148:151], v156 offset:1024
	ds_read_b128 v[152:155], v156 offset:2048
	ds_read_b128 v[156:159], v156 offset:3072
	ds_read_b128 v[160:163], v172
	ds_read_b128 v[164:167], v172 offset:1024
	ds_read_b128 v[168:171], v172 offset:2048
	ds_read_b128 v[172:175], v172 offset:3072
	s_add_u32 s36, s36, 0x80000
	s_addc_u32 s37, s37, 0
	s_mov_b32 m0, s52
	v_lshl_add_u64 v[214:215], s[36:37], 0, v[0:1]
	ds_read_b128 v[176:179], v147 offset:32768
	ds_read_b128 v[180:183], v147 offset:33792
	ds_read_b128 v[184:187], v147 offset:34816
	ds_read_b128 v[188:191], v147 offset:35840
	ds_read_b128 v[192:195], v147 offset:36864
	ds_read_b128 v[196:199], v147 offset:37888
	ds_read_b128 v[200:203], v147 offset:38912
	ds_read_b128 v[204:207], v147 offset:39936
	global_load_lds_dwordx4 v[214:215], off
	v_lshl_add_u64 v[214:215], s[36:37], 0, v[130:131]
	s_mov_b32 m0, s53
	s_nop 0
	global_load_lds_dwordx4 v[214:215], off
	s_waitcnt vmcnt(8)
	s_waitcnt lgkmcnt(0)
	s_barrier
	s_setprio 1
	s_waitcnt lgkmcnt(0)
	v_mfma_f32_16x16x32_bf16 v[126:129], v[136:139], v[176:179], v[126:129]
	v_mfma_f32_16x16x32_bf16 v[122:125], v[152:155], v[176:179], v[122:125]
	v_mfma_f32_16x16x32_bf16 v[110:113], v[136:139], v[184:187], v[110:113]
	v_mfma_f32_16x16x32_bf16 v[106:109], v[152:155], v[184:187], v[106:109]
	v_mfma_f32_16x16x32_bf16 v[94:97], v[136:139], v[192:195], v[94:97]
	v_mfma_f32_16x16x32_bf16 v[90:93], v[152:155], v[192:195], v[90:93]
	v_mfma_f32_16x16x32_bf16 v[78:81], v[136:139], v[200:203], v[78:81]
	v_mfma_f32_16x16x32_bf16 v[74:77], v[152:155], v[200:203], v[74:77]
	v_mfma_f32_16x16x32_bf16 v[126:129], v[148:151], v[180:183], v[126:129]
	v_mfma_f32_16x16x32_bf16 v[122:125], v[156:159], v[180:183], v[122:125]
	v_mfma_f32_16x16x32_bf16 v[110:113], v[148:151], v[188:191], v[110:113]
	v_mfma_f32_16x16x32_bf16 v[106:109], v[156:159], v[188:191], v[106:109]
	v_mfma_f32_16x16x32_bf16 v[94:97], v[148:151], v[196:199], v[94:97]
	v_mfma_f32_16x16x32_bf16 v[90:93], v[156:159], v[196:199], v[90:93]
	v_mfma_f32_16x16x32_bf16 v[78:81], v[148:151], v[204:207], v[78:81]
	v_mfma_f32_16x16x32_bf16 v[74:77], v[156:159], v[204:207], v[74:77]
	v_mfma_f32_16x16x32_bf16 v[118:121], v[160:163], v[176:179], v[118:121]
	v_mfma_f32_16x16x32_bf16 v[114:117], v[168:171], v[176:179], v[114:117]
	v_mfma_f32_16x16x32_bf16 v[102:105], v[160:163], v[184:187], v[102:105]
	v_mfma_f32_16x16x32_bf16 v[98:101], v[168:171], v[184:187], v[98:101]
	v_mfma_f32_16x16x32_bf16 v[86:89], v[160:163], v[192:195], v[86:89]
	v_mfma_f32_16x16x32_bf16 v[82:85], v[168:171], v[192:195], v[82:85]
	v_mfma_f32_16x16x32_bf16 v[70:73], v[160:163], v[200:203], v[70:73]
	v_mfma_f32_16x16x32_bf16 v[66:69], v[168:171], v[200:203], v[66:69]
	v_mfma_f32_16x16x32_bf16 v[118:121], v[164:167], v[180:183], v[118:121]
	v_mfma_f32_16x16x32_bf16 v[114:117], v[172:175], v[180:183], v[114:117]
	v_mfma_f32_16x16x32_bf16 v[102:105], v[164:167], v[188:191], v[102:105]
	v_mfma_f32_16x16x32_bf16 v[98:101], v[172:175], v[188:191], v[98:101]
	v_mfma_f32_16x16x32_bf16 v[86:89], v[164:167], v[196:199], v[86:89]
	v_mfma_f32_16x16x32_bf16 v[82:85], v[172:175], v[196:199], v[82:85]
	v_mfma_f32_16x16x32_bf16 v[70:73], v[164:167], v[204:207], v[70:73]
	v_mfma_f32_16x16x32_bf16 v[66:69], v[172:175], v[204:207], v[66:69]
	s_setprio 0
	s_barrier
; #define PG8_STAGE(bufoff, gbase, voff) do { _Pragma("unroll") for (int _i = 0; _i < 2; ++_i) \
;         __builtin_amdgcn_global_load_lds((const unsigned*)((const char*)(gbase) + (voff)[_i]), (LAS unsigned*)(lds + (bufoff) + ldsw + _i * 8192), 16, 0, 0); } while (0)
; #define PG8_LDA(dst, b, h) do { _Pragma("unroll") for (int m = 0; m < 4; ++m) _Pragma("unroll") for (int k = 0; k < 2; ++k) dst[m][k] = *(const LAS bf16x8*)(lds + PG8_SA(b, h) + aoff + m * 2048 + k * 1024); } while (0)
; #define PG8_MMA(ai, bj, At, Bt) do { __builtin_amdgcn_s_setprio(1); _Pragma("unroll") for (int m = 0; m < 4; ++m) _Pragma("unroll") for (int n = 0; n < 2; ++n) _Pragma("unroll") for (int k = 0; k < 2; ++k) \
;         acc[ai][bj][m][n] = __builtin_amdgcn_mfma_f32_16x16x32_bf16(Bt[n][k], At[m][k], acc[ai][bj][m][n], 0, 0, 0); __builtin_amdgcn_s_setprio(0); } while (0)
; #define PG8_WAIT_V(n) asm volatile("s_waitcnt vmcnt(" #n ")" ::: "memory")
; #define PG8_WAIT_L(n) asm volatile("s_waitcnt lgkmcnt(" #n ")" ::: "memory")
; #define PG8_BAR __builtin_amdgcn_s_barrier()
; #define PG8_SCHED __builtin_amdgcn_sched_barrier(0)
; template <class Epi, class Sched, bool ALIGN_EPI, bool LAST_FUSED = false, bool PERM = false, bool CARRY = false>
; __device__ __forceinline__ void gemm_phase(LAS unsigned char* lds, const int tid, const int K, const int lda, const int ldb, const Sched& S, const Epi& E) {
;     ...
;             PG8_LDA(At, 1, 1); PG8_STAGE(PG8_SB(1, 0), b3, voffB); PG8_STAGE(PG8_SB(1, 1), b3 + hstepB, voffB); PG8_STAGE(PG8_SA(1, 0), a3, voffA);
;             PG8_WAIT_V(8); PG8_WAIT_L(0); PG8_BAR; PG8_MMA(1, 0, At, B0); PG8_MMA(1, 1, At, B1); PG8_BAR; PG8_SCHED;
;         }
;         if constexpr (ALIGN_EPI) { if (wr == 0) PG8_BAR; }
	s_add_i32 s29, s29, s49
	v_lshl_add_u64 v[140:141], v[140:141], 0, s[68:69]
	s_mov_b32 m0, s29
	ds_read_b128 v[176:179], v147 offset:49152
	ds_read_b128 v[180:183], v147 offset:50176
	ds_read_b128 v[184:187], v147 offset:51200
	ds_read_b128 v[188:191], v147 offset:52224
	ds_read_b128 v[192:195], v147 offset:53248
	ds_read_b128 v[196:199], v147 offset:54272
	ds_read_b128 v[200:203], v147 offset:55296
	ds_read_b128 v[204:207], v147 offset:56320
	global_load_lds_dwordx4 v[140:141], off
	s_add_i32 m0, s29, 0x2000
	s_add_u32 s6, s6, 0x80080
	v_lshl_add_u64 v[140:141], v[208:209], 0, s[68:69]
	s_addc_u32 s7, s7, 0
	s_add_i32 s29, s31, s49
	global_load_lds_dwordx4 v[140:141], off
	v_lshl_add_u64 v[140:141], s[6:7], 0, v[0:1]
	s_mov_b32 m0, s29
	s_nop 0
	global_load_lds_dwordx4 v[140:141], off
	v_lshl_add_u64 v[140:141], s[6:7], 0, v[130:131]
	s_add_i32 m0, s29, 0x2000
	s_nop 0
	global_load_lds_dwordx4 v[140:141], off
	v_lshl_add_u64 v[140:141], v[210:211], 0, s[68:69]
	s_mov_b32 m0, s55
	s_nop 0
	global_load_lds_dwordx4 v[140:141], off
	v_lshl_add_u64 v[140:141], v[212:213], 0, s[68:69]
	s_mov_b32 m0, s56
	s_nop 0
	global_load_lds_dwordx4 v[140:141], off
	s_waitcnt vmcnt(8)
	s_waitcnt lgkmcnt(0)
	s_barrier
	s_setprio 1
	s_waitcnt lgkmcnt(0)
	v_mfma_f32_16x16x32_bf16 v[62:65], v[136:139], v[176:179], v[62:65]
	v_mfma_f32_16x16x32_bf16 v[58:61], v[152:155], v[176:179], v[58:61]
	v_mfma_f32_16x16x32_bf16 v[46:49], v[136:139], v[184:187], v[46:49]
	v_mfma_f32_16x16x32_bf16 v[42:45], v[152:155], v[184:187], v[42:45]
	v_mfma_f32_16x16x32_bf16 v[30:33], v[136:139], v[192:195], v[30:33]
	v_mfma_f32_16x16x32_bf16 v[26:29], v[152:155], v[192:195], v[26:29]
	v_mfma_f32_16x16x32_bf16 v[14:17], v[136:139], v[200:203], v[14:17]
	v_mfma_f32_16x16x32_bf16 v[10:13], v[152:155], v[200:203], v[10:13]
	v_mfma_f32_16x16x32_bf16 v[62:65], v[148:151], v[180:183], v[62:65]
	v_mfma_f32_16x16x32_bf16 v[58:61], v[156:159], v[180:183], v[58:61]
	v_mfma_f32_16x16x32_bf16 v[46:49], v[148:151], v[188:191], v[46:49]
	v_mfma_f32_16x16x32_bf16 v[42:45], v[156:159], v[188:191], v[42:45]
	v_mfma_f32_16x16x32_bf16 v[30:33], v[148:151], v[196:199], v[30:33]
	v_mfma_f32_16x16x32_bf16 v[26:29], v[156:159], v[196:199], v[26:29]
	v_mfma_f32_16x16x32_bf16 v[14:17], v[148:151], v[204:207], v[14:17]
	v_mfma_f32_16x16x32_bf16 v[10:13], v[156:159], v[204:207], v[10:13]
	v_mfma_f32_16x16x32_bf16 v[54:57], v[160:163], v[176:179], v[54:57]
	v_mfma_f32_16x16x32_bf16 v[50:53], v[168:171], v[176:179], v[50:53]
	v_mfma_f32_16x16x32_bf16 v[38:41], v[160:163], v[184:187], v[38:41]
	v_mfma_f32_16x16x32_bf16 v[34:37], v[168:171], v[184:187], v[34:37]
	v_mfma_f32_16x16x32_bf16 v[22:25], v[160:163], v[192:195], v[22:25]
	v_mfma_f32_16x16x32_bf16 v[18:21], v[168:171], v[192:195], v[18:21]
	v_mfma_f32_16x16x32_bf16 v[6:9], v[160:163], v[200:203], v[6:9]
	v_mfma_f32_16x16x32_bf16 v[2:5], v[168:171], v[200:203], v[2:5]
	v_mfma_f32_16x16x32_bf16 v[54:57], v[164:167], v[180:183], v[54:57]
	v_mfma_f32_16x16x32_bf16 v[50:53], v[172:175], v[180:183], v[50:53]
	v_mfma_f32_16x16x32_bf16 v[38:41], v[164:167], v[188:191], v[38:41]
	v_mfma_f32_16x16x32_bf16 v[34:37], v[172:175], v[188:191], v[34:37]
	v_mfma_f32_16x16x32_bf16 v[22:25], v[164:167], v[196:199], v[22:25]
	v_mfma_f32_16x16x32_bf16 v[18:21], v[172:175], v[196:199], v[18:21]
	v_mfma_f32_16x16x32_bf16 v[6:9], v[164:167], v[204:207], v[6:9]
	v_mfma_f32_16x16x32_bf16 v[2:5], v[172:175], v[204:207], v[2:5]
	s_setprio 0
	s_barrier
	s_add_i32 s28, s28, 2
	s_add_u32 s4, s4, 0x100
	s_addc_u32 s5, s5, 0
	s_add_u32 s22, s22, 0x100
	s_addc_u32 s23, s23, 0
	s_cmp_gt_u32 s28, 29
	s_cbranch_scc0 .LBB0_838
	s_and_b64 vcc, exec, s[26:27]
	s_cbranch_vccz .LBB0_841
	s_barrier

; #define PG8_STAGE(bufoff, gbase, voff) do { _Pragma("unroll") for (int _i = 0; _i < 2; ++_i) \
;         __builtin_amdgcn_global_load_lds((const unsigned*)((const char*)(gbase) + (voff)[_i]), (LAS unsigned*)(lds + (bufoff) + ldsw + _i * 8192), 16, 0, 0); } while (0)
; #define PG8_LDA(dst, b, h) do { _Pragma("unroll") for (int m = 0; m < 4; ++m) _Pragma("unroll") for (int k = 0; k < 2; ++k) dst[m][k] = *(const LAS bf16x8*)(lds + PG8_SA(b, h) + aoff + m * 2048 + k * 1024); } while (0)
; #define PG8_LDB(dst, b, h) do { _Pragma("unroll") for (int n = 0; n < 2; ++n) _Pragma("unroll") for (int k = 0; k < 2; ++k) dst[n][k] = *(const LAS bf16x8*)(lds + PG8_SB(b, h) + boff + n * 2048 + k * 1024); } while (0)
; #define PG8_MMA(ai, bj, At, Bt) do { __builtin_amdgcn_s_setprio(1); _Pragma("unroll") for (int m = 0; m < 4; ++m) _Pragma("unroll") for (int n = 0; n < 2; ++n) _Pragma("unroll") for (int k = 0; k < 2; ++k) \
;         acc[ai][bj][m][n] = __builtin_amdgcn_mfma_f32_16x16x32_bf16(Bt[n][k], At[m][k], acc[ai][bj][m][n], 0, 0, 0); __builtin_amdgcn_s_setprio(0); } while (0)
; #define PG8_WAIT_V(n) asm volatile("s_waitcnt vmcnt(" #n ")" ::: "memory")
; #define PG8_WAIT_L(n) asm volatile("s_waitcnt lgkmcnt(" #n ")" ::: "memory")
; template <class Epi, class Sched, bool ALIGN_EPI, bool LAST_FUSED = false, bool PERM = false, bool CARRY = false>
; __device__ __forceinline__ void gemm_phase(LAS unsigned char* lds, const int tid, const int K, const int lda, const int ldb, const Sched& S, const Epi& E) {
;     ...
;         for (int t = 0; t < nt; t += 2) {
;             const bool last = (t == nt - 2);
;             const char* a1 = cA + (size_t)(t + 1) * kstep;
;             const char* a2 = last ? nA : cA + (size_t)(t + 2) * kstep; const char* b2 = last ? nB : cB + (size_t)(t + 2) * kstep;
;             const char* a3 = a2 + kstep; const char* b3 = b2 + kstep;
;             PG8_LDB(B0, 0, 0); PG8_LDB(B1, 0, 1); PG8_SCHED; PG8_LDA(At, 0, 0); PG8_STAGE(PG8_SA(1, 1), a1 + hstepA, voffA);
;             PG8_WAIT_V(8); PG8_WAIT_L(0); PG8_BAR; PG8_MMA(0, 0, At, B0); PG8_MMA(0, 1, At, B1); PG8_BAR; PG8_SCHED;
;             PG8_LDA(At, 0, 1); PG8_STAGE(PG8_SB(0, 0), b2, voffB); PG8_STAGE(PG8_SB(0, 1), b2 + hstepB, voffB); PG8_STAGE(PG8_SA(0, 0), a2, voffA);
;             PG8_WAIT_V(8); PG8_WAIT_L(0); PG8_BAR; PG8_MMA(1, 0, At, B0); PG8_MMA(1, 1, At, B1); PG8_BAR; PG8_SCHED;
.LBB0_1077:
	s_add_u32 s23, s26, 0xfff80080
	s_addc_u32 s28, s27, -1
	s_add_i32 s29, 0, 0x10000
	s_cmp_eq_u32 s15, 28
	s_cselect_b32 s37, s17, s28
	s_cselect_b32 s36, s16, s23
	s_cselect_b32 s31, s19, s13
	s_cselect_b32 s30, s18, s5
	s_add_i32 s23, 0, 0x14000
	v_add_u32_e32 v152, s29, v142
	v_add_u32_e32 v168, s23, v142
	ds_read_b128 v[136:139], v152
	ds_read_b128 v[144:147], v152 offset:1024
	ds_read_b128 v[148:151], v152 offset:2048
	ds_read_b128 v[152:155], v152 offset:3072
	ds_read_b128 v[156:159], v168
	ds_read_b128 v[160:163], v168 offset:1024
	ds_read_b128 v[164:167], v168 offset:2048
	ds_read_b128 v[168:171], v168 offset:3072
	v_lshl_add_u64 v[204:205], s[26:27], 0, v[132:133]
	s_add_i32 m0, s46, 0xc000
	ds_read_b128 v[172:175], v143
	ds_read_b128 v[176:179], v143 offset:1024
	ds_read_b128 v[180:183], v143 offset:2048
	ds_read_b128 v[184:187], v143 offset:3072
	ds_read_b128 v[188:191], v143 offset:4096
	ds_read_b128 v[192:195], v143 offset:5120
	ds_read_b128 v[196:199], v143 offset:6144
	ds_read_b128 v[200:203], v143 offset:7168
	global_load_lds_dwordx4 v[204:205], off
	v_lshl_add_u64 v[204:205], s[26:27], 0, v[134:135]
	s_add_i32 m0, s46, 0xe000
	s_nop 0
	global_load_lds_dwordx4 v[204:205], off
	s_waitcnt vmcnt(8)
	s_waitcnt lgkmcnt(0)
	s_barrier
	s_setprio 1
	s_waitcnt lgkmcnt(0)
	v_mfma_f32_16x16x32_bf16 v[126:129], v[136:139], v[172:175], v[126:129]
	v_mfma_f32_16x16x32_bf16 v[122:125], v[148:151], v[172:175], v[122:125]
	v_mfma_f32_16x16x32_bf16 v[110:113], v[136:139], v[180:183], v[110:113]
	v_mfma_f32_16x16x32_bf16 v[106:109], v[148:151], v[180:183], v[106:109]
	v_mfma_f32_16x16x32_bf16 v[94:97], v[136:139], v[188:191], v[94:97]
	v_mfma_f32_16x16x32_bf16 v[90:93], v[148:151], v[188:191], v[90:93]
	v_mfma_f32_16x16x32_bf16 v[78:81], v[136:139], v[196:199], v[78:81]
	v_mfma_f32_16x16x32_bf16 v[74:77], v[148:151], v[196:199], v[74:77]
	v_mfma_f32_16x16x32_bf16 v[126:129], v[144:147], v[176:179], v[126:129]
	v_mfma_f32_16x16x32_bf16 v[122:125], v[152:155], v[176:179], v[122:125]
	v_mfma_f32_16x16x32_bf16 v[110:113], v[144:147], v[184:187], v[110:113]
	v_mfma_f32_16x16x32_bf16 v[106:109], v[152:155], v[184:187], v[106:109]
	v_mfma_f32_16x16x32_bf16 v[94:97], v[144:147], v[192:195], v[94:97]
	v_mfma_f32_16x16x32_bf16 v[90:93], v[152:155], v[192:195], v[90:93]
	v_mfma_f32_16x16x32_bf16 v[78:81], v[144:147], v[200:203], v[78:81]
	v_mfma_f32_16x16x32_bf16 v[74:77], v[152:155], v[200:203], v[74:77]
	v_mfma_f32_16x16x32_bf16 v[118:121], v[156:159], v[172:175], v[118:121]
	v_mfma_f32_16x16x32_bf16 v[114:117], v[164:167], v[172:175], v[114:117]
	v_mfma_f32_16x16x32_bf16 v[102:105], v[156:159], v[180:183], v[102:105]
	v_mfma_f32_16x16x32_bf16 v[98:101], v[164:167], v[180:183], v[98:101]
	v_mfma_f32_16x16x32_bf16 v[86:89], v[156:159], v[188:191], v[86:89]
	v_mfma_f32_16x16x32_bf16 v[82:85], v[164:167], v[188:191], v[82:85]
	v_mfma_f32_16x16x32_bf16 v[70:73], v[156:159], v[196:199], v[70:73]
	v_mfma_f32_16x16x32_bf16 v[66:69], v[164:167], v[196:199], v[66:69]
	v_mfma_f32_16x16x32_bf16 v[118:121], v[160:163], v[176:179], v[118:121]
	v_mfma_f32_16x16x32_bf16 v[114:117], v[168:171], v[176:179], v[114:117]
	v_mfma_f32_16x16x32_bf16 v[102:105], v[160:163], v[184:187], v[102:105]
	v_mfma_f32_16x16x32_bf16 v[98:101], v[168:171], v[184:187], v[98:101]
	v_mfma_f32_16x16x32_bf16 v[86:89], v[160:163], v[192:195], v[86:89]
	v_mfma_f32_16x16x32_bf16 v[82:85], v[168:171], v[192:195], v[82:85]
	v_mfma_f32_16x16x32_bf16 v[70:73], v[160:163], v[200:203], v[70:73]
	v_mfma_f32_16x16x32_bf16 v[66:69], v[168:171], v[200:203], v[66:69]
	s_setprio 0
	s_barrier
	s_add_i32 s28, s29, s43
	v_lshl_add_u64 v[204:205], s[30:31], 0, v[0:1]
	s_mov_b32 m0, s28
	ds_read_b128 v[172:175], v143 offset:16384
	ds_read_b128 v[176:179], v143 offset:17408
	ds_read_b128 v[180:183], v143 offset:18432
	ds_read_b128 v[184:187], v143 offset:19456
	ds_read_b128 v[188:191], v143 offset:20480
	ds_read_b128 v[192:195], v143 offset:21504
	ds_read_b128 v[196:199], v143 offset:22528
	ds_read_b128 v[200:203], v143 offset:23552
	global_load_lds_dwordx4 v[204:205], off
	s_add_i32 m0, s28, 0x2000
	s_add_u32 s28, s30, 0x80000
	v_lshl_add_u64 v[206:207], s[30:31], 0, v[130:131]
	s_addc_u32 s29, s31, 0
	s_add_i32 s23, s23, s43
	global_load_lds_dwordx4 v[206:207], off
	v_lshl_add_u64 v[208:209], s[28:29], 0, v[0:1]
	s_mov_b32 m0, s23
	v_lshl_add_u64 v[210:211], s[36:37], 0, v[130:131]
	global_load_lds_dwordx4 v[208:209], off
	v_lshl_add_u64 v[208:209], s[28:29], 0, v[130:131]
	s_add_i32 m0, s23, 0x2000
	s_nop 0
	global_load_lds_dwordx4 v[208:209], off
	v_lshl_add_u64 v[208:209], s[36:37], 0, v[0:1]
	s_mov_b32 m0, s46
	s_nop 0
	global_load_lds_dwordx4 v[208:209], off
	s_mov_b32 m0, s47
	s_nop 0
	global_load_lds_dwordx4 v[210:211], off
	s_waitcnt vmcnt(8)
	s_waitcnt lgkmcnt(0)
	s_barrier
; #define PG8_STAGE(bufoff, gbase, voff) do { _Pragma("unroll") for (int _i = 0; _i < 2; ++_i) \
;         __builtin_amdgcn_global_load_lds((const unsigned*)((const char*)(gbase) + (voff)[_i]), (LAS unsigned*)(lds + (bufoff) + ldsw + _i * 8192), 16, 0, 0); } while (0)
; #define PG8_LDA(dst, b, h) do { _Pragma("unroll") for (int m = 0; m < 4; ++m) _Pragma("unroll") for (int k = 0; k < 2; ++k) dst[m][k] = *(const LAS bf16x8*)(lds + PG8_SA(b, h) + aoff + m * 2048 + k * 1024); } while (0)
; #define PG8_LDB(dst, b, h) do { _Pragma("unroll") for (int n = 0; n < 2; ++n) _Pragma("unroll") for (int k = 0; k < 2; ++k) dst[n][k] = *(const LAS bf16x8*)(lds + PG8_SB(b, h) + boff + n * 2048 + k * 1024); } while (0)
; #define PG8_MMA(ai, bj, At, Bt) do { __builtin_amdgcn_s_setprio(1); _Pragma("unroll") for (int m = 0; m < 4; ++m) _Pragma("unroll") for (int n = 0; n < 2; ++n) _Pragma("unroll") for (int k = 0; k < 2; ++k) \
;         acc[ai][bj][m][n] = __builtin_amdgcn_mfma_f32_16x16x32_bf16(Bt[n][k], At[m][k], acc[ai][bj][m][n], 0, 0, 0); __builtin_amdgcn_s_setprio(0); } while (0)
; #define PG8_WAIT_V(n) asm volatile("s_waitcnt vmcnt(" #n ")" ::: "memory")
; #define PG8_WAIT_L(n) asm volatile("s_waitcnt lgkmcnt(" #n ")" ::: "memory")
; #define PG8_BAR __builtin_amdgcn_s_barrier()
; #define PG8_SCHED __builtin_amdgcn_sched_barrier(0)
; template <class Epi, class Sched, bool ALIGN_EPI, bool LAST_FUSED = false, bool PERM = false, bool CARRY = false>
; __device__ __forceinline__ void gemm_phase(LAS unsigned char* lds, const int tid, const int K, const int lda, const int ldb, const Sched& S, const Epi& E) {
;     ...
;             PG8_WAIT_V(8); PG8_WAIT_L(0); PG8_BAR; PG8_MMA(1, 0, At, B0); PG8_MMA(1, 1, At, B1); PG8_BAR; PG8_SCHED;
;             PG8_LDB(B0, 1, 0); PG8_LDB(B1, 1, 1); PG8_SCHED; PG8_LDA(At, 1, 0); PG8_STAGE(PG8_SA(0, 1), a2 + hstepA, voffA);
;             PG8_WAIT_V(8); PG8_WAIT_L(0); PG8_BAR; PG8_MMA(0, 0, At, B0); PG8_MMA(0, 1, At, B1); PG8_BAR; PG8_SCHED;
	s_setprio 1
	s_waitcnt lgkmcnt(0)
	v_mfma_f32_16x16x32_bf16 v[62:65], v[136:139], v[172:175], v[62:65]
	v_mfma_f32_16x16x32_bf16 v[58:61], v[148:151], v[172:175], v[58:61]
	v_mfma_f32_16x16x32_bf16 v[46:49], v[136:139], v[180:183], v[46:49]
	v_mfma_f32_16x16x32_bf16 v[42:45], v[148:151], v[180:183], v[42:45]
	v_mfma_f32_16x16x32_bf16 v[30:33], v[136:139], v[188:191], v[30:33]
	v_mfma_f32_16x16x32_bf16 v[26:29], v[148:151], v[188:191], v[26:29]
	v_mfma_f32_16x16x32_bf16 v[14:17], v[136:139], v[196:199], v[14:17]
	v_mfma_f32_16x16x32_bf16 v[10:13], v[148:151], v[196:199], v[10:13]
	v_mfma_f32_16x16x32_bf16 v[62:65], v[144:147], v[176:179], v[62:65]
	v_mfma_f32_16x16x32_bf16 v[58:61], v[152:155], v[176:179], v[58:61]
	v_mfma_f32_16x16x32_bf16 v[46:49], v[144:147], v[184:187], v[46:49]
	v_mfma_f32_16x16x32_bf16 v[42:45], v[152:155], v[184:187], v[42:45]
	v_mfma_f32_16x16x32_bf16 v[30:33], v[144:147], v[192:195], v[30:33]
	v_mfma_f32_16x16x32_bf16 v[26:29], v[152:155], v[192:195], v[26:29]
	v_mfma_f32_16x16x32_bf16 v[14:17], v[144:147], v[200:203], v[14:17]
	v_mfma_f32_16x16x32_bf16 v[10:13], v[152:155], v[200:203], v[10:13]
	v_mfma_f32_16x16x32_bf16 v[54:57], v[156:159], v[172:175], v[54:57]
	v_mfma_f32_16x16x32_bf16 v[50:53], v[164:167], v[172:175], v[50:53]
	v_mfma_f32_16x16x32_bf16 v[38:41], v[156:159], v[180:183], v[38:41]
	v_mfma_f32_16x16x32_bf16 v[34:37], v[164:167], v[180:183], v[34:37]
	v_mfma_f32_16x16x32_bf16 v[22:25], v[156:159], v[188:191], v[22:25]
	v_mfma_f32_16x16x32_bf16 v[18:21], v[164:167], v[188:191], v[18:21]
	v_mfma_f32_16x16x32_bf16 v[6:9], v[156:159], v[196:199], v[6:9]
	v_mfma_f32_16x16x32_bf16 v[2:5], v[164:167], v[196:199], v[2:5]
	v_mfma_f32_16x16x32_bf16 v[54:57], v[160:163], v[176:179], v[54:57]
	v_mfma_f32_16x16x32_bf16 v[50:53], v[168:171], v[176:179], v[50:53]
	v_mfma_f32_16x16x32_bf16 v[38:41], v[160:163], v[184:187], v[38:41]
	v_mfma_f32_16x16x32_bf16 v[34:37], v[168:171], v[184:187], v[34:37]
	v_mfma_f32_16x16x32_bf16 v[22:25], v[160:163], v[192:195], v[22:25]
	v_mfma_f32_16x16x32_bf16 v[18:21], v[168:171], v[192:195], v[18:21]
	v_mfma_f32_16x16x32_bf16 v[6:9], v[160:163], v[200:203], v[6:9]
	v_mfma_f32_16x16x32_bf16 v[2:5], v[168:171], v[200:203], v[2:5]
	s_setprio 0
	s_barrier
	s_add_i32 s23, 0, 0x18000
	s_add_i32 s35, 0, 0x1c000
	v_add_u32_e32 v152, s23, v142
	v_add_u32_e32 v168, s35, v142
	ds_read_b128 v[136:139], v152
	ds_read_b128 v[144:147], v152 offset:1024
	ds_read_b128 v[148:151], v152 offset:2048
	ds_read_b128 v[152:155], v152 offset:3072
	ds_read_b128 v[156:159], v168
	ds_read_b128 v[160:163], v168 offset:1024
	ds_read_b128 v[164:167], v168 offset:2048
	ds_read_b128 v[168:171], v168 offset:3072
	s_add_u32 s28, s36, 0x80000
	s_addc_u32 s29, s37, 0
	s_mov_b32 m0, s48
	v_lshl_add_u64 v[212:213], s[28:29], 0, v[0:1]
	ds_read_b128 v[172:175], v143 offset:32768
	ds_read_b128 v[176:179], v143 offset:33792
	ds_read_b128 v[180:183], v143 offset:34816
	ds_read_b128 v[184:187], v143 offset:35840
	ds_read_b128 v[188:191], v143 offset:36864
	ds_read_b128 v[192:195], v143 offset:37888
	ds_read_b128 v[196:199], v143 offset:38912
	ds_read_b128 v[200:203], v143 offset:39936
	global_load_lds_dwordx4 v[212:213], off
	v_lshl_add_u64 v[212:213], s[28:29], 0, v[130:131]
	s_mov_b32 m0, s49
	s_nop 0
	global_load_lds_dwordx4 v[212:213], off
	s_waitcnt vmcnt(8)
	s_waitcnt lgkmcnt(0)
	s_barrier
	s_setprio 1
	s_waitcnt lgkmcnt(0)
	v_mfma_f32_16x16x32_bf16 v[126:129], v[136:139], v[172:175], v[126:129]
	v_mfma_f32_16x16x32_bf16 v[122:125], v[148:151], v[172:175], v[122:125]
	v_mfma_f32_16x16x32_bf16 v[110:113], v[136:139], v[180:183], v[110:113]
	v_mfma_f32_16x16x32_bf16 v[106:109], v[148:151], v[180:183], v[106:109]
	v_mfma_f32_16x16x32_bf16 v[94:97], v[136:139], v[188:191], v[94:97]
	v_mfma_f32_16x16x32_bf16 v[90:93], v[148:151], v[188:191], v[90:93]
	v_mfma_f32_16x16x32_bf16 v[78:81], v[136:139], v[196:199], v[78:81]
	v_mfma_f32_16x16x32_bf16 v[74:77], v[148:151], v[196:199], v[74:77]
	v_mfma_f32_16x16x32_bf16 v[126:129], v[144:147], v[176:179], v[126:129]
	v_mfma_f32_16x16x32_bf16 v[122:125], v[152:155], v[176:179], v[122:125]
	v_mfma_f32_16x16x32_bf16 v[110:113], v[144:147], v[184:187], v[110:113]
	v_mfma_f32_16x16x32_bf16 v[106:109], v[152:155], v[184:187], v[106:109]
	v_mfma_f32_16x16x32_bf16 v[94:97], v[144:147], v[192:195], v[94:97]
	v_mfma_f32_16x16x32_bf16 v[90:93], v[152:155], v[192:195], v[90:93]
	v_mfma_f32_16x16x32_bf16 v[78:81], v[144:147], v[200:203], v[78:81]
	v_mfma_f32_16x16x32_bf16 v[74:77], v[152:155], v[200:203], v[74:77]
	v_mfma_f32_16x16x32_bf16 v[118:121], v[156:159], v[172:175], v[118:121]
	v_mfma_f32_16x16x32_bf16 v[114:117], v[164:167], v[172:175], v[114:117]
	v_mfma_f32_16x16x32_bf16 v[102:105], v[156:159], v[180:183], v[102:105]
	v_mfma_f32_16x16x32_bf16 v[98:101], v[164:167], v[180:183], v[98:101]
	v_mfma_f32_16x16x32_bf16 v[86:89], v[156:159], v[188:191], v[86:89]
	v_mfma_f32_16x16x32_bf16 v[82:85], v[164:167], v[188:191], v[82:85]
	v_mfma_f32_16x16x32_bf16 v[70:73], v[156:159], v[196:199], v[70:73]
	v_mfma_f32_16x16x32_bf16 v[66:69], v[164:167], v[196:199], v[66:69]
	v_mfma_f32_16x16x32_bf16 v[118:121], v[160:163], v[176:179], v[118:121]
	v_mfma_f32_16x16x32_bf16 v[114:117], v[168:171], v[176:179], v[114:117]
	v_mfma_f32_16x16x32_bf16 v[102:105], v[160:163], v[184:187], v[102:105]
	v_mfma_f32_16x16x32_bf16 v[98:101], v[168:171], v[184:187], v[98:101]
	v_mfma_f32_16x16x32_bf16 v[86:89], v[160:163], v[192:195], v[86:89]
	v_mfma_f32_16x16x32_bf16 v[82:85], v[168:171], v[192:195], v[82:85]
	v_mfma_f32_16x16x32_bf16 v[70:73], v[160:163], v[200:203], v[70:73]
	v_mfma_f32_16x16x32_bf16 v[66:69], v[168:171], v[200:203], v[66:69]
	s_setprio 0
	s_barrier
; #define PG8_STAGE(bufoff, gbase, voff) do { _Pragma("unroll") for (int _i = 0; _i < 2; ++_i) \
;         __builtin_amdgcn_global_load_lds((const unsigned*)((const char*)(gbase) + (voff)[_i]), (LAS unsigned*)(lds + (bufoff) + ldsw + _i * 8192), 16, 0, 0); } while (0)
; #define PG8_LDA(dst, b, h) do { _Pragma("unroll") for (int m = 0; m < 4; ++m) _Pragma("unroll") for (int k = 0; k < 2; ++k) dst[m][k] = *(const LAS bf16x8*)(lds + PG8_SA(b, h) + aoff + m * 2048 + k * 1024); } while (0)
; #define PG8_MMA(ai, bj, At, Bt) do { __builtin_amdgcn_s_setprio(1); _Pragma("unroll") for (int m = 0; m < 4; ++m) _Pragma("unroll") for (int n = 0; n < 2; ++n) _Pragma("unroll") for (int k = 0; k < 2; ++k) \
;         acc[ai][bj][m][n] = __builtin_amdgcn_mfma_f32_16x16x32_bf16(Bt[n][k], At[m][k], acc[ai][bj][m][n], 0, 0, 0); __builtin_amdgcn_s_setprio(0); } while (0)
; #define PG8_WAIT_V(n) asm volatile("s_waitcnt vmcnt(" #n ")" ::: "memory")
; #define PG8_WAIT_L(n) asm volatile("s_waitcnt lgkmcnt(" #n ")" ::: "memory")
; #define PG8_BAR __builtin_amdgcn_s_barrier()
; #define PG8_SCHED __builtin_amdgcn_sched_barrier(0)
; template <class Epi, class Sched, bool ALIGN_EPI, bool LAST_FUSED = false, bool PERM = false, bool CARRY = false>
; __device__ __forceinline__ void gemm_phase(LAS unsigned char* lds, const int tid, const int K, const int lda, const int ldb, const Sched& S, const Epi& E) {
;     ...
;             PG8_LDA(At, 1, 1); PG8_STAGE(PG8_SB(1, 0), b3, voffB); PG8_STAGE(PG8_SB(1, 1), b3 + hstepB, voffB); PG8_STAGE(PG8_SA(1, 0), a3, voffA);
;             PG8_WAIT_V(8); PG8_WAIT_L(0); PG8_BAR; PG8_MMA(1, 0, At, B0); PG8_MMA(1, 1, At, B1); PG8_BAR; PG8_SCHED;
;         }
;         if constexpr (ALIGN_EPI) { if (wr == 0) PG8_BAR; }
	s_add_i32 s23, s23, s43
	v_lshl_add_u64 v[204:205], v[204:205], 0, s[68:69]
	s_mov_b32 m0, s23
	ds_read_b128 v[172:175], v143 offset:49152
	ds_read_b128 v[176:179], v143 offset:50176
	ds_read_b128 v[180:183], v143 offset:51200
	ds_read_b128 v[184:187], v143 offset:52224
	ds_read_b128 v[188:191], v143 offset:53248
	ds_read_b128 v[192:195], v143 offset:54272
	ds_read_b128 v[196:199], v143 offset:55296
	ds_read_b128 v[200:203], v143 offset:56320
	global_load_lds_dwordx4 v[204:205], off
	s_add_i32 m0, s23, 0x2000
	s_add_u32 s28, s30, 0x80080
	v_lshl_add_u64 v[204:205], v[206:207], 0, s[68:69]
	s_addc_u32 s29, s31, 0
	s_add_i32 s23, s35, s43
	global_load_lds_dwordx4 v[204:205], off
	v_lshl_add_u64 v[204:205], s[28:29], 0, v[0:1]
	s_mov_b32 m0, s23
	s_nop 0
	global_load_lds_dwordx4 v[204:205], off
	v_lshl_add_u64 v[204:205], s[28:29], 0, v[130:131]
	s_add_i32 m0, s23, 0x2000
	s_nop 0
	global_load_lds_dwordx4 v[204:205], off
	v_lshl_add_u64 v[204:205], v[208:209], 0, s[68:69]
	s_mov_b32 m0, s51
	s_nop 0
	global_load_lds_dwordx4 v[204:205], off
	v_lshl_add_u64 v[204:205], v[210:211], 0, s[68:69]
	s_mov_b32 m0, s52
	s_nop 0
	global_load_lds_dwordx4 v[204:205], off
	s_waitcnt vmcnt(8)
	s_waitcnt lgkmcnt(0)
	s_barrier
	s_setprio 1
	s_waitcnt lgkmcnt(0)
	v_mfma_f32_16x16x32_bf16 v[62:65], v[136:139], v[172:175], v[62:65]
	v_mfma_f32_16x16x32_bf16 v[58:61], v[148:151], v[172:175], v[58:61]
	v_mfma_f32_16x16x32_bf16 v[46:49], v[136:139], v[180:183], v[46:49]
	v_mfma_f32_16x16x32_bf16 v[42:45], v[148:151], v[180:183], v[42:45]
	v_mfma_f32_16x16x32_bf16 v[30:33], v[136:139], v[188:191], v[30:33]
	v_mfma_f32_16x16x32_bf16 v[26:29], v[148:151], v[188:191], v[26:29]
	v_mfma_f32_16x16x32_bf16 v[14:17], v[136:139], v[196:199], v[14:17]
	v_mfma_f32_16x16x32_bf16 v[10:13], v[148:151], v[196:199], v[10:13]
	v_mfma_f32_16x16x32_bf16 v[62:65], v[144:147], v[176:179], v[62:65]
	v_mfma_f32_16x16x32_bf16 v[58:61], v[152:155], v[176:179], v[58:61]
	v_mfma_f32_16x16x32_bf16 v[46:49], v[144:147], v[184:187], v[46:49]
	v_mfma_f32_16x16x32_bf16 v[42:45], v[152:155], v[184:187], v[42:45]
	v_mfma_f32_16x16x32_bf16 v[30:33], v[144:147], v[192:195], v[30:33]
	v_mfma_f32_16x16x32_bf16 v[26:29], v[152:155], v[192:195], v[26:29]
	v_mfma_f32_16x16x32_bf16 v[14:17], v[144:147], v[200:203], v[14:17]
	v_mfma_f32_16x16x32_bf16 v[10:13], v[152:155], v[200:203], v[10:13]
	v_mfma_f32_16x16x32_bf16 v[54:57], v[156:159], v[172:175], v[54:57]
	v_mfma_f32_16x16x32_bf16 v[50:53], v[164:167], v[172:175], v[50:53]
	v_mfma_f32_16x16x32_bf16 v[38:41], v[156:159], v[180:183], v[38:41]
	v_mfma_f32_16x16x32_bf16 v[34:37], v[164:167], v[180:183], v[34:37]
	v_mfma_f32_16x16x32_bf16 v[22:25], v[156:159], v[188:191], v[22:25]
	v_mfma_f32_16x16x32_bf16 v[18:21], v[164:167], v[188:191], v[18:21]
	v_mfma_f32_16x16x32_bf16 v[6:9], v[156:159], v[196:199], v[6:9]
	v_mfma_f32_16x16x32_bf16 v[2:5], v[164:167], v[196:199], v[2:5]
	v_mfma_f32_16x16x32_bf16 v[54:57], v[160:163], v[176:179], v[54:57]
	v_mfma_f32_16x16x32_bf16 v[50:53], v[168:171], v[176:179], v[50:53]
	v_mfma_f32_16x16x32_bf16 v[38:41], v[160:163], v[184:187], v[38:41]
	v_mfma_f32_16x16x32_bf16 v[34:37], v[168:171], v[184:187], v[34:37]
	v_mfma_f32_16x16x32_bf16 v[22:25], v[160:163], v[192:195], v[22:25]
	v_mfma_f32_16x16x32_bf16 v[18:21], v[168:171], v[192:195], v[18:21]
	v_mfma_f32_16x16x32_bf16 v[6:9], v[160:163], v[200:203], v[6:9]
	v_mfma_f32_16x16x32_bf16 v[2:5], v[168:171], v[200:203], v[2:5]
	s_setprio 0
	s_barrier
	s_add_i32 s15, s15, 2
	s_add_u32 s26, s26, 0x100
	s_addc_u32 s27, s27, 0
	s_add_u32 s5, s5, 0x100
	s_addc_u32 s13, s13, 0
	s_cmp_gt_u32 s15, 29
	s_cbranch_scc0 .LBB0_1077
	s_and_b64 vcc, exec, s[10:11]
	s_cbranch_vccz .LBB0_1080
	s_barrier

; #define PG8_STAGE(bufoff, gbase, voff) do { _Pragma("unroll") for (int _i = 0; _i < 2; ++_i) \
;         __builtin_amdgcn_global_load_lds((const unsigned*)((const char*)(gbase) + (voff)[_i]), (LAS unsigned*)(lds + (bufoff) + ldsw + _i * 8192), 16, 0, 0); } while (0)
; #define PG8_LDA(dst, b, h) do { _Pragma("unroll") for (int m = 0; m < 4; ++m) _Pragma("unroll") for (int k = 0; k < 2; ++k) dst[m][k] = *(const LAS bf16x8*)(lds + PG8_SA(b, h) + aoff + m * 2048 + k * 1024); } while (0)
; #define PG8_LDB(dst, b, h) do { _Pragma("unroll") for (int n = 0; n < 2; ++n) _Pragma("unroll") for (int k = 0; k < 2; ++k) dst[n][k] = *(const LAS bf16x8*)(lds + PG8_SB(b, h) + boff + n * 2048 + k * 1024); } while (0)
; #define PG8_MMA(ai, bj, At, Bt) do { __builtin_amdgcn_s_setprio(1); _Pragma("unroll") for (int m = 0; m < 4; ++m) _Pragma("unroll") for (int n = 0; n < 2; ++n) _Pragma("unroll") for (int k = 0; k < 2; ++k) \
;         acc[ai][bj][m][n] = __builtin_amdgcn_mfma_f32_16x16x32_bf16(Bt[n][k], At[m][k], acc[ai][bj][m][n], 0, 0, 0); __builtin_amdgcn_s_setprio(0); } while (0)
; #define PG8_WAIT_V(n) asm volatile("s_waitcnt vmcnt(" #n ")" ::: "memory")
; #define PG8_WAIT_L(n) asm volatile("s_waitcnt lgkmcnt(" #n ")" ::: "memory")
; template <class Epi, class Sched, bool ALIGN_EPI, bool LAST_FUSED = false, bool PERM = false, bool CARRY = false>
; __device__ __forceinline__ void gemm_phase(LAS unsigned char* lds, const int tid, const int K, const int lda, const int ldb, const Sched& S, const Epi& E) {
;     ...
;         for (int t = 0; t < nt; t += 2) {
;             const bool last = (t == nt - 2);
;             const char* a1 = cA + (size_t)(t + 1) * kstep;
;             const char* a2 = last ? nA : cA + (size_t)(t + 2) * kstep; const char* b2 = last ? nB : cB + (size_t)(t + 2) * kstep;
;             const char* a3 = a2 + kstep; const char* b3 = b2 + kstep;
;             PG8_LDB(B0, 0, 0); PG8_LDB(B1, 0, 1); PG8_SCHED; PG8_LDA(At, 0, 0); PG8_STAGE(PG8_SA(1, 1), a1 + hstepA, voffA);
;             PG8_WAIT_V(8); PG8_WAIT_L(0); PG8_BAR; PG8_MMA(0, 0, At, B0); PG8_MMA(0, 1, At, B1); PG8_BAR; PG8_SCHED;
;             PG8_LDA(At, 0, 1); PG8_STAGE(PG8_SB(0, 0), b2, voffB); PG8_STAGE(PG8_SB(0, 1), b2 + hstepB, voffB); PG8_STAGE(PG8_SA(0, 0), a2, voffA);
;             PG8_WAIT_V(8); PG8_WAIT_L(0); PG8_BAR; PG8_MMA(1, 0, At, B0); PG8_MMA(1, 1, At, B1); PG8_BAR; PG8_SCHED;
.LBB0_1367:
	s_add_u32 s19, s38, s17
	s_addc_u32 s23, s39, 0
	s_add_u32 s35, s19, 0x100
	s_addc_u32 s37, s23, 0
	s_and_b64 s[28:29], s[46:47], exec
	s_cselect_b32 s51, s27, s37
	s_cselect_b32 s50, s26, s35
	s_add_u32 s17, s40, s17
	s_addc_u32 s28, s41, 0
	s_add_u32 s17, s17, 0x100
	s_addc_u32 s35, s28, 0
	s_add_i32 s45, 0, 0x10000
	s_and_b64 s[28:29], s[46:47], exec
	s_cselect_b32 s55, s31, s35
	s_cselect_b32 s54, s30, s17
	s_add_i32 s47, 0, 0x14000
	s_add_u32 s52, s19, 0x80080
	s_addc_u32 s53, s23, 0
	s_add_i32 s44, s45, s61
	s_add_i32 m0, s63, 0xc000
	s_add_i32 s79, s63, 0xe000
	s_add_i32 s29, s44, 0x2000
	s_add_u32 s58, s54, 0x10000
	v_add_u32_e32 v46, s45, v216
	v_add_u32_e32 v164, s47, v216
	s_addc_u32 s59, s55, 0
	s_add_i32 s37, s47, s61
	ds_read_b128 v[26:29], v46
	ds_read_b128 v[34:37], v46 offset:1024
	ds_read_b128 v[38:41], v46 offset:2048
	ds_read_b128 v[46:49], v46 offset:3072
	ds_read_b128 v[54:57], v164
	ds_read_b128 v[58:61], v164 offset:1024
	ds_read_b128 v[160:163], v164 offset:2048
	ds_read_b128 v[164:167], v164 offset:3072
	s_add_i32 s35, s37, 0x2000
	s_add_i32 s28, 0, 0x18000
	s_add_i32 s23, 0, 0x1c000
	s_add_u32 s48, s50, 0x80000
	s_addc_u32 s49, s51, 0
	s_add_i32 s19, s28, s61
	s_add_i32 s17, s19, 0x2000
	s_add_u32 s46, s54, 0x10080
	s_addc_u32 s47, s55, 0
	s_add_i32 s78, s23, s61
	s_add_i32 s45, s78, 0x2000
	v_lshl_add_u64 v[200:201], s[52:53], 0, v[158:159]
	ds_read_b128 v[168:171], v217
	ds_read_b128 v[172:175], v217 offset:1024
	ds_read_b128 v[176:179], v217 offset:2048
	ds_read_b128 v[180:183], v217 offset:3072
	ds_read_b128 v[184:187], v217 offset:4096
	ds_read_b128 v[188:191], v217 offset:5120
	ds_read_b128 v[192:195], v217 offset:6144
	ds_read_b128 v[196:199], v217 offset:7168
	global_load_lds_dwordx4 v[200:201], off
	v_lshl_add_u64 v[200:201], s[52:53], 0, v[156:157]
	s_mov_b32 m0, s79
	s_nop 0
	global_load_lds_dwordx4 v[200:201], off
	s_waitcnt vmcnt(8)
	s_waitcnt lgkmcnt(0)
	s_barrier
	s_setprio 1
	s_waitcnt lgkmcnt(0)
	v_mfma_f32_16x16x32_bf16 v[150:153], v[26:29], v[168:171], v[150:153]
	v_mfma_f32_16x16x32_bf16 v[142:145], v[38:41], v[168:171], v[142:145]
	v_mfma_f32_16x16x32_bf16 v[134:137], v[26:29], v[176:179], v[134:137]
	v_mfma_f32_16x16x32_bf16 v[126:129], v[38:41], v[176:179], v[126:129]
	v_mfma_f32_16x16x32_bf16 v[118:121], v[26:29], v[184:187], v[118:121]
	v_mfma_f32_16x16x32_bf16 v[110:113], v[38:41], v[184:187], v[110:113]
	v_mfma_f32_16x16x32_bf16 v[102:105], v[26:29], v[192:195], v[102:105]
	v_mfma_f32_16x16x32_bf16 v[94:97], v[38:41], v[192:195], v[94:97]
	v_mfma_f32_16x16x32_bf16 v[150:153], v[34:37], v[172:175], v[150:153]
	v_mfma_f32_16x16x32_bf16 v[142:145], v[46:49], v[172:175], v[142:145]
	v_mfma_f32_16x16x32_bf16 v[134:137], v[34:37], v[180:183], v[134:137]
	v_mfma_f32_16x16x32_bf16 v[126:129], v[46:49], v[180:183], v[126:129]
	v_mfma_f32_16x16x32_bf16 v[118:121], v[34:37], v[188:191], v[118:121]
	v_mfma_f32_16x16x32_bf16 v[110:113], v[46:49], v[188:191], v[110:113]
	v_mfma_f32_16x16x32_bf16 v[102:105], v[34:37], v[196:199], v[102:105]
	v_mfma_f32_16x16x32_bf16 v[94:97], v[46:49], v[196:199], v[94:97]
	v_mfma_f32_16x16x32_bf16 v[146:149], v[54:57], v[168:171], v[146:149]
	v_mfma_f32_16x16x32_bf16 v[138:141], v[160:163], v[168:171], v[138:141]
	v_mfma_f32_16x16x32_bf16 v[130:133], v[54:57], v[176:179], v[130:133]
	v_mfma_f32_16x16x32_bf16 v[122:125], v[160:163], v[176:179], v[122:125]
	v_mfma_f32_16x16x32_bf16 v[114:117], v[54:57], v[184:187], v[114:117]
	v_mfma_f32_16x16x32_bf16 v[106:109], v[160:163], v[184:187], v[106:109]
	v_mfma_f32_16x16x32_bf16 v[98:101], v[54:57], v[192:195], v[98:101]
	v_mfma_f32_16x16x32_bf16 v[90:93], v[160:163], v[192:195], v[90:93]
	v_mfma_f32_16x16x32_bf16 v[146:149], v[58:61], v[172:175], v[146:149]
	v_mfma_f32_16x16x32_bf16 v[138:141], v[164:167], v[172:175], v[138:141]
	v_mfma_f32_16x16x32_bf16 v[130:133], v[58:61], v[180:183], v[130:133]
	v_mfma_f32_16x16x32_bf16 v[122:125], v[164:167], v[180:183], v[122:125]
	v_mfma_f32_16x16x32_bf16 v[114:117], v[58:61], v[188:191], v[114:117]
	v_mfma_f32_16x16x32_bf16 v[106:109], v[164:167], v[188:191], v[106:109]
	v_mfma_f32_16x16x32_bf16 v[98:101], v[58:61], v[196:199], v[98:101]
	v_mfma_f32_16x16x32_bf16 v[90:93], v[164:167], v[196:199], v[90:93]
	s_setprio 0
	s_barrier
	s_mov_b32 m0, s44
	v_lshl_add_u64 v[204:205], s[54:55], 0, v[0:1]
	ds_read_b128 v[168:171], v217 offset:16384
	ds_read_b128 v[172:175], v217 offset:17408
	ds_read_b128 v[176:179], v217 offset:18432
	ds_read_b128 v[180:183], v217 offset:19456
	ds_read_b128 v[184:187], v217 offset:20480
	ds_read_b128 v[188:191], v217 offset:21504
	ds_read_b128 v[192:195], v217 offset:22528
	ds_read_b128 v[196:199], v217 offset:23552
	global_load_lds_dwordx4 v[204:205], off
	v_lshl_add_u64 v[206:207], s[54:55], 0, v[154:155]
	s_mov_b32 m0, s29
	v_lshl_add_u64 v[200:201], s[58:59], 0, v[0:1]
	global_load_lds_dwordx4 v[206:207], off
	s_mov_b32 m0, s37
	v_lshl_add_u64 v[208:209], s[50:51], 0, v[158:159]
	global_load_lds_dwordx4 v[200:201], off
	v_lshl_add_u64 v[200:201], s[58:59], 0, v[154:155]
	s_mov_b32 m0, s35
	v_lshl_add_u64 v[210:211], s[50:51], 0, v[156:157]
	global_load_lds_dwordx4 v[200:201], off
	s_mov_b32 m0, s63
	s_nop 0
	global_load_lds_dwordx4 v[208:209], off
	s_mov_b32 m0, s64
	s_nop 0
	global_load_lds_dwordx4 v[210:211], off
	s_waitcnt vmcnt(8)
	s_waitcnt lgkmcnt(0)
	s_barrier
; #define PG8_STAGE(bufoff, gbase, voff) do { _Pragma("unroll") for (int _i = 0; _i < 2; ++_i) \
;         __builtin_amdgcn_global_load_lds((const unsigned*)((const char*)(gbase) + (voff)[_i]), (LAS unsigned*)(lds + (bufoff) + ldsw + _i * 8192), 16, 0, 0); } while (0)
; #define PG8_LDA(dst, b, h) do { _Pragma("unroll") for (int m = 0; m < 4; ++m) _Pragma("unroll") for (int k = 0; k < 2; ++k) dst[m][k] = *(const LAS bf16x8*)(lds + PG8_SA(b, h) + aoff + m * 2048 + k * 1024); } while (0)
; #define PG8_LDB(dst, b, h) do { _Pragma("unroll") for (int n = 0; n < 2; ++n) _Pragma("unroll") for (int k = 0; k < 2; ++k) dst[n][k] = *(const LAS bf16x8*)(lds + PG8_SB(b, h) + boff + n * 2048 + k * 1024); } while (0)
; #define PG8_MMA(ai, bj, At, Bt) do { __builtin_amdgcn_s_setprio(1); _Pragma("unroll") for (int m = 0; m < 4; ++m) _Pragma("unroll") for (int n = 0; n < 2; ++n) _Pragma("unroll") for (int k = 0; k < 2; ++k) \
;         acc[ai][bj][m][n] = __builtin_amdgcn_mfma_f32_16x16x32_bf16(Bt[n][k], At[m][k], acc[ai][bj][m][n], 0, 0, 0); __builtin_amdgcn_s_setprio(0); } while (0)
; #define PG8_WAIT_V(n) asm volatile("s_waitcnt vmcnt(" #n ")" ::: "memory")
; #define PG8_WAIT_L(n) asm volatile("s_waitcnt lgkmcnt(" #n ")" ::: "memory")
; #define PG8_BAR __builtin_amdgcn_s_barrier()
; #define PG8_SCHED __builtin_amdgcn_sched_barrier(0)
; template <class Epi, class Sched, bool ALIGN_EPI, bool LAST_FUSED = false, bool PERM = false, bool CARRY = false>
; __device__ __forceinline__ void gemm_phase(LAS unsigned char* lds, const int tid, const int K, const int lda, const int ldb, const Sched& S, const Epi& E) {
;     ...
;             PG8_WAIT_V(8); PG8_WAIT_L(0); PG8_BAR; PG8_MMA(1, 0, At, B0); PG8_MMA(1, 1, At, B1); PG8_BAR; PG8_SCHED;
;             PG8_LDB(B0, 1, 0); PG8_LDB(B1, 1, 1); PG8_SCHED; PG8_LDA(At, 1, 0); PG8_STAGE(PG8_SA(0, 1), a2 + hstepA, voffA);
;             PG8_WAIT_V(8); PG8_WAIT_L(0); PG8_BAR; PG8_MMA(0, 0, At, B0); PG8_MMA(0, 1, At, B1); PG8_BAR; PG8_SCHED;
	s_setprio 1
	s_waitcnt lgkmcnt(0)
	v_mfma_f32_16x16x32_bf16 v[86:89], v[26:29], v[168:171], v[86:89]
	v_mfma_f32_16x16x32_bf16 v[78:81], v[38:41], v[168:171], v[78:81]
	v_mfma_f32_16x16x32_bf16 v[70:73], v[26:29], v[176:179], v[70:73]
	v_mfma_f32_16x16x32_bf16 v[62:65], v[38:41], v[176:179], v[62:65]
	v_mfma_f32_16x16x32_bf16 v[42:45], v[26:29], v[184:187], v[42:45]
	v_mfma_f32_16x16x32_bf16 v[22:25], v[38:41], v[184:187], v[22:25]
	v_mfma_f32_16x16x32_bf16 v[14:17], v[26:29], v[192:195], v[14:17]
	v_mfma_f32_16x16x32_bf16 v[6:9], v[38:41], v[192:195], v[6:9]
	v_mfma_f32_16x16x32_bf16 v[86:89], v[34:37], v[172:175], v[86:89]
	v_mfma_f32_16x16x32_bf16 v[78:81], v[46:49], v[172:175], v[78:81]
	v_mfma_f32_16x16x32_bf16 v[70:73], v[34:37], v[180:183], v[70:73]
	v_mfma_f32_16x16x32_bf16 v[62:65], v[46:49], v[180:183], v[62:65]
	v_mfma_f32_16x16x32_bf16 v[42:45], v[34:37], v[188:191], v[42:45]
	v_mfma_f32_16x16x32_bf16 v[22:25], v[46:49], v[188:191], v[22:25]
	v_mfma_f32_16x16x32_bf16 v[14:17], v[34:37], v[196:199], v[14:17]
	v_mfma_f32_16x16x32_bf16 v[6:9], v[46:49], v[196:199], v[6:9]
	v_mfma_f32_16x16x32_bf16 v[30:33], v[54:57], v[184:187], v[30:33]
	v_mfma_f32_16x16x32_bf16 v[18:21], v[160:163], v[184:187], v[18:21]
	v_mfma_f32_16x16x32_bf16 v[10:13], v[54:57], v[192:195], v[10:13]
	v_mfma_f32_16x16x32_bf16 v[2:5], v[160:163], v[192:195], v[2:5]
	v_mfma_f32_16x16x32_bf16 v[26:29], v[54:57], v[168:171], v[82:85]
	v_mfma_f32_16x16x32_bf16 v[34:37], v[160:163], v[168:171], v[74:77]
	v_mfma_f32_16x16x32_bf16 v[38:41], v[54:57], v[176:179], v[66:69]
	v_mfma_f32_16x16x32_bf16 v[46:49], v[160:163], v[176:179], v[50:53]
	v_mfma_f32_16x16x32_bf16 v[30:33], v[58:61], v[188:191], v[30:33]
	v_mfma_f32_16x16x32_bf16 v[18:21], v[164:167], v[188:191], v[18:21]
	v_mfma_f32_16x16x32_bf16 v[10:13], v[58:61], v[196:199], v[10:13]
	v_mfma_f32_16x16x32_bf16 v[2:5], v[164:167], v[196:199], v[2:5]
	v_mfma_f32_16x16x32_bf16 v[26:29], v[58:61], v[172:175], v[26:29]
	v_mfma_f32_16x16x32_bf16 v[34:37], v[164:167], v[172:175], v[34:37]
	v_mfma_f32_16x16x32_bf16 v[38:41], v[58:61], v[180:183], v[38:41]
	v_mfma_f32_16x16x32_bf16 v[46:49], v[164:167], v[180:183], v[46:49]
	s_setprio 0
	s_barrier
	v_add_u32_e32 v66, s28, v216
	v_add_u32_e32 v74, s23, v216
	ds_read_b128 v[50:53], v66
	ds_read_b128 v[54:57], v66 offset:1024
	ds_read_b128 v[58:61], v66 offset:2048
	ds_read_b128 v[66:69], v66 offset:3072
	ds_read_b128 v[160:163], v74
	ds_read_b128 v[164:167], v74 offset:1024
	ds_read_b128 v[168:171], v74 offset:2048
	ds_read_b128 v[172:175], v74 offset:3072
	s_mov_b32 m0, s65
	v_lshl_add_u64 v[200:201], s[48:49], 0, v[158:159]
	ds_read_b128 v[74:77], v217 offset:32768
	ds_read_b128 v[82:85], v217 offset:33792
	ds_read_b128 v[176:179], v217 offset:34816
	ds_read_b128 v[180:183], v217 offset:35840
	ds_read_b128 v[184:187], v217 offset:36864
	ds_read_b128 v[188:191], v217 offset:37888
	ds_read_b128 v[192:195], v217 offset:38912
	ds_read_b128 v[196:199], v217 offset:39936
	global_load_lds_dwordx4 v[200:201], off
	v_lshl_add_u64 v[200:201], s[48:49], 0, v[156:157]
	s_mov_b32 m0, s66
	s_nop 0
	global_load_lds_dwordx4 v[200:201], off
	s_waitcnt vmcnt(8)
	s_waitcnt lgkmcnt(0)
	s_barrier
	s_setprio 1
	s_waitcnt lgkmcnt(0)
	v_mfma_f32_16x16x32_bf16 v[150:153], v[50:53], v[74:77], v[150:153]
	v_mfma_f32_16x16x32_bf16 v[142:145], v[58:61], v[74:77], v[142:145]
	v_mfma_f32_16x16x32_bf16 v[134:137], v[50:53], v[176:179], v[134:137]
	v_mfma_f32_16x16x32_bf16 v[126:129], v[58:61], v[176:179], v[126:129]
	v_mfma_f32_16x16x32_bf16 v[118:121], v[50:53], v[184:187], v[118:121]
	v_mfma_f32_16x16x32_bf16 v[110:113], v[58:61], v[184:187], v[110:113]
	v_mfma_f32_16x16x32_bf16 v[102:105], v[50:53], v[192:195], v[102:105]
	v_mfma_f32_16x16x32_bf16 v[94:97], v[58:61], v[192:195], v[94:97]
	v_mfma_f32_16x16x32_bf16 v[150:153], v[54:57], v[82:85], v[150:153]
	v_mfma_f32_16x16x32_bf16 v[142:145], v[66:69], v[82:85], v[142:145]
	v_mfma_f32_16x16x32_bf16 v[134:137], v[54:57], v[180:183], v[134:137]
	v_mfma_f32_16x16x32_bf16 v[126:129], v[66:69], v[180:183], v[126:129]
	v_mfma_f32_16x16x32_bf16 v[118:121], v[54:57], v[188:191], v[118:121]
	v_mfma_f32_16x16x32_bf16 v[110:113], v[66:69], v[188:191], v[110:113]
	v_mfma_f32_16x16x32_bf16 v[102:105], v[54:57], v[196:199], v[102:105]
	v_mfma_f32_16x16x32_bf16 v[94:97], v[66:69], v[196:199], v[94:97]
	v_mfma_f32_16x16x32_bf16 v[146:149], v[160:163], v[74:77], v[146:149]
	v_mfma_f32_16x16x32_bf16 v[74:77], v[168:171], v[74:77], v[138:141]
	v_mfma_f32_16x16x32_bf16 v[138:141], v[172:175], v[82:85], v[74:77]
	v_mfma_f32_16x16x32_bf16 v[74:77], v[160:163], v[176:179], v[130:133]
	v_mfma_f32_16x16x32_bf16 v[130:133], v[164:167], v[180:183], v[74:77]
	v_mfma_f32_16x16x32_bf16 v[74:77], v[168:171], v[176:179], v[122:125]
	v_mfma_f32_16x16x32_bf16 v[122:125], v[172:175], v[180:183], v[74:77]
	v_mfma_f32_16x16x32_bf16 v[74:77], v[160:163], v[184:187], v[114:117]
	v_mfma_f32_16x16x32_bf16 v[114:117], v[164:167], v[188:191], v[74:77]
	v_mfma_f32_16x16x32_bf16 v[74:77], v[168:171], v[184:187], v[106:109]
	v_mfma_f32_16x16x32_bf16 v[106:109], v[172:175], v[188:191], v[74:77]
	v_mfma_f32_16x16x32_bf16 v[74:77], v[160:163], v[192:195], v[98:101]
	v_mfma_f32_16x16x32_bf16 v[98:101], v[164:167], v[196:199], v[74:77]
	v_mfma_f32_16x16x32_bf16 v[74:77], v[168:171], v[192:195], v[90:93]
	v_mfma_f32_16x16x32_bf16 v[146:149], v[164:167], v[82:85], v[146:149]
	v_mfma_f32_16x16x32_bf16 v[90:93], v[172:175], v[196:199], v[74:77]
	s_setprio 0
	s_barrier
; #define PG8_STAGE(bufoff, gbase, voff) do { _Pragma("unroll") for (int _i = 0; _i < 2; ++_i) \
;         __builtin_amdgcn_global_load_lds((const unsigned*)((const char*)(gbase) + (voff)[_i]), (LAS unsigned*)(lds + (bufoff) + ldsw + _i * 8192), 16, 0, 0); } while (0)
; #define PG8_LDA(dst, b, h) do { _Pragma("unroll") for (int m = 0; m < 4; ++m) _Pragma("unroll") for (int k = 0; k < 2; ++k) dst[m][k] = *(const LAS bf16x8*)(lds + PG8_SA(b, h) + aoff + m * 2048 + k * 1024); } while (0)
; #define PG8_MMA(ai, bj, At, Bt) do { __builtin_amdgcn_s_setprio(1); _Pragma("unroll") for (int m = 0; m < 4; ++m) _Pragma("unroll") for (int n = 0; n < 2; ++n) _Pragma("unroll") for (int k = 0; k < 2; ++k) \
;         acc[ai][bj][m][n] = __builtin_amdgcn_mfma_f32_16x16x32_bf16(Bt[n][k], At[m][k], acc[ai][bj][m][n], 0, 0, 0); __builtin_amdgcn_s_setprio(0); } while (0)
; #define PG8_WAIT_V(n) asm volatile("s_waitcnt vmcnt(" #n ")" ::: "memory")
; #define PG8_WAIT_L(n) asm volatile("s_waitcnt lgkmcnt(" #n ")" ::: "memory")
; #define PG8_BAR __builtin_amdgcn_s_barrier()
; #define PG8_SCHED __builtin_amdgcn_sched_barrier(0)
; template <class Epi, class Sched, bool ALIGN_EPI, bool LAST_FUSED = false, bool PERM = false, bool CARRY = false>
; __device__ __forceinline__ void gemm_phase(LAS unsigned char* lds, const int tid, const int K, const int lda, const int ldb, const Sched& S, const Epi& E) {
;     ...
;             PG8_LDA(At, 1, 1); PG8_STAGE(PG8_SB(1, 0), b3, voffB); PG8_STAGE(PG8_SB(1, 1), b3 + hstepB, voffB); PG8_STAGE(PG8_SA(1, 0), a3, voffA);
;             PG8_WAIT_V(8); PG8_WAIT_L(0); PG8_BAR; PG8_MMA(1, 0, At, B0); PG8_MMA(1, 1, At, B1); PG8_BAR; PG8_SCHED;
;         }
;         if constexpr (ALIGN_EPI) { if (wr == 0) PG8_BAR; }
	s_mov_b32 m0, s19
	v_lshl_add_u64 v[82:83], v[204:205], 0, s[68:69]
	s_nop 1
	ds_read_b128 v[74:77], v217 offset:49152
	ds_read_b128 v[176:179], v217 offset:50176
	ds_read_b128 v[180:183], v217 offset:51200
	ds_read_b128 v[184:187], v217 offset:52224
	ds_read_b128 v[188:191], v217 offset:53248
	ds_read_b128 v[192:195], v217 offset:54272
	ds_read_b128 v[196:199], v217 offset:55296
	ds_read_b128 v[200:203], v217 offset:56320
	global_load_lds_dwordx4 v[82:83], off
	v_lshl_add_u64 v[82:83], v[206:207], 0, s[68:69]
	s_mov_b32 m0, s17
	s_nop 0
	global_load_lds_dwordx4 v[82:83], off
	v_lshl_add_u64 v[82:83], s[46:47], 0, v[0:1]
	s_mov_b32 m0, s78
	s_nop 0
	global_load_lds_dwordx4 v[82:83], off
	v_lshl_add_u64 v[82:83], s[46:47], 0, v[154:155]
	s_mov_b32 m0, s45
	s_nop 0
	global_load_lds_dwordx4 v[82:83], off
	v_lshl_add_u64 v[82:83], v[208:209], 0, s[68:69]
	s_mov_b32 m0, s74
	s_nop 0
	global_load_lds_dwordx4 v[82:83], off
	v_lshl_add_u64 v[82:83], v[210:211], 0, s[68:69]
	s_mov_b32 m0, s75
	s_nop 0
	global_load_lds_dwordx4 v[82:83], off
	s_waitcnt vmcnt(8)
	s_waitcnt lgkmcnt(0)
	s_barrier
	s_setprio 1
	s_waitcnt lgkmcnt(0)
	v_mfma_f32_16x16x32_bf16 v[82:85], v[50:53], v[74:77], v[86:89]
	v_mfma_f32_16x16x32_bf16 v[78:81], v[58:61], v[74:77], v[78:81]
	v_mfma_f32_16x16x32_bf16 v[70:73], v[50:53], v[180:183], v[70:73]
	v_mfma_f32_16x16x32_bf16 v[62:65], v[58:61], v[180:183], v[62:65]
	v_mfma_f32_16x16x32_bf16 v[42:45], v[50:53], v[188:191], v[42:45]
	v_mfma_f32_16x16x32_bf16 v[22:25], v[58:61], v[188:191], v[22:25]
	v_mfma_f32_16x16x32_bf16 v[14:17], v[50:53], v[196:199], v[14:17]
	v_mfma_f32_16x16x32_bf16 v[6:9], v[58:61], v[196:199], v[6:9]
	v_mfma_f32_16x16x32_bf16 v[86:89], v[54:57], v[176:179], v[82:85]
	v_mfma_f32_16x16x32_bf16 v[78:81], v[66:69], v[176:179], v[78:81]
	v_mfma_f32_16x16x32_bf16 v[70:73], v[54:57], v[184:187], v[70:73]
	v_mfma_f32_16x16x32_bf16 v[62:65], v[66:69], v[184:187], v[62:65]
	v_mfma_f32_16x16x32_bf16 v[42:45], v[54:57], v[192:195], v[42:45]
	v_mfma_f32_16x16x32_bf16 v[22:25], v[66:69], v[192:195], v[22:25]
	v_mfma_f32_16x16x32_bf16 v[14:17], v[54:57], v[200:203], v[14:17]
	v_mfma_f32_16x16x32_bf16 v[6:9], v[66:69], v[200:203], v[6:9]
	v_mfma_f32_16x16x32_bf16 v[26:29], v[160:163], v[74:77], v[26:29]
	v_mfma_f32_16x16x32_bf16 v[82:85], v[164:167], v[176:179], v[26:29]
	v_mfma_f32_16x16x32_bf16 v[26:29], v[168:171], v[74:77], v[34:37]
	v_mfma_f32_16x16x32_bf16 v[74:77], v[172:175], v[176:179], v[26:29]
	v_mfma_f32_16x16x32_bf16 v[26:29], v[160:163], v[180:183], v[38:41]
	v_mfma_f32_16x16x32_bf16 v[66:69], v[164:167], v[184:187], v[26:29]
	v_mfma_f32_16x16x32_bf16 v[26:29], v[168:171], v[180:183], v[46:49]
	v_mfma_f32_16x16x32_bf16 v[50:53], v[172:175], v[184:187], v[26:29]
	v_mfma_f32_16x16x32_bf16 v[26:29], v[160:163], v[188:191], v[30:33]
	v_mfma_f32_16x16x32_bf16 v[18:21], v[168:171], v[188:191], v[18:21]
	v_mfma_f32_16x16x32_bf16 v[10:13], v[160:163], v[196:199], v[10:13]
	v_mfma_f32_16x16x32_bf16 v[2:5], v[168:171], v[196:199], v[2:5]
	v_mfma_f32_16x16x32_bf16 v[30:33], v[164:167], v[192:195], v[26:29]
	v_mfma_f32_16x16x32_bf16 v[18:21], v[172:175], v[192:195], v[18:21]
	v_mfma_f32_16x16x32_bf16 v[10:13], v[164:167], v[200:203], v[10:13]
	v_mfma_f32_16x16x32_bf16 v[2:5], v[172:175], v[200:203], v[2:5]
	s_setprio 0
	s_barrier
	s_movk_i32 s17, 0x100
	s_andn2_b64 vcc, exec, s[42:43]
	s_mov_b64 s[46:47], -1
	s_mov_b64 s[42:43], 0
	s_cbranch_vccz .LBB0_1367
	s_and_b64 vcc, exec, s[14:15]
	s_cbranch_vccz .LBB0_1370
	s_barrier

; #define PG8_STAGE(bufoff, gbase, voff) do { _Pragma("unroll") for (int _i = 0; _i < 2; ++_i) \
;         __builtin_amdgcn_global_load_lds((const unsigned*)((const char*)(gbase) + (voff)[_i]), (LAS unsigned*)(lds + (bufoff) + ldsw + _i * 8192), 16, 0, 0); } while (0)
; #define PG8_LDA(dst, b, h) do { _Pragma("unroll") for (int m = 0; m < 4; ++m) _Pragma("unroll") for (int k = 0; k < 2; ++k) dst[m][k] = *(const LAS bf16x8*)(lds + PG8_SA(b, h) + aoff + m * 2048 + k * 1024); } while (0)
; #define PG8_LDB(dst, b, h) do { _Pragma("unroll") for (int n = 0; n < 2; ++n) _Pragma("unroll") for (int k = 0; k < 2; ++k) dst[n][k] = *(const LAS bf16x8*)(lds + PG8_SB(b, h) + boff + n * 2048 + k * 1024); } while (0)
; #define PG8_MMA(ai, bj, At, Bt) do { __builtin_amdgcn_s_setprio(1); _Pragma("unroll") for (int m = 0; m < 4; ++m) _Pragma("unroll") for (int n = 0; n < 2; ++n) _Pragma("unroll") for (int k = 0; k < 2; ++k) \
;         acc[ai][bj][m][n] = __builtin_amdgcn_mfma_f32_16x16x32_bf16(Bt[n][k], At[m][k], acc[ai][bj][m][n], 0, 0, 0); __builtin_amdgcn_s_setprio(0); } while (0)
; #define PG8_WAIT_V(n) asm volatile("s_waitcnt vmcnt(" #n ")" ::: "memory")
; #define PG8_WAIT_L(n) asm volatile("s_waitcnt lgkmcnt(" #n ")" ::: "memory")
; template <class Epi, class Sched, bool ALIGN_EPI, bool LAST_FUSED = false, bool PERM = false, bool CARRY = false>
; __device__ __forceinline__ void gemm_phase(LAS unsigned char* lds, const int tid, const int K, const int lda, const int ldb, const Sched& S, const Epi& E) {
;     ...
;         for (int t = 0; t < nt; t += 2) {
;             const bool last = (t == nt - 2);
;             const char* a1 = cA + (size_t)(t + 1) * kstep;
;             const char* a2 = last ? nA : cA + (size_t)(t + 2) * kstep; const char* b2 = last ? nB : cB + (size_t)(t + 2) * kstep;
;             const char* a3 = a2 + kstep; const char* b3 = b2 + kstep;
;             PG8_LDB(B0, 0, 0); PG8_LDB(B1, 0, 1); PG8_SCHED; PG8_LDA(At, 0, 0); PG8_STAGE(PG8_SA(1, 1), a1 + hstepA, voffA);
;             PG8_WAIT_V(8); PG8_WAIT_L(0); PG8_BAR; PG8_MMA(0, 0, At, B0); PG8_MMA(0, 1, At, B1); PG8_BAR; PG8_SCHED;
;             PG8_LDA(At, 0, 1); PG8_STAGE(PG8_SB(0, 0), b2, voffB); PG8_STAGE(PG8_SB(0, 1), b2 + hstepB, voffB); PG8_STAGE(PG8_SA(0, 0), a2, voffA);
;             PG8_WAIT_V(8); PG8_WAIT_L(0); PG8_BAR; PG8_MMA(1, 0, At, B0); PG8_MMA(1, 1, At, B1); PG8_BAR; PG8_SCHED;
.LBB0_1585:
	s_add_u32 s52, s42, s48
	s_addc_u32 s53, s43, s49
	s_add_u32 s76, s40, s48
	s_addc_u32 s77, s41, s49
	s_add_i32 s96, 0, 0x10000
	s_cmp_eq_u32 s3, s95
	s_cselect_b32 s53, s24, s53
	s_cselect_b32 s52, s55, s52
	s_cselect_b32 s77, s93, s77
	s_cselect_b32 s76, s94, s76
	s_add_i32 vcc_lo, 0, 0x14000
	v_add_u32_e32 v156, s96, v140
	v_add_u32_e32 v172, vcc_lo, v140
	ds_read_b128 v[142:145], v156
	ds_read_b128 v[146:149], v156 offset:1024
	ds_read_b128 v[150:153], v156 offset:2048
	ds_read_b128 v[156:159], v156 offset:3072
	ds_read_b128 v[160:163], v172
	ds_read_b128 v[164:167], v172 offset:1024
	ds_read_b128 v[168:171], v172 offset:2048
	ds_read_b128 v[172:175], v172 offset:3072
	v_lshl_add_u64 v[208:209], s[42:43], 0, v[138:139]
	s_add_i32 m0, s35, 0xc000
	ds_read_b128 v[176:179], v141
	ds_read_b128 v[180:183], v141 offset:1024
	ds_read_b128 v[184:187], v141 offset:2048
	ds_read_b128 v[188:191], v141 offset:3072
	ds_read_b128 v[192:195], v141 offset:4096
	ds_read_b128 v[196:199], v141 offset:5120
	ds_read_b128 v[200:203], v141 offset:6144
	ds_read_b128 v[204:207], v141 offset:7168
	global_load_lds_dwordx4 v[208:209], off
	v_lshl_add_u64 v[208:209], s[42:43], 0, v[128:129]
	s_add_i32 m0, s35, 0xe000
	s_nop 0
	global_load_lds_dwordx4 v[208:209], off
	s_waitcnt vmcnt(8)
	s_waitcnt lgkmcnt(0)
	s_barrier
	s_setprio 1
	s_waitcnt lgkmcnt(0)
	v_mfma_f32_16x16x32_bf16 v[62:65], v[142:145], v[176:179], v[62:65]
	v_mfma_f32_16x16x32_bf16 v[42:45], v[150:153], v[176:179], v[42:45]
	v_mfma_f32_16x16x32_bf16 v[18:21], v[142:145], v[184:187], v[18:21]
	v_mfma_f32_16x16x32_bf16 v[14:17], v[150:153], v[184:187], v[14:17]
	v_mfma_f32_16x16x32_bf16 v[38:41], v[142:145], v[192:195], v[38:41]
	v_mfma_f32_16x16x32_bf16 v[30:33], v[150:153], v[192:195], v[30:33]
	v_mfma_f32_16x16x32_bf16 v[58:61], v[142:145], v[200:203], v[58:61]
	v_mfma_f32_16x16x32_bf16 v[54:57], v[150:153], v[200:203], v[54:57]
	v_mfma_f32_16x16x32_bf16 v[62:65], v[146:149], v[180:183], v[62:65]
	v_mfma_f32_16x16x32_bf16 v[42:45], v[156:159], v[180:183], v[42:45]
	v_mfma_f32_16x16x32_bf16 v[18:21], v[146:149], v[188:191], v[18:21]
	v_mfma_f32_16x16x32_bf16 v[14:17], v[156:159], v[188:191], v[14:17]
	v_mfma_f32_16x16x32_bf16 v[38:41], v[146:149], v[196:199], v[38:41]
	v_mfma_f32_16x16x32_bf16 v[30:33], v[156:159], v[196:199], v[30:33]
	v_mfma_f32_16x16x32_bf16 v[58:61], v[146:149], v[204:207], v[58:61]
	v_mfma_f32_16x16x32_bf16 v[54:57], v[156:159], v[204:207], v[54:57]
	v_mfma_f32_16x16x32_bf16 v[34:37], v[160:163], v[176:179], v[34:37]
	v_mfma_f32_16x16x32_bf16 v[2:5], v[168:171], v[176:179], v[2:5]
	v_mfma_f32_16x16x32_bf16 v[10:13], v[160:163], v[184:187], v[10:13]
	v_mfma_f32_16x16x32_bf16 v[6:9], v[168:171], v[184:187], v[6:9]
	v_mfma_f32_16x16x32_bf16 v[26:29], v[160:163], v[192:195], v[26:29]
	v_mfma_f32_16x16x32_bf16 v[22:25], v[168:171], v[192:195], v[22:25]
	v_mfma_f32_16x16x32_bf16 v[50:53], v[160:163], v[200:203], v[50:53]
	v_mfma_f32_16x16x32_bf16 v[46:49], v[168:171], v[200:203], v[46:49]
	v_mfma_f32_16x16x32_bf16 v[34:37], v[164:167], v[180:183], v[34:37]
	v_mfma_f32_16x16x32_bf16 v[2:5], v[172:175], v[180:183], v[2:5]
	v_mfma_f32_16x16x32_bf16 v[10:13], v[164:167], v[188:191], v[10:13]
	v_mfma_f32_16x16x32_bf16 v[6:9], v[172:175], v[188:191], v[6:9]
	v_mfma_f32_16x16x32_bf16 v[26:29], v[164:167], v[196:199], v[26:29]
	v_mfma_f32_16x16x32_bf16 v[22:25], v[172:175], v[196:199], v[22:25]
	v_mfma_f32_16x16x32_bf16 v[50:53], v[164:167], v[204:207], v[50:53]
	v_mfma_f32_16x16x32_bf16 v[46:49], v[172:175], v[204:207], v[46:49]
	s_setprio 0
	s_barrier
	s_add_i32 s96, s96, s87
	v_lshl_add_u64 v[208:209], s[76:77], 0, v[0:1]
	s_mov_b32 m0, s96
	ds_read_b128 v[176:179], v141 offset:16384
	ds_read_b128 v[180:183], v141 offset:17408
	ds_read_b128 v[184:187], v141 offset:18432
	ds_read_b128 v[188:191], v141 offset:19456
	ds_read_b128 v[192:195], v141 offset:20480
	ds_read_b128 v[196:199], v141 offset:21504
	ds_read_b128 v[200:203], v141 offset:22528
	ds_read_b128 v[204:207], v141 offset:23552
	global_load_lds_dwordx4 v[208:209], off
	s_add_i32 m0, s96, 0x2000
	s_add_u32 s96, s76, 0x80000
	v_lshl_add_u64 v[210:211], s[76:77], 0, v[122:123]
	s_addc_u32 s97, s77, 0
	s_add_i32 vcc_lo, vcc_lo, s87
	global_load_lds_dwordx4 v[210:211], off
	v_lshl_add_u64 v[212:213], s[96:97], 0, v[0:1]
	s_mov_b32 m0, vcc_lo
	v_lshl_add_u64 v[214:215], s[52:53], 0, v[122:123]
	global_load_lds_dwordx4 v[212:213], off
	v_lshl_add_u64 v[212:213], s[96:97], 0, v[122:123]
	s_add_i32 m0, vcc_lo, 0x2000
	s_nop 0
	global_load_lds_dwordx4 v[212:213], off
	v_lshl_add_u64 v[212:213], s[52:53], 0, v[0:1]
	s_mov_b32 m0, s35
	s_nop 0
	global_load_lds_dwordx4 v[212:213], off
	s_mov_b32 m0, s28
	s_nop 0
	global_load_lds_dwordx4 v[214:215], off
	s_waitcnt vmcnt(8)
	s_waitcnt lgkmcnt(0)
	s_barrier
; #define PG8_STAGE(bufoff, gbase, voff) do { _Pragma("unroll") for (int _i = 0; _i < 2; ++_i) \
;         __builtin_amdgcn_global_load_lds((const unsigned*)((const char*)(gbase) + (voff)[_i]), (LAS unsigned*)(lds + (bufoff) + ldsw + _i * 8192), 16, 0, 0); } while (0)
; #define PG8_LDA(dst, b, h) do { _Pragma("unroll") for (int m = 0; m < 4; ++m) _Pragma("unroll") for (int k = 0; k < 2; ++k) dst[m][k] = *(const LAS bf16x8*)(lds + PG8_SA(b, h) + aoff + m * 2048 + k * 1024); } while (0)
; #define PG8_LDB(dst, b, h) do { _Pragma("unroll") for (int n = 0; n < 2; ++n) _Pragma("unroll") for (int k = 0; k < 2; ++k) dst[n][k] = *(const LAS bf16x8*)(lds + PG8_SB(b, h) + boff + n * 2048 + k * 1024); } while (0)
; #define PG8_MMA(ai, bj, At, Bt) do { __builtin_amdgcn_s_setprio(1); _Pragma("unroll") for (int m = 0; m < 4; ++m) _Pragma("unroll") for (int n = 0; n < 2; ++n) _Pragma("unroll") for (int k = 0; k < 2; ++k) \
;         acc[ai][bj][m][n] = __builtin_amdgcn_mfma_f32_16x16x32_bf16(Bt[n][k], At[m][k], acc[ai][bj][m][n], 0, 0, 0); __builtin_amdgcn_s_setprio(0); } while (0)
; #define PG8_WAIT_V(n) asm volatile("s_waitcnt vmcnt(" #n ")" ::: "memory")
; #define PG8_WAIT_L(n) asm volatile("s_waitcnt lgkmcnt(" #n ")" ::: "memory")
; #define PG8_BAR __builtin_amdgcn_s_barrier()
; #define PG8_SCHED __builtin_amdgcn_sched_barrier(0)
; template <class Epi, class Sched, bool ALIGN_EPI, bool LAST_FUSED = false, bool PERM = false, bool CARRY = false>
; __device__ __forceinline__ void gemm_phase(LAS unsigned char* lds, const int tid, const int K, const int lda, const int ldb, const Sched& S, const Epi& E) {
;     ...
;             PG8_WAIT_V(8); PG8_WAIT_L(0); PG8_BAR; PG8_MMA(1, 0, At, B0); PG8_MMA(1, 1, At, B1); PG8_BAR; PG8_SCHED;
;             PG8_LDB(B0, 1, 0); PG8_LDB(B1, 1, 1); PG8_SCHED; PG8_LDA(At, 1, 0); PG8_STAGE(PG8_SA(0, 1), a2 + hstepA, voffA);
;             PG8_WAIT_V(8); PG8_WAIT_L(0); PG8_BAR; PG8_MMA(0, 0, At, B0); PG8_MMA(0, 1, At, B1); PG8_BAR; PG8_SCHED;
	s_setprio 1
	s_waitcnt lgkmcnt(0)
	v_mfma_f32_16x16x32_bf16 v[78:81], v[142:145], v[176:179], v[78:81]
	v_mfma_f32_16x16x32_bf16 v[74:77], v[150:153], v[176:179], v[74:77]
	v_mfma_f32_16x16x32_bf16 v[98:101], v[142:145], v[184:187], v[98:101]
	v_mfma_f32_16x16x32_bf16 v[94:97], v[150:153], v[184:187], v[94:97]
	v_mfma_f32_16x16x32_bf16 v[118:121], v[142:145], v[192:195], v[118:121]
	v_mfma_f32_16x16x32_bf16 v[114:117], v[150:153], v[192:195], v[114:117]
	v_mfma_f32_16x16x32_bf16 v[134:137], v[142:145], v[200:203], v[134:137]
	v_mfma_f32_16x16x32_bf16 v[130:133], v[150:153], v[200:203], v[130:133]
	v_mfma_f32_16x16x32_bf16 v[78:81], v[146:149], v[180:183], v[78:81]
	v_mfma_f32_16x16x32_bf16 v[74:77], v[156:159], v[180:183], v[74:77]
	v_mfma_f32_16x16x32_bf16 v[98:101], v[146:149], v[188:191], v[98:101]
	v_mfma_f32_16x16x32_bf16 v[94:97], v[156:159], v[188:191], v[94:97]
	v_mfma_f32_16x16x32_bf16 v[118:121], v[146:149], v[196:199], v[118:121]
	v_mfma_f32_16x16x32_bf16 v[114:117], v[156:159], v[196:199], v[114:117]
	v_mfma_f32_16x16x32_bf16 v[134:137], v[146:149], v[204:207], v[134:137]
	v_mfma_f32_16x16x32_bf16 v[130:133], v[156:159], v[204:207], v[130:133]
	v_mfma_f32_16x16x32_bf16 v[70:73], v[160:163], v[176:179], v[70:73]
	v_mfma_f32_16x16x32_bf16 v[66:69], v[168:171], v[176:179], v[66:69]
	v_mfma_f32_16x16x32_bf16 v[90:93], v[160:163], v[184:187], v[90:93]
	v_mfma_f32_16x16x32_bf16 v[86:89], v[168:171], v[184:187], v[86:89]
	v_mfma_f32_16x16x32_bf16 v[110:113], v[160:163], v[192:195], v[110:113]
	v_mfma_f32_16x16x32_bf16 v[106:109], v[168:171], v[192:195], v[106:109]
	v_mfma_f32_16x16x32_bf16 v[102:105], v[160:163], v[200:203], v[102:105]
	v_mfma_f32_16x16x32_bf16 v[82:85], v[168:171], v[200:203], v[82:85]
	v_mfma_f32_16x16x32_bf16 v[70:73], v[164:167], v[180:183], v[70:73]
	v_mfma_f32_16x16x32_bf16 v[66:69], v[172:175], v[180:183], v[66:69]
	v_mfma_f32_16x16x32_bf16 v[90:93], v[164:167], v[188:191], v[90:93]
	v_mfma_f32_16x16x32_bf16 v[86:89], v[172:175], v[188:191], v[86:89]
	v_mfma_f32_16x16x32_bf16 v[110:113], v[164:167], v[196:199], v[110:113]
	v_mfma_f32_16x16x32_bf16 v[106:109], v[172:175], v[196:199], v[106:109]
	v_mfma_f32_16x16x32_bf16 v[102:105], v[164:167], v[204:207], v[102:105]
	v_mfma_f32_16x16x32_bf16 v[82:85], v[172:175], v[204:207], v[82:85]
	s_setprio 0
	s_barrier
	s_add_i32 s96, 0, 0x18000
	s_add_i32 s97, 0, 0x1c000
	v_add_u32_e32 v156, s96, v140
	v_add_u32_e32 v172, s97, v140
	ds_read_b128 v[142:145], v156
	ds_read_b128 v[146:149], v156 offset:1024
	ds_read_b128 v[150:153], v156 offset:2048
	ds_read_b128 v[156:159], v156 offset:3072
	ds_read_b128 v[160:163], v172
	ds_read_b128 v[164:167], v172 offset:1024
	ds_read_b128 v[168:171], v172 offset:2048
	ds_read_b128 v[172:175], v172 offset:3072
	s_add_u32 s52, s52, 0x80000
	s_addc_u32 s53, s53, 0
	s_mov_b32 m0, s29
	v_lshl_add_u64 v[216:217], s[52:53], 0, v[0:1]
	ds_read_b128 v[176:179], v141 offset:32768
	ds_read_b128 v[180:183], v141 offset:33792
	ds_read_b128 v[184:187], v141 offset:34816
	ds_read_b128 v[188:191], v141 offset:35840
	ds_read_b128 v[192:195], v141 offset:36864
	ds_read_b128 v[196:199], v141 offset:37888
	ds_read_b128 v[200:203], v141 offset:38912
	ds_read_b128 v[204:207], v141 offset:39936
	global_load_lds_dwordx4 v[216:217], off
	v_lshl_add_u64 v[216:217], s[52:53], 0, v[122:123]
	s_mov_b32 m0, s14
	s_nop 0
	global_load_lds_dwordx4 v[216:217], off
	s_waitcnt vmcnt(8)
	s_waitcnt lgkmcnt(0)
	s_barrier
	s_setprio 1
	s_waitcnt lgkmcnt(0)
	v_mfma_f32_16x16x32_bf16 v[62:65], v[142:145], v[176:179], v[62:65]
	v_mfma_f32_16x16x32_bf16 v[42:45], v[150:153], v[176:179], v[42:45]
	v_mfma_f32_16x16x32_bf16 v[18:21], v[142:145], v[184:187], v[18:21]
	v_mfma_f32_16x16x32_bf16 v[14:17], v[150:153], v[184:187], v[14:17]
	v_mfma_f32_16x16x32_bf16 v[38:41], v[142:145], v[192:195], v[38:41]
	v_mfma_f32_16x16x32_bf16 v[30:33], v[150:153], v[192:195], v[30:33]
	v_mfma_f32_16x16x32_bf16 v[58:61], v[142:145], v[200:203], v[58:61]
	v_mfma_f32_16x16x32_bf16 v[54:57], v[150:153], v[200:203], v[54:57]
	v_mfma_f32_16x16x32_bf16 v[62:65], v[146:149], v[180:183], v[62:65]
	v_mfma_f32_16x16x32_bf16 v[42:45], v[156:159], v[180:183], v[42:45]
	v_mfma_f32_16x16x32_bf16 v[18:21], v[146:149], v[188:191], v[18:21]
	v_mfma_f32_16x16x32_bf16 v[14:17], v[156:159], v[188:191], v[14:17]
	v_mfma_f32_16x16x32_bf16 v[38:41], v[146:149], v[196:199], v[38:41]
	v_mfma_f32_16x16x32_bf16 v[30:33], v[156:159], v[196:199], v[30:33]
	v_mfma_f32_16x16x32_bf16 v[58:61], v[146:149], v[204:207], v[58:61]
	v_mfma_f32_16x16x32_bf16 v[54:57], v[156:159], v[204:207], v[54:57]
	v_mfma_f32_16x16x32_bf16 v[34:37], v[160:163], v[176:179], v[34:37]
	v_mfma_f32_16x16x32_bf16 v[2:5], v[168:171], v[176:179], v[2:5]
	v_mfma_f32_16x16x32_bf16 v[10:13], v[160:163], v[184:187], v[10:13]
	v_mfma_f32_16x16x32_bf16 v[6:9], v[168:171], v[184:187], v[6:9]
	v_mfma_f32_16x16x32_bf16 v[26:29], v[160:163], v[192:195], v[26:29]
	v_mfma_f32_16x16x32_bf16 v[22:25], v[168:171], v[192:195], v[22:25]
	v_mfma_f32_16x16x32_bf16 v[50:53], v[160:163], v[200:203], v[50:53]
	v_mfma_f32_16x16x32_bf16 v[46:49], v[168:171], v[200:203], v[46:49]
	v_mfma_f32_16x16x32_bf16 v[34:37], v[164:167], v[180:183], v[34:37]
	v_mfma_f32_16x16x32_bf16 v[2:5], v[172:175], v[180:183], v[2:5]
	v_mfma_f32_16x16x32_bf16 v[10:13], v[164:167], v[188:191], v[10:13]
	v_mfma_f32_16x16x32_bf16 v[6:9], v[172:175], v[188:191], v[6:9]
	v_mfma_f32_16x16x32_bf16 v[26:29], v[164:167], v[196:199], v[26:29]
	v_mfma_f32_16x16x32_bf16 v[22:25], v[172:175], v[196:199], v[22:25]
	v_mfma_f32_16x16x32_bf16 v[50:53], v[164:167], v[204:207], v[50:53]
	v_mfma_f32_16x16x32_bf16 v[46:49], v[172:175], v[204:207], v[46:49]
	s_setprio 0
	s_barrier
; #define PG8_STAGE(bufoff, gbase, voff) do { _Pragma("unroll") for (int _i = 0; _i < 2; ++_i) \
;         __builtin_amdgcn_global_load_lds((const unsigned*)((const char*)(gbase) + (voff)[_i]), (LAS unsigned*)(lds + (bufoff) + ldsw + _i * 8192), 16, 0, 0); } while (0)
; #define PG8_LDA(dst, b, h) do { _Pragma("unroll") for (int m = 0; m < 4; ++m) _Pragma("unroll") for (int k = 0; k < 2; ++k) dst[m][k] = *(const LAS bf16x8*)(lds + PG8_SA(b, h) + aoff + m * 2048 + k * 1024); } while (0)
; #define PG8_MMA(ai, bj, At, Bt) do { __builtin_amdgcn_s_setprio(1); _Pragma("unroll") for (int m = 0; m < 4; ++m) _Pragma("unroll") for (int n = 0; n < 2; ++n) _Pragma("unroll") for (int k = 0; k < 2; ++k) \
;         acc[ai][bj][m][n] = __builtin_amdgcn_mfma_f32_16x16x32_bf16(Bt[n][k], At[m][k], acc[ai][bj][m][n], 0, 0, 0); __builtin_amdgcn_s_setprio(0); } while (0)
; #define PG8_WAIT_V(n) asm volatile("s_waitcnt vmcnt(" #n ")" ::: "memory")
; #define PG8_WAIT_L(n) asm volatile("s_waitcnt lgkmcnt(" #n ")" ::: "memory")
; #define PG8_BAR __builtin_amdgcn_s_barrier()
; #define PG8_SCHED __builtin_amdgcn_sched_barrier(0)
; template <class Epi, class Sched, bool ALIGN_EPI, bool LAST_FUSED = false, bool PERM = false, bool CARRY = false>
; __device__ __forceinline__ void gemm_phase(LAS unsigned char* lds, const int tid, const int K, const int lda, const int ldb, const Sched& S, const Epi& E) {
;     ...
;             PG8_LDA(At, 1, 1); PG8_STAGE(PG8_SB(1, 0), b3, voffB); PG8_STAGE(PG8_SB(1, 1), b3 + hstepB, voffB); PG8_STAGE(PG8_SA(1, 0), a3, voffA);
;             PG8_WAIT_V(8); PG8_WAIT_L(0); PG8_BAR; PG8_MMA(1, 0, At, B0); PG8_MMA(1, 1, At, B1); PG8_BAR; PG8_SCHED;
;         }
;         if constexpr (ALIGN_EPI) { if (wr == 0) PG8_BAR; }
	s_add_i32 s52, s96, s87
	v_lshl_add_u64 v[208:209], v[208:209], 0, s[68:69]
	s_mov_b32 m0, s52
	ds_read_b128 v[176:179], v141 offset:49152
	ds_read_b128 v[180:183], v141 offset:50176
	ds_read_b128 v[184:187], v141 offset:51200
	ds_read_b128 v[188:191], v141 offset:52224
	ds_read_b128 v[192:195], v141 offset:53248
	ds_read_b128 v[196:199], v141 offset:54272
	ds_read_b128 v[200:203], v141 offset:55296
	ds_read_b128 v[204:207], v141 offset:56320
	global_load_lds_dwordx4 v[208:209], off
	s_add_i32 m0, s52, 0x2000
	s_add_u32 s52, s76, 0x80080
	v_lshl_add_u64 v[208:209], v[210:211], 0, s[68:69]
	s_addc_u32 s53, s77, 0
	s_add_i32 s76, s97, s87
	global_load_lds_dwordx4 v[208:209], off
	v_lshl_add_u64 v[208:209], s[52:53], 0, v[0:1]
	s_mov_b32 m0, s76
	s_nop 0
	global_load_lds_dwordx4 v[208:209], off
	v_lshl_add_u64 v[208:209], s[52:53], 0, v[122:123]
	s_add_i32 m0, s76, 0x2000
	s_nop 0
	global_load_lds_dwordx4 v[208:209], off
	v_lshl_add_u64 v[208:209], v[212:213], 0, s[68:69]
	s_mov_b32 m0, s85
	s_nop 0
	global_load_lds_dwordx4 v[208:209], off
	v_lshl_add_u64 v[208:209], v[214:215], 0, s[68:69]
	s_mov_b32 m0, s89
	s_nop 0
	global_load_lds_dwordx4 v[208:209], off
	s_waitcnt vmcnt(8)
	s_waitcnt lgkmcnt(0)
	s_barrier
	s_setprio 1
	s_waitcnt lgkmcnt(0)
	v_mfma_f32_16x16x32_bf16 v[78:81], v[142:145], v[176:179], v[78:81]
	v_mfma_f32_16x16x32_bf16 v[74:77], v[150:153], v[176:179], v[74:77]
	v_mfma_f32_16x16x32_bf16 v[98:101], v[142:145], v[184:187], v[98:101]
	v_mfma_f32_16x16x32_bf16 v[94:97], v[150:153], v[184:187], v[94:97]
	v_mfma_f32_16x16x32_bf16 v[118:121], v[142:145], v[192:195], v[118:121]
	v_mfma_f32_16x16x32_bf16 v[114:117], v[150:153], v[192:195], v[114:117]
	v_mfma_f32_16x16x32_bf16 v[134:137], v[142:145], v[200:203], v[134:137]
	v_mfma_f32_16x16x32_bf16 v[130:133], v[150:153], v[200:203], v[130:133]
	v_mfma_f32_16x16x32_bf16 v[78:81], v[146:149], v[180:183], v[78:81]
	v_mfma_f32_16x16x32_bf16 v[74:77], v[156:159], v[180:183], v[74:77]
	v_mfma_f32_16x16x32_bf16 v[98:101], v[146:149], v[188:191], v[98:101]
	v_mfma_f32_16x16x32_bf16 v[94:97], v[156:159], v[188:191], v[94:97]
	v_mfma_f32_16x16x32_bf16 v[118:121], v[146:149], v[196:199], v[118:121]
	v_mfma_f32_16x16x32_bf16 v[114:117], v[156:159], v[196:199], v[114:117]
	v_mfma_f32_16x16x32_bf16 v[134:137], v[146:149], v[204:207], v[134:137]
	v_mfma_f32_16x16x32_bf16 v[130:133], v[156:159], v[204:207], v[130:133]
	v_mfma_f32_16x16x32_bf16 v[70:73], v[160:163], v[176:179], v[70:73]
	v_mfma_f32_16x16x32_bf16 v[66:69], v[168:171], v[176:179], v[66:69]
	v_mfma_f32_16x16x32_bf16 v[90:93], v[160:163], v[184:187], v[90:93]
	v_mfma_f32_16x16x32_bf16 v[86:89], v[168:171], v[184:187], v[86:89]
	v_mfma_f32_16x16x32_bf16 v[110:113], v[160:163], v[192:195], v[110:113]
	v_mfma_f32_16x16x32_bf16 v[106:109], v[168:171], v[192:195], v[106:109]
	v_mfma_f32_16x16x32_bf16 v[102:105], v[160:163], v[200:203], v[102:105]
	v_mfma_f32_16x16x32_bf16 v[82:85], v[168:171], v[200:203], v[82:85]
	v_mfma_f32_16x16x32_bf16 v[70:73], v[164:167], v[180:183], v[70:73]
	v_mfma_f32_16x16x32_bf16 v[66:69], v[172:175], v[180:183], v[66:69]
	v_mfma_f32_16x16x32_bf16 v[90:93], v[164:167], v[188:191], v[90:93]
	v_mfma_f32_16x16x32_bf16 v[86:89], v[172:175], v[188:191], v[86:89]
	v_mfma_f32_16x16x32_bf16 v[110:113], v[164:167], v[196:199], v[110:113]
	v_mfma_f32_16x16x32_bf16 v[106:109], v[172:175], v[196:199], v[106:109]
	v_mfma_f32_16x16x32_bf16 v[102:105], v[164:167], v[204:207], v[102:105]
	v_mfma_f32_16x16x32_bf16 v[82:85], v[172:175], v[204:207], v[82:85]
	s_setprio 0
	s_barrier
	s_add_i32 s52, s95, 2
	s_add_u32 s48, s48, 0x100
	s_addc_u32 s49, s49, 0
	v_lshl_add_u64 v[138:139], v[138:139], 0, s[72:73]
	v_lshl_add_u64 v[128:129], v[128:129], 0, s[72:73]
	s_cmp_ge_i32 s95, s3
	s_mov_b32 s95, s52
	s_cbranch_scc0 .LBB0_1585
	s_and_b64 vcc, exec, s[36:37]
	s_cbranch_vccz .LBB0_1588
	s_barrier

; #define PG8_STAGE(bufoff, gbase, voff) do { _Pragma("unroll") for (int _i = 0; _i < 2; ++_i) \
;         __builtin_amdgcn_global_load_lds((const unsigned*)((const char*)(gbase) + (voff)[_i]), (LAS unsigned*)(lds + (bufoff) + ldsw + _i * 8192), 16, 0, 0); } while (0)
; #define PG8_LDA(dst, b, h) do { _Pragma("unroll") for (int m = 0; m < 4; ++m) _Pragma("unroll") for (int k = 0; k < 2; ++k) dst[m][k] = *(const LAS bf16x8*)(lds + PG8_SA(b, h) + aoff + m * 2048 + k * 1024); } while (0)
; #define PG8_LDB(dst, b, h) do { _Pragma("unroll") for (int n = 0; n < 2; ++n) _Pragma("unroll") for (int k = 0; k < 2; ++k) dst[n][k] = *(const LAS bf16x8*)(lds + PG8_SB(b, h) + boff + n * 2048 + k * 1024); } while (0)
; #define PG8_MMA(ai, bj, At, Bt) do { __builtin_amdgcn_s_setprio(1); _Pragma("unroll") for (int m = 0; m < 4; ++m) _Pragma("unroll") for (int n = 0; n < 2; ++n) _Pragma("unroll") for (int k = 0; k < 2; ++k) \
;         acc[ai][bj][m][n] = __builtin_amdgcn_mfma_f32_16x16x32_bf16(Bt[n][k], At[m][k], acc[ai][bj][m][n], 0, 0, 0); __builtin_amdgcn_s_setprio(0); } while (0)
; #define PG8_WAIT_V(n) asm volatile("s_waitcnt vmcnt(" #n ")" ::: "memory")
; #define PG8_WAIT_L(n) asm volatile("s_waitcnt lgkmcnt(" #n ")" ::: "memory")
; template <class Epi, class Sched, bool ALIGN_EPI, bool LAST_FUSED = false, bool PERM = false, bool CARRY = false>
; __device__ __forceinline__ void gemm_phase(LAS unsigned char* lds, const int tid, const int K, const int lda, const int ldb, const Sched& S, const Epi& E) {
;     ...
;         for (int t = 0; t < nt; t += 2) {
;             const bool last = (t == nt - 2);
;             const char* a1 = cA + (size_t)(t + 1) * kstep;
;             const char* a2 = last ? nA : cA + (size_t)(t + 2) * kstep; const char* b2 = last ? nB : cB + (size_t)(t + 2) * kstep;
;             const char* a3 = a2 + kstep; const char* b3 = b2 + kstep;
;             PG8_LDB(B0, 0, 0); PG8_LDB(B1, 0, 1); PG8_SCHED; PG8_LDA(At, 0, 0); PG8_STAGE(PG8_SA(1, 1), a1 + hstepA, voffA);
;             PG8_WAIT_V(8); PG8_WAIT_L(0); PG8_BAR; PG8_MMA(0, 0, At, B0); PG8_MMA(0, 1, At, B1); PG8_BAR; PG8_SCHED;
;             PG8_LDA(At, 0, 1); PG8_STAGE(PG8_SB(0, 0), b2, voffB); PG8_STAGE(PG8_SB(0, 1), b2 + hstepB, voffB); PG8_STAGE(PG8_SA(0, 0), a2, voffA);
;             PG8_WAIT_V(8); PG8_WAIT_L(0); PG8_BAR; PG8_MMA(1, 0, At, B0); PG8_MMA(1, 1, At, B1); PG8_BAR; PG8_SCHED;
.LBB0_1662:
	s_add_u32 s52, s38, s48
	s_addc_u32 s53, s39, s49
	s_add_u32 s66, s40, s48
	s_addc_u32 s67, s41, s49
	s_waitcnt lgkmcnt(0)
	s_add_i32 s90, 0, 0x10000
	s_cmp_eq_u32 s3, s89
	s_cselect_b32 s53, s24, s53
	s_cselect_b32 s52, s85, s52
	s_cselect_b32 s67, s86, s67
	s_cselect_b32 s66, s87, s66
	s_add_i32 s92, 0, 0x14000
	v_add_u32_e32 v156, s90, v140
	v_add_u32_e32 v172, s92, v140
	ds_read_b128 v[142:145], v156
	ds_read_b128 v[146:149], v156 offset:1024
	ds_read_b128 v[150:153], v156 offset:2048
	ds_read_b128 v[156:159], v156 offset:3072
	ds_read_b128 v[160:163], v172
	ds_read_b128 v[164:167], v172 offset:1024
	ds_read_b128 v[168:171], v172 offset:2048
	ds_read_b128 v[172:175], v172 offset:3072
	v_lshl_add_u64 v[208:209], s[38:39], 0, v[138:139]
	s_add_i32 m0, s35, 0xc000
	ds_read_b128 v[176:179], v141
	ds_read_b128 v[180:183], v141 offset:1024
	ds_read_b128 v[184:187], v141 offset:2048
	ds_read_b128 v[188:191], v141 offset:3072
	ds_read_b128 v[192:195], v141 offset:4096
	ds_read_b128 v[196:199], v141 offset:5120
	ds_read_b128 v[200:203], v141 offset:6144
	ds_read_b128 v[204:207], v141 offset:7168
	global_load_lds_dwordx4 v[208:209], off
	v_lshl_add_u64 v[208:209], s[38:39], 0, v[128:129]
	s_add_i32 m0, s35, 0xe000
	s_nop 0
	global_load_lds_dwordx4 v[208:209], off
	s_waitcnt vmcnt(8)
	s_waitcnt lgkmcnt(0)
	s_barrier
	s_setprio 1
	s_waitcnt lgkmcnt(0)
	v_mfma_f32_16x16x32_bf16 v[62:65], v[142:145], v[176:179], v[62:65]
	v_mfma_f32_16x16x32_bf16 v[42:45], v[150:153], v[176:179], v[42:45]
	v_mfma_f32_16x16x32_bf16 v[18:21], v[142:145], v[184:187], v[18:21]
	v_mfma_f32_16x16x32_bf16 v[14:17], v[150:153], v[184:187], v[14:17]
	v_mfma_f32_16x16x32_bf16 v[38:41], v[142:145], v[192:195], v[38:41]
	v_mfma_f32_16x16x32_bf16 v[30:33], v[150:153], v[192:195], v[30:33]
	v_mfma_f32_16x16x32_bf16 v[58:61], v[142:145], v[200:203], v[58:61]
	v_mfma_f32_16x16x32_bf16 v[54:57], v[150:153], v[200:203], v[54:57]
	v_mfma_f32_16x16x32_bf16 v[62:65], v[146:149], v[180:183], v[62:65]
	v_mfma_f32_16x16x32_bf16 v[42:45], v[156:159], v[180:183], v[42:45]
	v_mfma_f32_16x16x32_bf16 v[18:21], v[146:149], v[188:191], v[18:21]
	v_mfma_f32_16x16x32_bf16 v[14:17], v[156:159], v[188:191], v[14:17]
	v_mfma_f32_16x16x32_bf16 v[38:41], v[146:149], v[196:199], v[38:41]
	v_mfma_f32_16x16x32_bf16 v[30:33], v[156:159], v[196:199], v[30:33]
	v_mfma_f32_16x16x32_bf16 v[58:61], v[146:149], v[204:207], v[58:61]
	v_mfma_f32_16x16x32_bf16 v[54:57], v[156:159], v[204:207], v[54:57]
	v_mfma_f32_16x16x32_bf16 v[34:37], v[160:163], v[176:179], v[34:37]
	v_mfma_f32_16x16x32_bf16 v[2:5], v[168:171], v[176:179], v[2:5]
	v_mfma_f32_16x16x32_bf16 v[10:13], v[160:163], v[184:187], v[10:13]
	v_mfma_f32_16x16x32_bf16 v[6:9], v[168:171], v[184:187], v[6:9]
	v_mfma_f32_16x16x32_bf16 v[26:29], v[160:163], v[192:195], v[26:29]
	v_mfma_f32_16x16x32_bf16 v[22:25], v[168:171], v[192:195], v[22:25]
	v_mfma_f32_16x16x32_bf16 v[50:53], v[160:163], v[200:203], v[50:53]
	v_mfma_f32_16x16x32_bf16 v[46:49], v[168:171], v[200:203], v[46:49]
	v_mfma_f32_16x16x32_bf16 v[34:37], v[164:167], v[180:183], v[34:37]
	v_mfma_f32_16x16x32_bf16 v[2:5], v[172:175], v[180:183], v[2:5]
	v_mfma_f32_16x16x32_bf16 v[10:13], v[164:167], v[188:191], v[10:13]
	v_mfma_f32_16x16x32_bf16 v[6:9], v[172:175], v[188:191], v[6:9]
	v_mfma_f32_16x16x32_bf16 v[26:29], v[164:167], v[196:199], v[26:29]
	v_mfma_f32_16x16x32_bf16 v[22:25], v[172:175], v[196:199], v[22:25]
	v_mfma_f32_16x16x32_bf16 v[50:53], v[164:167], v[204:207], v[50:53]
	v_mfma_f32_16x16x32_bf16 v[46:49], v[172:175], v[204:207], v[46:49]
	s_setprio 0
	s_barrier
	s_add_i32 s90, s90, s76
	v_lshl_add_u64 v[208:209], s[66:67], 0, v[0:1]
	s_mov_b32 m0, s90
	ds_read_b128 v[176:179], v141 offset:16384
	ds_read_b128 v[180:183], v141 offset:17408
	ds_read_b128 v[184:187], v141 offset:18432
	ds_read_b128 v[188:191], v141 offset:19456
	ds_read_b128 v[192:195], v141 offset:20480
	ds_read_b128 v[196:199], v141 offset:21504
	ds_read_b128 v[200:203], v141 offset:22528
	ds_read_b128 v[204:207], v141 offset:23552
	global_load_lds_dwordx4 v[208:209], off
	s_add_i32 m0, s90, 0x2000
	s_add_u32 s90, s66, 0x100000
	v_lshl_add_u64 v[210:211], s[66:67], 0, v[122:123]
	s_addc_u32 s91, s67, 0
	s_add_i32 s92, s92, s76
	global_load_lds_dwordx4 v[210:211], off
	v_lshl_add_u64 v[212:213], s[90:91], 0, v[0:1]
	s_mov_b32 m0, s92
	v_lshl_add_u64 v[214:215], s[52:53], 0, v[122:123]
	global_load_lds_dwordx4 v[212:213], off
	v_lshl_add_u64 v[212:213], s[90:91], 0, v[122:123]
	s_add_i32 m0, s92, 0x2000
	s_nop 0
	global_load_lds_dwordx4 v[212:213], off
	v_lshl_add_u64 v[212:213], s[52:53], 0, v[0:1]
	s_mov_b32 m0, s35
	s_nop 0
	global_load_lds_dwordx4 v[212:213], off
	s_mov_b32 m0, s28
	s_nop 0
	global_load_lds_dwordx4 v[214:215], off
	s_waitcnt vmcnt(8)
	s_waitcnt lgkmcnt(0)
	s_barrier
; #define PG8_STAGE(bufoff, gbase, voff) do { _Pragma("unroll") for (int _i = 0; _i < 2; ++_i) \
;         __builtin_amdgcn_global_load_lds((const unsigned*)((const char*)(gbase) + (voff)[_i]), (LAS unsigned*)(lds + (bufoff) + ldsw + _i * 8192), 16, 0, 0); } while (0)
; #define PG8_LDA(dst, b, h) do { _Pragma("unroll") for (int m = 0; m < 4; ++m) _Pragma("unroll") for (int k = 0; k < 2; ++k) dst[m][k] = *(const LAS bf16x8*)(lds + PG8_SA(b, h) + aoff + m * 2048 + k * 1024); } while (0)
; #define PG8_LDB(dst, b, h) do { _Pragma("unroll") for (int n = 0; n < 2; ++n) _Pragma("unroll") for (int k = 0; k < 2; ++k) dst[n][k] = *(const LAS bf16x8*)(lds + PG8_SB(b, h) + boff + n * 2048 + k * 1024); } while (0)
; #define PG8_MMA(ai, bj, At, Bt) do { __builtin_amdgcn_s_setprio(1); _Pragma("unroll") for (int m = 0; m < 4; ++m) _Pragma("unroll") for (int n = 0; n < 2; ++n) _Pragma("unroll") for (int k = 0; k < 2; ++k) \
;         acc[ai][bj][m][n] = __builtin_amdgcn_mfma_f32_16x16x32_bf16(Bt[n][k], At[m][k], acc[ai][bj][m][n], 0, 0, 0); __builtin_amdgcn_s_setprio(0); } while (0)
; #define PG8_WAIT_V(n) asm volatile("s_waitcnt vmcnt(" #n ")" ::: "memory")
; #define PG8_WAIT_L(n) asm volatile("s_waitcnt lgkmcnt(" #n ")" ::: "memory")
; #define PG8_BAR __builtin_amdgcn_s_barrier()
; #define PG8_SCHED __builtin_amdgcn_sched_barrier(0)
; template <class Epi, class Sched, bool ALIGN_EPI, bool LAST_FUSED = false, bool PERM = false, bool CARRY = false>
; __device__ __forceinline__ void gemm_phase(LAS unsigned char* lds, const int tid, const int K, const int lda, const int ldb, const Sched& S, const Epi& E) {
;     ...
;             PG8_WAIT_V(8); PG8_WAIT_L(0); PG8_BAR; PG8_MMA(1, 0, At, B0); PG8_MMA(1, 1, At, B1); PG8_BAR; PG8_SCHED;
;             PG8_LDB(B0, 1, 0); PG8_LDB(B1, 1, 1); PG8_SCHED; PG8_LDA(At, 1, 0); PG8_STAGE(PG8_SA(0, 1), a2 + hstepA, voffA);
;             PG8_WAIT_V(8); PG8_WAIT_L(0); PG8_BAR; PG8_MMA(0, 0, At, B0); PG8_MMA(0, 1, At, B1); PG8_BAR; PG8_SCHED;
	s_setprio 1
	s_waitcnt lgkmcnt(0)
	v_mfma_f32_16x16x32_bf16 v[78:81], v[142:145], v[176:179], v[78:81]
	v_mfma_f32_16x16x32_bf16 v[74:77], v[150:153], v[176:179], v[74:77]
	v_mfma_f32_16x16x32_bf16 v[98:101], v[142:145], v[184:187], v[98:101]
	v_mfma_f32_16x16x32_bf16 v[94:97], v[150:153], v[184:187], v[94:97]
	v_mfma_f32_16x16x32_bf16 v[118:121], v[142:145], v[192:195], v[118:121]
	v_mfma_f32_16x16x32_bf16 v[114:117], v[150:153], v[192:195], v[114:117]
	v_mfma_f32_16x16x32_bf16 v[134:137], v[142:145], v[200:203], v[134:137]
	v_mfma_f32_16x16x32_bf16 v[130:133], v[150:153], v[200:203], v[130:133]
	v_mfma_f32_16x16x32_bf16 v[78:81], v[146:149], v[180:183], v[78:81]
	v_mfma_f32_16x16x32_bf16 v[74:77], v[156:159], v[180:183], v[74:77]
	v_mfma_f32_16x16x32_bf16 v[98:101], v[146:149], v[188:191], v[98:101]
	v_mfma_f32_16x16x32_bf16 v[94:97], v[156:159], v[188:191], v[94:97]
	v_mfma_f32_16x16x32_bf16 v[118:121], v[146:149], v[196:199], v[118:121]
	v_mfma_f32_16x16x32_bf16 v[114:117], v[156:159], v[196:199], v[114:117]
	v_mfma_f32_16x16x32_bf16 v[134:137], v[146:149], v[204:207], v[134:137]
	v_mfma_f32_16x16x32_bf16 v[130:133], v[156:159], v[204:207], v[130:133]
	v_mfma_f32_16x16x32_bf16 v[70:73], v[160:163], v[176:179], v[70:73]
	v_mfma_f32_16x16x32_bf16 v[66:69], v[168:171], v[176:179], v[66:69]
	v_mfma_f32_16x16x32_bf16 v[90:93], v[160:163], v[184:187], v[90:93]
	v_mfma_f32_16x16x32_bf16 v[86:89], v[168:171], v[184:187], v[86:89]
	v_mfma_f32_16x16x32_bf16 v[110:113], v[160:163], v[192:195], v[110:113]
	v_mfma_f32_16x16x32_bf16 v[106:109], v[168:171], v[192:195], v[106:109]
	v_mfma_f32_16x16x32_bf16 v[102:105], v[160:163], v[200:203], v[102:105]
	v_mfma_f32_16x16x32_bf16 v[82:85], v[168:171], v[200:203], v[82:85]
	v_mfma_f32_16x16x32_bf16 v[70:73], v[164:167], v[180:183], v[70:73]
	v_mfma_f32_16x16x32_bf16 v[66:69], v[172:175], v[180:183], v[66:69]
	v_mfma_f32_16x16x32_bf16 v[90:93], v[164:167], v[188:191], v[90:93]
	v_mfma_f32_16x16x32_bf16 v[86:89], v[172:175], v[188:191], v[86:89]
	v_mfma_f32_16x16x32_bf16 v[110:113], v[164:167], v[196:199], v[110:113]
	v_mfma_f32_16x16x32_bf16 v[106:109], v[172:175], v[196:199], v[106:109]
	v_mfma_f32_16x16x32_bf16 v[102:105], v[164:167], v[204:207], v[102:105]
	v_mfma_f32_16x16x32_bf16 v[82:85], v[172:175], v[204:207], v[82:85]
	s_setprio 0
	s_barrier
	s_add_i32 s90, 0, 0x18000
	s_add_i32 s91, 0, 0x1c000
	v_add_u32_e32 v156, s90, v140
	v_add_u32_e32 v172, s91, v140
	ds_read_b128 v[142:145], v156
	ds_read_b128 v[146:149], v156 offset:1024
	ds_read_b128 v[150:153], v156 offset:2048
	ds_read_b128 v[156:159], v156 offset:3072
	ds_read_b128 v[160:163], v172
	ds_read_b128 v[164:167], v172 offset:1024
	ds_read_b128 v[168:171], v172 offset:2048
	ds_read_b128 v[172:175], v172 offset:3072
	s_add_u32 s52, s52, 0x100000
	s_addc_u32 s53, s53, 0
	s_mov_b32 m0, s29
	v_lshl_add_u64 v[216:217], s[52:53], 0, v[0:1]
	ds_read_b128 v[176:179], v141 offset:32768
	ds_read_b128 v[180:183], v141 offset:33792
	ds_read_b128 v[184:187], v141 offset:34816
	ds_read_b128 v[188:191], v141 offset:35840
	ds_read_b128 v[192:195], v141 offset:36864
	ds_read_b128 v[196:199], v141 offset:37888
	ds_read_b128 v[200:203], v141 offset:38912
	ds_read_b128 v[204:207], v141 offset:39936
	global_load_lds_dwordx4 v[216:217], off
	v_lshl_add_u64 v[216:217], s[52:53], 0, v[122:123]
	s_mov_b32 m0, s14
	s_nop 0
	global_load_lds_dwordx4 v[216:217], off
	s_waitcnt vmcnt(8)
	s_waitcnt lgkmcnt(0)
	s_barrier
	s_setprio 1
	s_waitcnt lgkmcnt(0)
	v_mfma_f32_16x16x32_bf16 v[62:65], v[142:145], v[176:179], v[62:65]
	v_mfma_f32_16x16x32_bf16 v[42:45], v[150:153], v[176:179], v[42:45]
	v_mfma_f32_16x16x32_bf16 v[18:21], v[142:145], v[184:187], v[18:21]
	v_mfma_f32_16x16x32_bf16 v[14:17], v[150:153], v[184:187], v[14:17]
	v_mfma_f32_16x16x32_bf16 v[38:41], v[142:145], v[192:195], v[38:41]
	v_mfma_f32_16x16x32_bf16 v[30:33], v[150:153], v[192:195], v[30:33]
	v_mfma_f32_16x16x32_bf16 v[58:61], v[142:145], v[200:203], v[58:61]
	v_mfma_f32_16x16x32_bf16 v[54:57], v[150:153], v[200:203], v[54:57]
	v_mfma_f32_16x16x32_bf16 v[62:65], v[146:149], v[180:183], v[62:65]
	v_mfma_f32_16x16x32_bf16 v[42:45], v[156:159], v[180:183], v[42:45]
	v_mfma_f32_16x16x32_bf16 v[18:21], v[146:149], v[188:191], v[18:21]
	v_mfma_f32_16x16x32_bf16 v[14:17], v[156:159], v[188:191], v[14:17]
	v_mfma_f32_16x16x32_bf16 v[38:41], v[146:149], v[196:199], v[38:41]
	v_mfma_f32_16x16x32_bf16 v[30:33], v[156:159], v[196:199], v[30:33]
	v_mfma_f32_16x16x32_bf16 v[58:61], v[146:149], v[204:207], v[58:61]
	v_mfma_f32_16x16x32_bf16 v[54:57], v[156:159], v[204:207], v[54:57]
	v_mfma_f32_16x16x32_bf16 v[34:37], v[160:163], v[176:179], v[34:37]
	v_mfma_f32_16x16x32_bf16 v[2:5], v[168:171], v[176:179], v[2:5]
	v_mfma_f32_16x16x32_bf16 v[10:13], v[160:163], v[184:187], v[10:13]
	v_mfma_f32_16x16x32_bf16 v[6:9], v[168:171], v[184:187], v[6:9]
	v_mfma_f32_16x16x32_bf16 v[26:29], v[160:163], v[192:195], v[26:29]
	v_mfma_f32_16x16x32_bf16 v[22:25], v[168:171], v[192:195], v[22:25]
	v_mfma_f32_16x16x32_bf16 v[50:53], v[160:163], v[200:203], v[50:53]
	v_mfma_f32_16x16x32_bf16 v[46:49], v[168:171], v[200:203], v[46:49]
	v_mfma_f32_16x16x32_bf16 v[34:37], v[164:167], v[180:183], v[34:37]
	v_mfma_f32_16x16x32_bf16 v[2:5], v[172:175], v[180:183], v[2:5]
	v_mfma_f32_16x16x32_bf16 v[10:13], v[164:167], v[188:191], v[10:13]
	v_mfma_f32_16x16x32_bf16 v[6:9], v[172:175], v[188:191], v[6:9]
	v_mfma_f32_16x16x32_bf16 v[26:29], v[164:167], v[196:199], v[26:29]
	v_mfma_f32_16x16x32_bf16 v[22:25], v[172:175], v[196:199], v[22:25]
	v_mfma_f32_16x16x32_bf16 v[50:53], v[164:167], v[204:207], v[50:53]
	v_mfma_f32_16x16x32_bf16 v[46:49], v[172:175], v[204:207], v[46:49]
	s_setprio 0
	s_barrier
; #define PG8_STAGE(bufoff, gbase, voff) do { _Pragma("unroll") for (int _i = 0; _i < 2; ++_i) \
;         __builtin_amdgcn_global_load_lds((const unsigned*)((const char*)(gbase) + (voff)[_i]), (LAS unsigned*)(lds + (bufoff) + ldsw + _i * 8192), 16, 0, 0); } while (0)
; #define PG8_LDA(dst, b, h) do { _Pragma("unroll") for (int m = 0; m < 4; ++m) _Pragma("unroll") for (int k = 0; k < 2; ++k) dst[m][k] = *(const LAS bf16x8*)(lds + PG8_SA(b, h) + aoff + m * 2048 + k * 1024); } while (0)
; #define PG8_MMA(ai, bj, At, Bt) do { __builtin_amdgcn_s_setprio(1); _Pragma("unroll") for (int m = 0; m < 4; ++m) _Pragma("unroll") for (int n = 0; n < 2; ++n) _Pragma("unroll") for (int k = 0; k < 2; ++k) \
;         acc[ai][bj][m][n] = __builtin_amdgcn_mfma_f32_16x16x32_bf16(Bt[n][k], At[m][k], acc[ai][bj][m][n], 0, 0, 0); __builtin_amdgcn_s_setprio(0); } while (0)
; #define PG8_WAIT_V(n) asm volatile("s_waitcnt vmcnt(" #n ")" ::: "memory")
; #define PG8_WAIT_L(n) asm volatile("s_waitcnt lgkmcnt(" #n ")" ::: "memory")
; #define PG8_BAR __builtin_amdgcn_s_barrier()
; #define PG8_SCHED __builtin_amdgcn_sched_barrier(0)
; template <class Epi, class Sched, bool ALIGN_EPI, bool LAST_FUSED = false, bool PERM = false, bool CARRY = false>
; __device__ __forceinline__ void gemm_phase(LAS unsigned char* lds, const int tid, const int K, const int lda, const int ldb, const Sched& S, const Epi& E) {
;     ...
;             PG8_LDA(At, 1, 1); PG8_STAGE(PG8_SB(1, 0), b3, voffB); PG8_STAGE(PG8_SB(1, 1), b3 + hstepB, voffB); PG8_STAGE(PG8_SA(1, 0), a3, voffA);
;             PG8_WAIT_V(8); PG8_WAIT_L(0); PG8_BAR; PG8_MMA(1, 0, At, B0); PG8_MMA(1, 1, At, B1); PG8_BAR; PG8_SCHED;
;         }
;         if constexpr (ALIGN_EPI) { if (wr == 0) PG8_BAR; }
	s_add_i32 s52, s90, s76
	v_lshl_add_u64 v[208:209], v[208:209], 0, s[68:69]
	s_mov_b32 m0, s52
	ds_read_b128 v[176:179], v141 offset:49152
	ds_read_b128 v[180:183], v141 offset:50176
	ds_read_b128 v[184:187], v141 offset:51200
	ds_read_b128 v[188:191], v141 offset:52224
	ds_read_b128 v[192:195], v141 offset:53248
	ds_read_b128 v[196:199], v141 offset:54272
	ds_read_b128 v[200:203], v141 offset:55296
	ds_read_b128 v[204:207], v141 offset:56320
	global_load_lds_dwordx4 v[208:209], off
	s_add_i32 m0, s52, 0x2000
	s_add_u32 s52, s66, 0x100080
	v_lshl_add_u64 v[208:209], v[210:211], 0, s[68:69]
	s_addc_u32 s53, s67, 0
	s_add_i32 s66, s91, s76
	global_load_lds_dwordx4 v[208:209], off
	v_lshl_add_u64 v[208:209], s[52:53], 0, v[0:1]
	s_mov_b32 m0, s66
	s_nop 0
	global_load_lds_dwordx4 v[208:209], off
	v_lshl_add_u64 v[208:209], s[52:53], 0, v[122:123]
	s_add_i32 m0, s66, 0x2000
	s_nop 0
	global_load_lds_dwordx4 v[208:209], off
	v_lshl_add_u64 v[208:209], v[212:213], 0, s[68:69]
	s_mov_b32 m0, s77
	s_nop 0
	global_load_lds_dwordx4 v[208:209], off
	v_lshl_add_u64 v[208:209], v[214:215], 0, s[68:69]
	s_mov_b32 m0, s79
	s_nop 0
	global_load_lds_dwordx4 v[208:209], off
	s_waitcnt vmcnt(8)
	s_waitcnt lgkmcnt(0)
	s_barrier
	s_setprio 1
	s_waitcnt lgkmcnt(0)
	v_mfma_f32_16x16x32_bf16 v[78:81], v[142:145], v[176:179], v[78:81]
	v_mfma_f32_16x16x32_bf16 v[74:77], v[150:153], v[176:179], v[74:77]
	v_mfma_f32_16x16x32_bf16 v[98:101], v[142:145], v[184:187], v[98:101]
	v_mfma_f32_16x16x32_bf16 v[94:97], v[150:153], v[184:187], v[94:97]
	v_mfma_f32_16x16x32_bf16 v[118:121], v[142:145], v[192:195], v[118:121]
	v_mfma_f32_16x16x32_bf16 v[114:117], v[150:153], v[192:195], v[114:117]
	v_mfma_f32_16x16x32_bf16 v[134:137], v[142:145], v[200:203], v[134:137]
	v_mfma_f32_16x16x32_bf16 v[130:133], v[150:153], v[200:203], v[130:133]
	v_mfma_f32_16x16x32_bf16 v[78:81], v[146:149], v[180:183], v[78:81]
	v_mfma_f32_16x16x32_bf16 v[74:77], v[156:159], v[180:183], v[74:77]
	v_mfma_f32_16x16x32_bf16 v[98:101], v[146:149], v[188:191], v[98:101]
	v_mfma_f32_16x16x32_bf16 v[94:97], v[156:159], v[188:191], v[94:97]
	v_mfma_f32_16x16x32_bf16 v[118:121], v[146:149], v[196:199], v[118:121]
	v_mfma_f32_16x16x32_bf16 v[114:117], v[156:159], v[196:199], v[114:117]
	v_mfma_f32_16x16x32_bf16 v[134:137], v[146:149], v[204:207], v[134:137]
	v_mfma_f32_16x16x32_bf16 v[130:133], v[156:159], v[204:207], v[130:133]
	v_mfma_f32_16x16x32_bf16 v[70:73], v[160:163], v[176:179], v[70:73]
	v_mfma_f32_16x16x32_bf16 v[66:69], v[168:171], v[176:179], v[66:69]
	v_mfma_f32_16x16x32_bf16 v[90:93], v[160:163], v[184:187], v[90:93]
	v_mfma_f32_16x16x32_bf16 v[86:89], v[168:171], v[184:187], v[86:89]
	v_mfma_f32_16x16x32_bf16 v[110:113], v[160:163], v[192:195], v[110:113]
	v_mfma_f32_16x16x32_bf16 v[106:109], v[168:171], v[192:195], v[106:109]
	v_mfma_f32_16x16x32_bf16 v[102:105], v[160:163], v[200:203], v[102:105]
	v_mfma_f32_16x16x32_bf16 v[82:85], v[168:171], v[200:203], v[82:85]
	v_mfma_f32_16x16x32_bf16 v[70:73], v[164:167], v[180:183], v[70:73]
	v_mfma_f32_16x16x32_bf16 v[66:69], v[172:175], v[180:183], v[66:69]
	v_mfma_f32_16x16x32_bf16 v[90:93], v[164:167], v[188:191], v[90:93]
	v_mfma_f32_16x16x32_bf16 v[86:89], v[172:175], v[188:191], v[86:89]
	v_mfma_f32_16x16x32_bf16 v[110:113], v[164:167], v[196:199], v[110:113]
	v_mfma_f32_16x16x32_bf16 v[106:109], v[172:175], v[196:199], v[106:109]
	v_mfma_f32_16x16x32_bf16 v[102:105], v[164:167], v[204:207], v[102:105]
	v_mfma_f32_16x16x32_bf16 v[82:85], v[172:175], v[204:207], v[82:85]
	s_setprio 0
	s_barrier
	s_add_i32 s52, s89, 2
	s_add_u32 s48, s48, 0x100
	s_addc_u32 s49, s49, 0
	v_lshl_add_u64 v[138:139], v[138:139], 0, s[72:73]
	v_lshl_add_u64 v[128:129], v[128:129], 0, s[72:73]
	s_cmp_ge_i32 s89, s3
	s_mov_b32 s89, s52
	s_cbranch_scc0 .LBB0_1662
	s_and_b64 vcc, exec, s[36:37]
	s_cbranch_vccz .LBB0_1665
	s_barrier

; #define PG8_STAGE(bufoff, gbase, voff) do { _Pragma("unroll") for (int _i = 0; _i < 2; ++_i) \
;         __builtin_amdgcn_global_load_lds((const unsigned*)((const char*)(gbase) + (voff)[_i]), (LAS unsigned*)(lds + (bufoff) + ldsw + _i * 8192), 16, 0, 0); } while (0)
; #define PG8_LDA(dst, b, h) do { _Pragma("unroll") for (int m = 0; m < 4; ++m) _Pragma("unroll") for (int k = 0; k < 2; ++k) dst[m][k] = *(const LAS bf16x8*)(lds + PG8_SA(b, h) + aoff + m * 2048 + k * 1024); } while (0)
; #define PG8_LDB(dst, b, h) do { _Pragma("unroll") for (int n = 0; n < 2; ++n) _Pragma("unroll") for (int k = 0; k < 2; ++k) dst[n][k] = *(const LAS bf16x8*)(lds + PG8_SB(b, h) + boff + n * 2048 + k * 1024); } while (0)
; #define PG8_MMA(ai, bj, At, Bt) do { __builtin_amdgcn_s_setprio(1); _Pragma("unroll") for (int m = 0; m < 4; ++m) _Pragma("unroll") for (int n = 0; n < 2; ++n) _Pragma("unroll") for (int k = 0; k < 2; ++k) \
;         acc[ai][bj][m][n] = __builtin_amdgcn_mfma_f32_16x16x32_bf16(Bt[n][k], At[m][k], acc[ai][bj][m][n], 0, 0, 0); __builtin_amdgcn_s_setprio(0); } while (0)
; #define PG8_WAIT_V(n) asm volatile("s_waitcnt vmcnt(" #n ")" ::: "memory")
; #define PG8_WAIT_L(n) asm volatile("s_waitcnt lgkmcnt(" #n ")" ::: "memory")
; template <class Epi, class Sched, bool ALIGN_EPI, bool LAST_FUSED = false, bool PERM = false, bool CARRY = false>
; __device__ __forceinline__ void gemm_phase(LAS unsigned char* lds, const int tid, const int K, const int lda, const int ldb, const Sched& S, const Epi& E) {
;     ...
;         for (int t = 0; t < nt; t += 2) {
;             const bool last = (t == nt - 2);
;             const char* a1 = cA + (size_t)(t + 1) * kstep;
;             const char* a2 = last ? nA : cA + (size_t)(t + 2) * kstep; const char* b2 = last ? nB : cB + (size_t)(t + 2) * kstep;
;             const char* a3 = a2 + kstep; const char* b3 = b2 + kstep;
;             PG8_LDB(B0, 0, 0); PG8_LDB(B1, 0, 1); PG8_SCHED; PG8_LDA(At, 0, 0); PG8_STAGE(PG8_SA(1, 1), a1 + hstepA, voffA);
;             PG8_WAIT_V(8); PG8_WAIT_L(0); PG8_BAR; PG8_MMA(0, 0, At, B0); PG8_MMA(0, 1, At, B1); PG8_BAR; PG8_SCHED;
;             PG8_LDA(At, 0, 1); PG8_STAGE(PG8_SB(0, 0), b2, voffB); PG8_STAGE(PG8_SB(0, 1), b2 + hstepB, voffB); PG8_STAGE(PG8_SA(0, 0), a2, voffA);
;             PG8_WAIT_V(8); PG8_WAIT_L(0); PG8_BAR; PG8_MMA(1, 0, At, B0); PG8_MMA(1, 1, At, B1); PG8_BAR; PG8_SCHED;
.LBB0_1763:
	s_add_u32 s16, s48, 0xfff80080
	s_addc_u32 s17, s49, -1
	s_add_i32 s67, 0, 0x10000
	s_cmp_eq_u32 s41, 28
	s_cselect_b32 s53, s43, s17
	s_cselect_b32 s52, s42, s16
	v_add_u32_e32 v140, s67, v146
	s_cselect_b32 s55, s51, s39
	s_cselect_b32 s54, s50, s27
	s_add_i32 s16, 0, 0x14000
	ds_read_b128 v[148:151], v140
	ds_read_b128 v[152:155], v140 offset:1024
	ds_read_b128 v[156:159], v140 offset:2048
	ds_read_b128 v[160:163], v140 offset:3072
	v_add_u32_e32 v140, s16, v146
	ds_read_b128 v[164:167], v140
	ds_read_b128 v[168:171], v140 offset:1024
	ds_read_b128 v[172:175], v140 offset:2048
	ds_read_b128 v[176:179], v140 offset:3072
	v_lshl_add_u64 v[140:141], s[48:49], 0, v[136:137]
	s_add_i32 m0, s47, 0xc000
	ds_read_b128 v[180:183], v147
	ds_read_b128 v[184:187], v147 offset:1024
	ds_read_b128 v[188:191], v147 offset:2048
	ds_read_b128 v[192:195], v147 offset:3072
	ds_read_b128 v[196:199], v147 offset:4096
	ds_read_b128 v[200:203], v147 offset:5120
	ds_read_b128 v[204:207], v147 offset:6144
	ds_read_b128 v[208:211], v147 offset:7168
	global_load_lds_dwordx4 v[140:141], off
	v_lshl_add_u64 v[140:141], s[48:49], 0, v[138:139]
	s_add_i32 m0, s47, 0xe000
	s_nop 0
	global_load_lds_dwordx4 v[140:141], off
	s_waitcnt vmcnt(8)
	s_waitcnt lgkmcnt(0)
	s_barrier
	s_setprio 1
	s_waitcnt lgkmcnt(0)
	v_mfma_f32_16x16x32_bf16 v[126:129], v[148:151], v[180:183], v[126:129]
	v_mfma_f32_16x16x32_bf16 v[122:125], v[156:159], v[180:183], v[122:125]
	v_mfma_f32_16x16x32_bf16 v[110:113], v[148:151], v[188:191], v[110:113]
	v_mfma_f32_16x16x32_bf16 v[106:109], v[156:159], v[188:191], v[106:109]
	v_mfma_f32_16x16x32_bf16 v[94:97], v[148:151], v[196:199], v[94:97]
	v_mfma_f32_16x16x32_bf16 v[90:93], v[156:159], v[196:199], v[90:93]
	v_mfma_f32_16x16x32_bf16 v[78:81], v[148:151], v[204:207], v[78:81]
	v_mfma_f32_16x16x32_bf16 v[74:77], v[156:159], v[204:207], v[74:77]
	v_mfma_f32_16x16x32_bf16 v[126:129], v[152:155], v[184:187], v[126:129]
	v_mfma_f32_16x16x32_bf16 v[122:125], v[160:163], v[184:187], v[122:125]
	v_mfma_f32_16x16x32_bf16 v[110:113], v[152:155], v[192:195], v[110:113]
	v_mfma_f32_16x16x32_bf16 v[106:109], v[160:163], v[192:195], v[106:109]
	v_mfma_f32_16x16x32_bf16 v[94:97], v[152:155], v[200:203], v[94:97]
	v_mfma_f32_16x16x32_bf16 v[90:93], v[160:163], v[200:203], v[90:93]
	v_mfma_f32_16x16x32_bf16 v[78:81], v[152:155], v[208:211], v[78:81]
	v_mfma_f32_16x16x32_bf16 v[74:77], v[160:163], v[208:211], v[74:77]
	v_mfma_f32_16x16x32_bf16 v[118:121], v[164:167], v[180:183], v[118:121]
	v_mfma_f32_16x16x32_bf16 v[114:117], v[172:175], v[180:183], v[114:117]
	v_mfma_f32_16x16x32_bf16 v[102:105], v[164:167], v[188:191], v[102:105]
	v_mfma_f32_16x16x32_bf16 v[98:101], v[172:175], v[188:191], v[98:101]
	v_mfma_f32_16x16x32_bf16 v[86:89], v[164:167], v[196:199], v[86:89]
	v_mfma_f32_16x16x32_bf16 v[82:85], v[172:175], v[196:199], v[82:85]
	v_mfma_f32_16x16x32_bf16 v[70:73], v[164:167], v[204:207], v[70:73]
	v_mfma_f32_16x16x32_bf16 v[66:69], v[172:175], v[204:207], v[66:69]
	v_mfma_f32_16x16x32_bf16 v[118:121], v[168:171], v[184:187], v[118:121]
	v_mfma_f32_16x16x32_bf16 v[114:117], v[176:179], v[184:187], v[114:117]
	v_mfma_f32_16x16x32_bf16 v[102:105], v[168:171], v[192:195], v[102:105]
	v_mfma_f32_16x16x32_bf16 v[98:101], v[176:179], v[192:195], v[98:101]
	v_mfma_f32_16x16x32_bf16 v[86:89], v[168:171], v[200:203], v[86:89]
	v_mfma_f32_16x16x32_bf16 v[82:85], v[176:179], v[200:203], v[82:85]
	v_mfma_f32_16x16x32_bf16 v[70:73], v[168:171], v[208:211], v[70:73]
	v_mfma_f32_16x16x32_bf16 v[66:69], v[176:179], v[208:211], v[66:69]
	s_setprio 0
	s_barrier
	s_add_i32 s17, s67, s45
	v_lshl_add_u64 v[140:141], s[54:55], 0, v[0:1]
	s_mov_b32 m0, s17
	ds_read_b128 v[180:183], v147 offset:16384
	ds_read_b128 v[184:187], v147 offset:17408
	ds_read_b128 v[188:191], v147 offset:18432
	ds_read_b128 v[192:195], v147 offset:19456
	ds_read_b128 v[196:199], v147 offset:20480
	ds_read_b128 v[200:203], v147 offset:21504
	ds_read_b128 v[204:207], v147 offset:22528
	ds_read_b128 v[208:211], v147 offset:23552
	global_load_lds_dwordx4 v[140:141], off
	s_add_i32 m0, s17, 0x2000
	s_add_u32 s70, s54, 0x80000
	v_lshl_add_u64 v[212:213], s[54:55], 0, v[130:131]
	s_addc_u32 s71, s55, 0
	s_add_i32 s16, s16, s45
	global_load_lds_dwordx4 v[212:213], off
	v_lshl_add_u64 v[214:215], s[70:71], 0, v[0:1]
	s_mov_b32 m0, s16
	v_lshl_add_u64 v[216:217], s[52:53], 0, v[132:133]
	global_load_lds_dwordx4 v[214:215], off
	v_lshl_add_u64 v[214:215], s[70:71], 0, v[130:131]
	s_add_i32 m0, s16, 0x2000
	s_nop 0
	global_load_lds_dwordx4 v[214:215], off
	v_lshl_add_u64 v[214:215], s[52:53], 0, v[134:135]
	s_mov_b32 m0, s47
	s_nop 0
	global_load_lds_dwordx4 v[214:215], off
	s_mov_b32 m0, s57
	s_nop 0
	global_load_lds_dwordx4 v[216:217], off
	s_waitcnt vmcnt(8)
	s_waitcnt lgkmcnt(0)
	s_barrier
; #define PG8_STAGE(bufoff, gbase, voff) do { _Pragma("unroll") for (int _i = 0; _i < 2; ++_i) \
;         __builtin_amdgcn_global_load_lds((const unsigned*)((const char*)(gbase) + (voff)[_i]), (LAS unsigned*)(lds + (bufoff) + ldsw + _i * 8192), 16, 0, 0); } while (0)
; #define PG8_LDA(dst, b, h) do { _Pragma("unroll") for (int m = 0; m < 4; ++m) _Pragma("unroll") for (int k = 0; k < 2; ++k) dst[m][k] = *(const LAS bf16x8*)(lds + PG8_SA(b, h) + aoff + m * 2048 + k * 1024); } while (0)
; #define PG8_LDB(dst, b, h) do { _Pragma("unroll") for (int n = 0; n < 2; ++n) _Pragma("unroll") for (int k = 0; k < 2; ++k) dst[n][k] = *(const LAS bf16x8*)(lds + PG8_SB(b, h) + boff + n * 2048 + k * 1024); } while (0)
; #define PG8_MMA(ai, bj, At, Bt) do { __builtin_amdgcn_s_setprio(1); _Pragma("unroll") for (int m = 0; m < 4; ++m) _Pragma("unroll") for (int n = 0; n < 2; ++n) _Pragma("unroll") for (int k = 0; k < 2; ++k) \
;         acc[ai][bj][m][n] = __builtin_amdgcn_mfma_f32_16x16x32_bf16(Bt[n][k], At[m][k], acc[ai][bj][m][n], 0, 0, 0); __builtin_amdgcn_s_setprio(0); } while (0)
; #define PG8_WAIT_V(n) asm volatile("s_waitcnt vmcnt(" #n ")" ::: "memory")
; #define PG8_WAIT_L(n) asm volatile("s_waitcnt lgkmcnt(" #n ")" ::: "memory")
; #define PG8_BAR __builtin_amdgcn_s_barrier()
; #define PG8_SCHED __builtin_amdgcn_sched_barrier(0)
; template <class Epi, class Sched, bool ALIGN_EPI, bool LAST_FUSED = false, bool PERM = false, bool CARRY = false>
; __device__ __forceinline__ void gemm_phase(LAS unsigned char* lds, const int tid, const int K, const int lda, const int ldb, const Sched& S, const Epi& E) {
;     ...
;             PG8_WAIT_V(8); PG8_WAIT_L(0); PG8_BAR; PG8_MMA(1, 0, At, B0); PG8_MMA(1, 1, At, B1); PG8_BAR; PG8_SCHED;
;             PG8_LDB(B0, 1, 0); PG8_LDB(B1, 1, 1); PG8_SCHED; PG8_LDA(At, 1, 0); PG8_STAGE(PG8_SA(0, 1), a2 + hstepA, voffA);
;             PG8_WAIT_V(8); PG8_WAIT_L(0); PG8_BAR; PG8_MMA(0, 0, At, B0); PG8_MMA(0, 1, At, B1); PG8_BAR; PG8_SCHED;
	s_setprio 1
	s_waitcnt lgkmcnt(0)
	v_mfma_f32_16x16x32_bf16 v[62:65], v[148:151], v[180:183], v[62:65]
	v_mfma_f32_16x16x32_bf16 v[58:61], v[156:159], v[180:183], v[58:61]
	v_mfma_f32_16x16x32_bf16 v[46:49], v[148:151], v[188:191], v[46:49]
	v_mfma_f32_16x16x32_bf16 v[42:45], v[156:159], v[188:191], v[42:45]
	v_mfma_f32_16x16x32_bf16 v[30:33], v[148:151], v[196:199], v[30:33]
	v_mfma_f32_16x16x32_bf16 v[26:29], v[156:159], v[196:199], v[26:29]
	v_mfma_f32_16x16x32_bf16 v[14:17], v[148:151], v[204:207], v[14:17]
	v_mfma_f32_16x16x32_bf16 v[10:13], v[156:159], v[204:207], v[10:13]
	v_mfma_f32_16x16x32_bf16 v[62:65], v[152:155], v[184:187], v[62:65]
	v_mfma_f32_16x16x32_bf16 v[58:61], v[160:163], v[184:187], v[58:61]
	v_mfma_f32_16x16x32_bf16 v[46:49], v[152:155], v[192:195], v[46:49]
	v_mfma_f32_16x16x32_bf16 v[42:45], v[160:163], v[192:195], v[42:45]
	v_mfma_f32_16x16x32_bf16 v[30:33], v[152:155], v[200:203], v[30:33]
	v_mfma_f32_16x16x32_bf16 v[26:29], v[160:163], v[200:203], v[26:29]
	v_mfma_f32_16x16x32_bf16 v[14:17], v[152:155], v[208:211], v[14:17]
	v_mfma_f32_16x16x32_bf16 v[10:13], v[160:163], v[208:211], v[10:13]
	v_mfma_f32_16x16x32_bf16 v[54:57], v[164:167], v[180:183], v[54:57]
	v_mfma_f32_16x16x32_bf16 v[50:53], v[172:175], v[180:183], v[50:53]
	v_mfma_f32_16x16x32_bf16 v[38:41], v[164:167], v[188:191], v[38:41]
	v_mfma_f32_16x16x32_bf16 v[34:37], v[172:175], v[188:191], v[34:37]
	v_mfma_f32_16x16x32_bf16 v[22:25], v[164:167], v[196:199], v[22:25]
	v_mfma_f32_16x16x32_bf16 v[18:21], v[172:175], v[196:199], v[18:21]
	v_mfma_f32_16x16x32_bf16 v[6:9], v[164:167], v[204:207], v[6:9]
	v_mfma_f32_16x16x32_bf16 v[2:5], v[172:175], v[204:207], v[2:5]
	v_mfma_f32_16x16x32_bf16 v[54:57], v[168:171], v[184:187], v[54:57]
	v_mfma_f32_16x16x32_bf16 v[50:53], v[176:179], v[184:187], v[50:53]
	v_mfma_f32_16x16x32_bf16 v[38:41], v[168:171], v[192:195], v[38:41]
	v_mfma_f32_16x16x32_bf16 v[34:37], v[176:179], v[192:195], v[34:37]
	v_mfma_f32_16x16x32_bf16 v[22:25], v[168:171], v[200:203], v[22:25]
	v_mfma_f32_16x16x32_bf16 v[18:21], v[176:179], v[200:203], v[18:21]
	v_mfma_f32_16x16x32_bf16 v[6:9], v[168:171], v[208:211], v[6:9]
	v_mfma_f32_16x16x32_bf16 v[2:5], v[176:179], v[208:211], v[2:5]
	s_setprio 0
	s_barrier
	s_add_i32 s16, 0, 0x18000
	s_add_i32 s17, 0, 0x1c000
	v_add_u32_e32 v160, s16, v146
	v_add_u32_e32 v176, s17, v146
	ds_read_b128 v[148:151], v160
	ds_read_b128 v[152:155], v160 offset:1024
	ds_read_b128 v[156:159], v160 offset:2048
	ds_read_b128 v[160:163], v160 offset:3072
	ds_read_b128 v[164:167], v176
	ds_read_b128 v[168:171], v176 offset:1024
	ds_read_b128 v[172:175], v176 offset:2048
	ds_read_b128 v[176:179], v176 offset:3072
	s_add_u32 s52, s52, 0x80000
	s_addc_u32 s53, s53, 0
	s_mov_b32 m0, s58
	v_lshl_add_u64 v[218:219], s[52:53], 0, v[134:135]
	ds_read_b128 v[180:183], v147 offset:32768
	ds_read_b128 v[184:187], v147 offset:33792
	ds_read_b128 v[188:191], v147 offset:34816
	ds_read_b128 v[192:195], v147 offset:35840
	ds_read_b128 v[196:199], v147 offset:36864
	ds_read_b128 v[200:203], v147 offset:37888
	ds_read_b128 v[204:207], v147 offset:38912
	ds_read_b128 v[208:211], v147 offset:39936
	global_load_lds_dwordx4 v[218:219], off
	v_lshl_add_u64 v[218:219], s[52:53], 0, v[132:133]
	s_mov_b32 m0, s59
	s_nop 0
	global_load_lds_dwordx4 v[218:219], off
	s_waitcnt vmcnt(8)
	s_waitcnt lgkmcnt(0)
	s_barrier
	s_setprio 1
	s_waitcnt lgkmcnt(0)
	v_mfma_f32_16x16x32_bf16 v[126:129], v[148:151], v[180:183], v[126:129]
	v_mfma_f32_16x16x32_bf16 v[122:125], v[156:159], v[180:183], v[122:125]
	v_mfma_f32_16x16x32_bf16 v[110:113], v[148:151], v[188:191], v[110:113]
	v_mfma_f32_16x16x32_bf16 v[106:109], v[156:159], v[188:191], v[106:109]
	v_mfma_f32_16x16x32_bf16 v[94:97], v[148:151], v[196:199], v[94:97]
	v_mfma_f32_16x16x32_bf16 v[90:93], v[156:159], v[196:199], v[90:93]
	v_mfma_f32_16x16x32_bf16 v[78:81], v[148:151], v[204:207], v[78:81]
	v_mfma_f32_16x16x32_bf16 v[74:77], v[156:159], v[204:207], v[74:77]
	v_mfma_f32_16x16x32_bf16 v[126:129], v[152:155], v[184:187], v[126:129]
	v_mfma_f32_16x16x32_bf16 v[122:125], v[160:163], v[184:187], v[122:125]
	v_mfma_f32_16x16x32_bf16 v[110:113], v[152:155], v[192:195], v[110:113]
	v_mfma_f32_16x16x32_bf16 v[106:109], v[160:163], v[192:195], v[106:109]
	v_mfma_f32_16x16x32_bf16 v[94:97], v[152:155], v[200:203], v[94:97]
	v_mfma_f32_16x16x32_bf16 v[90:93], v[160:163], v[200:203], v[90:93]
	v_mfma_f32_16x16x32_bf16 v[78:81], v[152:155], v[208:211], v[78:81]
	v_mfma_f32_16x16x32_bf16 v[74:77], v[160:163], v[208:211], v[74:77]
	v_mfma_f32_16x16x32_bf16 v[118:121], v[164:167], v[180:183], v[118:121]
	v_mfma_f32_16x16x32_bf16 v[114:117], v[172:175], v[180:183], v[114:117]
	v_mfma_f32_16x16x32_bf16 v[102:105], v[164:167], v[188:191], v[102:105]
	v_mfma_f32_16x16x32_bf16 v[98:101], v[172:175], v[188:191], v[98:101]
	v_mfma_f32_16x16x32_bf16 v[86:89], v[164:167], v[196:199], v[86:89]
	v_mfma_f32_16x16x32_bf16 v[82:85], v[172:175], v[196:199], v[82:85]
	v_mfma_f32_16x16x32_bf16 v[70:73], v[164:167], v[204:207], v[70:73]
	v_mfma_f32_16x16x32_bf16 v[66:69], v[172:175], v[204:207], v[66:69]
	v_mfma_f32_16x16x32_bf16 v[118:121], v[168:171], v[184:187], v[118:121]
	v_mfma_f32_16x16x32_bf16 v[114:117], v[176:179], v[184:187], v[114:117]
	v_mfma_f32_16x16x32_bf16 v[102:105], v[168:171], v[192:195], v[102:105]
	v_mfma_f32_16x16x32_bf16 v[98:101], v[176:179], v[192:195], v[98:101]
	v_mfma_f32_16x16x32_bf16 v[86:89], v[168:171], v[200:203], v[86:89]
	v_mfma_f32_16x16x32_bf16 v[82:85], v[176:179], v[200:203], v[82:85]
	v_mfma_f32_16x16x32_bf16 v[70:73], v[168:171], v[208:211], v[70:73]
	v_mfma_f32_16x16x32_bf16 v[66:69], v[176:179], v[208:211], v[66:69]
	s_setprio 0
	s_barrier
; #define PG8_STAGE(bufoff, gbase, voff) do { _Pragma("unroll") for (int _i = 0; _i < 2; ++_i) \
;         __builtin_amdgcn_global_load_lds((const unsigned*)((const char*)(gbase) + (voff)[_i]), (LAS unsigned*)(lds + (bufoff) + ldsw + _i * 8192), 16, 0, 0); } while (0)
; #define PG8_LDA(dst, b, h) do { _Pragma("unroll") for (int m = 0; m < 4; ++m) _Pragma("unroll") for (int k = 0; k < 2; ++k) dst[m][k] = *(const LAS bf16x8*)(lds + PG8_SA(b, h) + aoff + m * 2048 + k * 1024); } while (0)
; #define PG8_MMA(ai, bj, At, Bt) do { __builtin_amdgcn_s_setprio(1); _Pragma("unroll") for (int m = 0; m < 4; ++m) _Pragma("unroll") for (int n = 0; n < 2; ++n) _Pragma("unroll") for (int k = 0; k < 2; ++k) \
;         acc[ai][bj][m][n] = __builtin_amdgcn_mfma_f32_16x16x32_bf16(Bt[n][k], At[m][k], acc[ai][bj][m][n], 0, 0, 0); __builtin_amdgcn_s_setprio(0); } while (0)
; #define PG8_WAIT_V(n) asm volatile("s_waitcnt vmcnt(" #n ")" ::: "memory")
; #define PG8_WAIT_L(n) asm volatile("s_waitcnt lgkmcnt(" #n ")" ::: "memory")
; #define PG8_BAR __builtin_amdgcn_s_barrier()
; #define PG8_SCHED __builtin_amdgcn_sched_barrier(0)
; template <class Epi, class Sched, bool ALIGN_EPI, bool LAST_FUSED = false, bool PERM = false, bool CARRY = false>
; __device__ __forceinline__ void gemm_phase(LAS unsigned char* lds, const int tid, const int K, const int lda, const int ldb, const Sched& S, const Epi& E) {
;     ...
;             PG8_LDA(At, 1, 1); PG8_STAGE(PG8_SB(1, 0), b3, voffB); PG8_STAGE(PG8_SB(1, 1), b3 + hstepB, voffB); PG8_STAGE(PG8_SA(1, 0), a3, voffA);
;             PG8_WAIT_V(8); PG8_WAIT_L(0); PG8_BAR; PG8_MMA(1, 0, At, B0); PG8_MMA(1, 1, At, B1); PG8_BAR; PG8_SCHED;
;         }
;         if constexpr (ALIGN_EPI) { if (wr == 0) PG8_BAR; }
	s_add_i32 s16, s16, s45
	v_lshl_add_u64 v[140:141], v[140:141], 0, s[68:69]
	s_mov_b32 m0, s16
	ds_read_b128 v[180:183], v147 offset:49152
	ds_read_b128 v[184:187], v147 offset:50176
	ds_read_b128 v[188:191], v147 offset:51200
	ds_read_b128 v[192:195], v147 offset:52224
	ds_read_b128 v[196:199], v147 offset:53248
	ds_read_b128 v[200:203], v147 offset:54272
	ds_read_b128 v[204:207], v147 offset:55296
	ds_read_b128 v[208:211], v147 offset:56320
	global_load_lds_dwordx4 v[140:141], off
	s_add_i32 m0, s16, 0x2000
	s_add_u32 s52, s54, 0x80080
	v_lshl_add_u64 v[140:141], v[212:213], 0, s[68:69]
	s_addc_u32 s53, s55, 0
	s_add_i32 s16, s17, s45
	global_load_lds_dwordx4 v[140:141], off
	v_lshl_add_u64 v[140:141], s[52:53], 0, v[0:1]
	s_mov_b32 m0, s16
	s_nop 0
	global_load_lds_dwordx4 v[140:141], off
	v_lshl_add_u64 v[140:141], s[52:53], 0, v[130:131]
	s_add_i32 m0, s16, 0x2000
	s_nop 0
	global_load_lds_dwordx4 v[140:141], off
	v_lshl_add_u64 v[140:141], v[214:215], 0, s[68:69]
	s_mov_b32 m0, s61
	s_nop 0
	global_load_lds_dwordx4 v[140:141], off
	v_lshl_add_u64 v[140:141], v[216:217], 0, s[68:69]
	s_mov_b32 m0, s62
	s_nop 0
	global_load_lds_dwordx4 v[140:141], off
	s_waitcnt vmcnt(8)
	s_waitcnt lgkmcnt(0)
	s_barrier
	s_setprio 1
	s_waitcnt lgkmcnt(0)
	v_mfma_f32_16x16x32_bf16 v[62:65], v[148:151], v[180:183], v[62:65]
	v_mfma_f32_16x16x32_bf16 v[58:61], v[156:159], v[180:183], v[58:61]
	v_mfma_f32_16x16x32_bf16 v[46:49], v[148:151], v[188:191], v[46:49]
	v_mfma_f32_16x16x32_bf16 v[42:45], v[156:159], v[188:191], v[42:45]
	v_mfma_f32_16x16x32_bf16 v[30:33], v[148:151], v[196:199], v[30:33]
	v_mfma_f32_16x16x32_bf16 v[26:29], v[156:159], v[196:199], v[26:29]
	v_mfma_f32_16x16x32_bf16 v[14:17], v[148:151], v[204:207], v[14:17]
	v_mfma_f32_16x16x32_bf16 v[10:13], v[156:159], v[204:207], v[10:13]
	v_mfma_f32_16x16x32_bf16 v[62:65], v[152:155], v[184:187], v[62:65]
	v_mfma_f32_16x16x32_bf16 v[58:61], v[160:163], v[184:187], v[58:61]
	v_mfma_f32_16x16x32_bf16 v[46:49], v[152:155], v[192:195], v[46:49]
	v_mfma_f32_16x16x32_bf16 v[42:45], v[160:163], v[192:195], v[42:45]
	v_mfma_f32_16x16x32_bf16 v[30:33], v[152:155], v[200:203], v[30:33]
	v_mfma_f32_16x16x32_bf16 v[26:29], v[160:163], v[200:203], v[26:29]
	v_mfma_f32_16x16x32_bf16 v[14:17], v[152:155], v[208:211], v[14:17]
	v_mfma_f32_16x16x32_bf16 v[10:13], v[160:163], v[208:211], v[10:13]
	v_mfma_f32_16x16x32_bf16 v[54:57], v[164:167], v[180:183], v[54:57]
	v_mfma_f32_16x16x32_bf16 v[50:53], v[172:175], v[180:183], v[50:53]
	v_mfma_f32_16x16x32_bf16 v[38:41], v[164:167], v[188:191], v[38:41]
	v_mfma_f32_16x16x32_bf16 v[34:37], v[172:175], v[188:191], v[34:37]
	v_mfma_f32_16x16x32_bf16 v[22:25], v[164:167], v[196:199], v[22:25]
	v_mfma_f32_16x16x32_bf16 v[18:21], v[172:175], v[196:199], v[18:21]
	v_mfma_f32_16x16x32_bf16 v[6:9], v[164:167], v[204:207], v[6:9]
	v_mfma_f32_16x16x32_bf16 v[2:5], v[172:175], v[204:207], v[2:5]
	v_mfma_f32_16x16x32_bf16 v[54:57], v[168:171], v[184:187], v[54:57]
	v_mfma_f32_16x16x32_bf16 v[50:53], v[176:179], v[184:187], v[50:53]
	v_mfma_f32_16x16x32_bf16 v[38:41], v[168:171], v[192:195], v[38:41]
	v_mfma_f32_16x16x32_bf16 v[34:37], v[176:179], v[192:195], v[34:37]
	v_mfma_f32_16x16x32_bf16 v[22:25], v[168:171], v[200:203], v[22:25]
	v_mfma_f32_16x16x32_bf16 v[18:21], v[176:179], v[200:203], v[18:21]
	v_mfma_f32_16x16x32_bf16 v[6:9], v[168:171], v[208:211], v[6:9]
	v_mfma_f32_16x16x32_bf16 v[2:5], v[176:179], v[208:211], v[2:5]
	s_setprio 0
	s_barrier
	s_add_i32 s41, s41, 2
	s_add_u32 s48, s48, 0x100
	s_addc_u32 s49, s49, 0
	s_add_u32 s27, s27, 0x100
	s_addc_u32 s39, s39, 0
	s_cmp_gt_u32 s41, 29
	s_cbranch_scc0 .LBB0_1763
	s_and_b64 vcc, exec, s[36:37]
	s_cbranch_vccz .LBB0_1766
	s_barrier

; #define PG8_STAGE(bufoff, gbase, voff) do { _Pragma("unroll") for (int _i = 0; _i < 2; ++_i) \
;         __builtin_amdgcn_global_load_lds((const unsigned*)((const char*)(gbase) + (voff)[_i]), (LAS unsigned*)(lds + (bufoff) + ldsw + _i * 8192), 16, 0, 0); } while (0)
; #define PG8_LDA(dst, b, h) do { _Pragma("unroll") for (int m = 0; m < 4; ++m) _Pragma("unroll") for (int k = 0; k < 2; ++k) dst[m][k] = *(const LAS bf16x8*)(lds + PG8_SA(b, h) + aoff + m * 2048 + k * 1024); } while (0)
; #define PG8_LDB(dst, b, h) do { _Pragma("unroll") for (int n = 0; n < 2; ++n) _Pragma("unroll") for (int k = 0; k < 2; ++k) dst[n][k] = *(const LAS bf16x8*)(lds + PG8_SB(b, h) + boff + n * 2048 + k * 1024); } while (0)
; #define PG8_MMA(ai, bj, At, Bt) do { __builtin_amdgcn_s_setprio(1); _Pragma("unroll") for (int m = 0; m < 4; ++m) _Pragma("unroll") for (int n = 0; n < 2; ++n) _Pragma("unroll") for (int k = 0; k < 2; ++k) \
;         acc[ai][bj][m][n] = __builtin_amdgcn_mfma_f32_16x16x32_bf16(Bt[n][k], At[m][k], acc[ai][bj][m][n], 0, 0, 0); __builtin_amdgcn_s_setprio(0); } while (0)
; #define PG8_WAIT_V(n) asm volatile("s_waitcnt vmcnt(" #n ")" ::: "memory")
; #define PG8_WAIT_L(n) asm volatile("s_waitcnt lgkmcnt(" #n ")" ::: "memory")
; template <class Epi, class Sched, bool ALIGN_EPI, bool LAST_FUSED = false, bool PERM = false, bool CARRY = false>
; __device__ __forceinline__ void gemm_phase(LAS unsigned char* lds, const int tid, const int K, const int lda, const int ldb, const Sched& S, const Epi& E) {
;     ...
;         for (int t = 0; t < nt; t += 2) {
;             const bool last = (t == nt - 2);
;             const char* a1 = cA + (size_t)(t + 1) * kstep;
;             const char* a2 = last ? nA : cA + (size_t)(t + 2) * kstep; const char* b2 = last ? nB : cB + (size_t)(t + 2) * kstep;
;             const char* a3 = a2 + kstep; const char* b3 = b2 + kstep;
;             PG8_LDB(B0, 0, 0); PG8_LDB(B1, 0, 1); PG8_SCHED; PG8_LDA(At, 0, 0); PG8_STAGE(PG8_SA(1, 1), a1 + hstepA, voffA);
;             PG8_WAIT_V(8); PG8_WAIT_L(0); PG8_BAR; PG8_MMA(0, 0, At, B0); PG8_MMA(0, 1, At, B1); PG8_BAR; PG8_SCHED;
;             PG8_LDA(At, 0, 1); PG8_STAGE(PG8_SB(0, 0), b2, voffB); PG8_STAGE(PG8_SB(0, 1), b2 + hstepB, voffB); PG8_STAGE(PG8_SA(0, 0), a2, voffA);
;             PG8_WAIT_V(8); PG8_WAIT_L(0); PG8_BAR; PG8_MMA(1, 0, At, B0); PG8_MMA(1, 1, At, B1); PG8_BAR; PG8_SCHED;
.LBB0_1854:
	s_add_u32 s16, s66, vcc_lo
	s_addc_u32 s17, s67, vcc_hi
	s_add_u32 s52, s50, vcc_lo
	s_addc_u32 s53, s51, vcc_hi
	s_add_i32 s92, 0, 0x10000
	s_cmp_eq_u32 s87, s60
	s_cselect_b32 s57, s24, s17
	s_cselect_b32 s56, s91, s16
	v_add_u32_e32 v154, s92, v140
	s_cselect_b32 s53, s70, s53
	s_cselect_b32 s52, s71, s52
	s_add_i32 s93, 0, 0x14000
	ds_read_b128 v[142:145], v154
	ds_read_b128 v[146:149], v154 offset:1024
	ds_read_b128 v[150:153], v154 offset:2048
	ds_read_b128 v[158:161], v154 offset:3072
	v_add_u32_e32 v154, s93, v140
	ds_read_b128 v[162:165], v154
	ds_read_b128 v[166:169], v154 offset:1024
	ds_read_b128 v[170:173], v154 offset:2048
	ds_read_b128 v[174:177], v154 offset:3072
	v_lshl_add_u64 v[154:155], s[66:67], 0, v[138:139]
	s_add_i32 m0, s28, 0xc000
	ds_read_b128 v[178:181], v141
	ds_read_b128 v[182:185], v141 offset:1024
	ds_read_b128 v[186:189], v141 offset:2048
	ds_read_b128 v[190:193], v141 offset:3072
	ds_read_b128 v[194:197], v141 offset:4096
	ds_read_b128 v[198:201], v141 offset:5120
	ds_read_b128 v[202:205], v141 offset:6144
	ds_read_b128 v[206:209], v141 offset:7168
	global_load_lds_dwordx4 v[154:155], off
	v_lshl_add_u64 v[154:155], s[66:67], 0, v[128:129]
	s_add_i32 m0, s28, 0xe000
	s_nop 0
	global_load_lds_dwordx4 v[154:155], off
	s_waitcnt vmcnt(8)
	s_waitcnt lgkmcnt(0)
	s_barrier
	s_setprio 1
	s_waitcnt lgkmcnt(0)
	v_mfma_f32_16x16x32_bf16 v[118:121], v[142:145], v[178:181], v[118:121]
	v_mfma_f32_16x16x32_bf16 v[114:117], v[150:153], v[178:181], v[114:117]
	v_mfma_f32_16x16x32_bf16 v[110:113], v[142:145], v[186:189], v[110:113]
	v_mfma_f32_16x16x32_bf16 v[106:109], v[150:153], v[186:189], v[106:109]
	v_mfma_f32_16x16x32_bf16 v[86:89], v[142:145], v[194:197], v[86:89]
	v_mfma_f32_16x16x32_bf16 v[82:85], v[150:153], v[194:197], v[82:85]
	v_mfma_f32_16x16x32_bf16 v[78:81], v[142:145], v[202:205], v[78:81]
	v_mfma_f32_16x16x32_bf16 v[74:77], v[150:153], v[202:205], v[74:77]
	v_mfma_f32_16x16x32_bf16 v[118:121], v[146:149], v[182:185], v[118:121]
	v_mfma_f32_16x16x32_bf16 v[114:117], v[158:161], v[182:185], v[114:117]
	v_mfma_f32_16x16x32_bf16 v[110:113], v[146:149], v[190:193], v[110:113]
	v_mfma_f32_16x16x32_bf16 v[106:109], v[158:161], v[190:193], v[106:109]
	v_mfma_f32_16x16x32_bf16 v[86:89], v[146:149], v[198:201], v[86:89]
	v_mfma_f32_16x16x32_bf16 v[82:85], v[158:161], v[198:201], v[82:85]
	v_mfma_f32_16x16x32_bf16 v[78:81], v[146:149], v[206:209], v[78:81]
	v_mfma_f32_16x16x32_bf16 v[74:77], v[158:161], v[206:209], v[74:77]
	v_mfma_f32_16x16x32_bf16 v[98:101], v[162:165], v[178:181], v[98:101]
	v_mfma_f32_16x16x32_bf16 v[102:105], v[170:173], v[178:181], v[102:105]
	v_mfma_f32_16x16x32_bf16 v[90:93], v[162:165], v[186:189], v[90:93]
	v_mfma_f32_16x16x32_bf16 v[94:97], v[170:173], v[186:189], v[94:97]
	v_mfma_f32_16x16x32_bf16 v[66:69], v[162:165], v[194:197], v[66:69]
	v_mfma_f32_16x16x32_bf16 v[70:73], v[170:173], v[194:197], v[70:73]
	v_mfma_f32_16x16x32_bf16 v[50:53], v[162:165], v[202:205], v[50:53]
	v_mfma_f32_16x16x32_bf16 v[54:57], v[170:173], v[202:205], v[54:57]
	v_mfma_f32_16x16x32_bf16 v[98:101], v[166:169], v[182:185], v[98:101]
	v_mfma_f32_16x16x32_bf16 v[102:105], v[174:177], v[182:185], v[102:105]
	v_mfma_f32_16x16x32_bf16 v[90:93], v[166:169], v[190:193], v[90:93]
	v_mfma_f32_16x16x32_bf16 v[94:97], v[174:177], v[190:193], v[94:97]
	v_mfma_f32_16x16x32_bf16 v[66:69], v[166:169], v[198:201], v[66:69]
	v_mfma_f32_16x16x32_bf16 v[70:73], v[174:177], v[198:201], v[70:73]
	v_mfma_f32_16x16x32_bf16 v[50:53], v[166:169], v[206:209], v[50:53]
	v_mfma_f32_16x16x32_bf16 v[54:57], v[174:177], v[206:209], v[54:57]
	s_setprio 0
	s_barrier
	s_add_i32 s16, s92, s95
	v_lshl_add_u64 v[154:155], s[52:53], 0, v[0:1]
	s_mov_b32 m0, s16
	ds_read_b128 v[178:181], v141 offset:16384
	ds_read_b128 v[182:185], v141 offset:17408
	ds_read_b128 v[186:189], v141 offset:18432
	ds_read_b128 v[190:193], v141 offset:19456
	ds_read_b128 v[194:197], v141 offset:20480
	ds_read_b128 v[198:201], v141 offset:21504
	ds_read_b128 v[202:205], v141 offset:22528
	ds_read_b128 v[206:209], v141 offset:23552
	global_load_lds_dwordx4 v[154:155], off
	s_add_i32 m0, s16, 0x2000
	s_add_u32 s16, s52, 0x200000
	v_lshl_add_u64 v[210:211], s[52:53], 0, v[122:123]
	s_addc_u32 s17, s53, 0
	s_add_i32 s92, s93, s95
	global_load_lds_dwordx4 v[210:211], off
	v_lshl_add_u64 v[212:213], s[16:17], 0, v[0:1]
	s_mov_b32 m0, s92
	v_lshl_add_u64 v[214:215], s[56:57], 0, v[122:123]
	global_load_lds_dwordx4 v[212:213], off
	v_lshl_add_u64 v[212:213], s[16:17], 0, v[122:123]
	s_add_i32 m0, s92, 0x2000
	s_nop 0
	global_load_lds_dwordx4 v[212:213], off
	v_lshl_add_u64 v[212:213], s[56:57], 0, v[0:1]
	s_mov_b32 m0, s28
	s_nop 0
	global_load_lds_dwordx4 v[212:213], off
	s_mov_b32 m0, s29
	s_nop 0
	global_load_lds_dwordx4 v[214:215], off
	s_waitcnt vmcnt(8)
	s_waitcnt lgkmcnt(0)
	s_barrier
; #define PG8_STAGE(bufoff, gbase, voff) do { _Pragma("unroll") for (int _i = 0; _i < 2; ++_i) \
;         __builtin_amdgcn_global_load_lds((const unsigned*)((const char*)(gbase) + (voff)[_i]), (LAS unsigned*)(lds + (bufoff) + ldsw + _i * 8192), 16, 0, 0); } while (0)
; #define PG8_LDA(dst, b, h) do { _Pragma("unroll") for (int m = 0; m < 4; ++m) _Pragma("unroll") for (int k = 0; k < 2; ++k) dst[m][k] = *(const LAS bf16x8*)(lds + PG8_SA(b, h) + aoff + m * 2048 + k * 1024); } while (0)
; #define PG8_LDB(dst, b, h) do { _Pragma("unroll") for (int n = 0; n < 2; ++n) _Pragma("unroll") for (int k = 0; k < 2; ++k) dst[n][k] = *(const LAS bf16x8*)(lds + PG8_SB(b, h) + boff + n * 2048 + k * 1024); } while (0)
; #define PG8_MMA(ai, bj, At, Bt) do { __builtin_amdgcn_s_setprio(1); _Pragma("unroll") for (int m = 0; m < 4; ++m) _Pragma("unroll") for (int n = 0; n < 2; ++n) _Pragma("unroll") for (int k = 0; k < 2; ++k) \
;         acc[ai][bj][m][n] = __builtin_amdgcn_mfma_f32_16x16x32_bf16(Bt[n][k], At[m][k], acc[ai][bj][m][n], 0, 0, 0); __builtin_amdgcn_s_setprio(0); } while (0)
; #define PG8_WAIT_V(n) asm volatile("s_waitcnt vmcnt(" #n ")" ::: "memory")
; #define PG8_WAIT_L(n) asm volatile("s_waitcnt lgkmcnt(" #n ")" ::: "memory")
; #define PG8_BAR __builtin_amdgcn_s_barrier()
; #define PG8_SCHED __builtin_amdgcn_sched_barrier(0)
; template <class Epi, class Sched, bool ALIGN_EPI, bool LAST_FUSED = false, bool PERM = false, bool CARRY = false>
; __device__ __forceinline__ void gemm_phase(LAS unsigned char* lds, const int tid, const int K, const int lda, const int ldb, const Sched& S, const Epi& E) {
;     ...
;             PG8_WAIT_V(8); PG8_WAIT_L(0); PG8_BAR; PG8_MMA(1, 0, At, B0); PG8_MMA(1, 1, At, B1); PG8_BAR; PG8_SCHED;
;             PG8_LDB(B0, 1, 0); PG8_LDB(B1, 1, 1); PG8_SCHED; PG8_LDA(At, 1, 0); PG8_STAGE(PG8_SA(0, 1), a2 + hstepA, voffA);
;             PG8_WAIT_V(8); PG8_WAIT_L(0); PG8_BAR; PG8_MMA(0, 0, At, B0); PG8_MMA(0, 1, At, B1); PG8_BAR; PG8_SCHED;
	s_setprio 1
	s_waitcnt lgkmcnt(0)
	v_mfma_f32_16x16x32_bf16 v[62:65], v[142:145], v[178:181], v[62:65]
	v_mfma_f32_16x16x32_bf16 v[58:61], v[150:153], v[178:181], v[58:61]
	v_mfma_f32_16x16x32_bf16 v[38:41], v[142:145], v[186:189], v[38:41]
	v_mfma_f32_16x16x32_bf16 v[34:37], v[150:153], v[186:189], v[34:37]
	v_mfma_f32_16x16x32_bf16 v[22:25], v[142:145], v[194:197], v[22:25]
	v_mfma_f32_16x16x32_bf16 v[18:21], v[150:153], v[194:197], v[18:21]
	v_mfma_f32_16x16x32_bf16 v[134:137], v[142:145], v[202:205], v[134:137]
	v_mfma_f32_16x16x32_bf16 v[130:133], v[150:153], v[202:205], v[130:133]
	v_mfma_f32_16x16x32_bf16 v[62:65], v[146:149], v[182:185], v[62:65]
	v_mfma_f32_16x16x32_bf16 v[58:61], v[158:161], v[182:185], v[58:61]
	v_mfma_f32_16x16x32_bf16 v[38:41], v[146:149], v[190:193], v[38:41]
	v_mfma_f32_16x16x32_bf16 v[34:37], v[158:161], v[190:193], v[34:37]
	v_mfma_f32_16x16x32_bf16 v[22:25], v[146:149], v[198:201], v[22:25]
	v_mfma_f32_16x16x32_bf16 v[18:21], v[158:161], v[198:201], v[18:21]
	v_mfma_f32_16x16x32_bf16 v[134:137], v[146:149], v[206:209], v[134:137]
	v_mfma_f32_16x16x32_bf16 v[130:133], v[158:161], v[206:209], v[130:133]
	v_mfma_f32_16x16x32_bf16 v[42:45], v[162:165], v[178:181], v[42:45]
	v_mfma_f32_16x16x32_bf16 v[46:49], v[170:173], v[178:181], v[46:49]
	v_mfma_f32_16x16x32_bf16 v[26:29], v[162:165], v[186:189], v[26:29]
	v_mfma_f32_16x16x32_bf16 v[30:33], v[170:173], v[186:189], v[30:33]
	v_mfma_f32_16x16x32_bf16 v[14:17], v[162:165], v[194:197], v[14:17]
	v_mfma_f32_16x16x32_bf16 v[10:13], v[170:173], v[194:197], v[10:13]
	v_mfma_f32_16x16x32_bf16 v[6:9], v[162:165], v[202:205], v[6:9]
	v_mfma_f32_16x16x32_bf16 v[2:5], v[170:173], v[202:205], v[2:5]
	v_mfma_f32_16x16x32_bf16 v[42:45], v[166:169], v[182:185], v[42:45]
	v_mfma_f32_16x16x32_bf16 v[46:49], v[174:177], v[182:185], v[46:49]
	v_mfma_f32_16x16x32_bf16 v[26:29], v[166:169], v[190:193], v[26:29]
	v_mfma_f32_16x16x32_bf16 v[30:33], v[174:177], v[190:193], v[30:33]
	v_mfma_f32_16x16x32_bf16 v[14:17], v[166:169], v[198:201], v[14:17]
	v_mfma_f32_16x16x32_bf16 v[10:13], v[174:177], v[198:201], v[10:13]
	v_mfma_f32_16x16x32_bf16 v[6:9], v[166:169], v[206:209], v[6:9]
	v_mfma_f32_16x16x32_bf16 v[2:5], v[174:177], v[206:209], v[2:5]
	s_setprio 0
	s_barrier
	s_add_i32 s92, 0, 0x18000
	s_add_i32 s93, 0, 0x1c000
	v_add_u32_e32 v158, s92, v140
	v_add_u32_e32 v174, s93, v140
	ds_read_b128 v[142:145], v158
	ds_read_b128 v[146:149], v158 offset:1024
	ds_read_b128 v[150:153], v158 offset:2048
	ds_read_b128 v[158:161], v158 offset:3072
	ds_read_b128 v[162:165], v174
	ds_read_b128 v[166:169], v174 offset:1024
	ds_read_b128 v[170:173], v174 offset:2048
	ds_read_b128 v[174:177], v174 offset:3072
	s_add_u32 s16, s56, 0x200000
	s_addc_u32 s17, s57, 0
	s_mov_b32 m0, s14
	v_lshl_add_u64 v[216:217], s[16:17], 0, v[0:1]
	ds_read_b128 v[178:181], v141 offset:32768
	ds_read_b128 v[182:185], v141 offset:33792
	ds_read_b128 v[186:189], v141 offset:34816
	ds_read_b128 v[190:193], v141 offset:35840
	ds_read_b128 v[194:197], v141 offset:36864
	ds_read_b128 v[198:201], v141 offset:37888
	ds_read_b128 v[202:205], v141 offset:38912
	ds_read_b128 v[206:209], v141 offset:39936
	global_load_lds_dwordx4 v[216:217], off
	v_lshl_add_u64 v[216:217], s[16:17], 0, v[122:123]
	s_mov_b32 m0, s22
	s_nop 0
	global_load_lds_dwordx4 v[216:217], off
	s_waitcnt vmcnt(8)
	s_waitcnt lgkmcnt(0)
	s_barrier
	s_setprio 1
	s_waitcnt lgkmcnt(0)
	v_mfma_f32_16x16x32_bf16 v[118:121], v[142:145], v[178:181], v[118:121]
	v_mfma_f32_16x16x32_bf16 v[114:117], v[150:153], v[178:181], v[114:117]
	v_mfma_f32_16x16x32_bf16 v[110:113], v[142:145], v[186:189], v[110:113]
	v_mfma_f32_16x16x32_bf16 v[106:109], v[150:153], v[186:189], v[106:109]
	v_mfma_f32_16x16x32_bf16 v[86:89], v[142:145], v[194:197], v[86:89]
	v_mfma_f32_16x16x32_bf16 v[82:85], v[150:153], v[194:197], v[82:85]
	v_mfma_f32_16x16x32_bf16 v[78:81], v[142:145], v[202:205], v[78:81]
	v_mfma_f32_16x16x32_bf16 v[74:77], v[150:153], v[202:205], v[74:77]
	v_mfma_f32_16x16x32_bf16 v[118:121], v[146:149], v[182:185], v[118:121]
	v_mfma_f32_16x16x32_bf16 v[114:117], v[158:161], v[182:185], v[114:117]
	v_mfma_f32_16x16x32_bf16 v[110:113], v[146:149], v[190:193], v[110:113]
	v_mfma_f32_16x16x32_bf16 v[106:109], v[158:161], v[190:193], v[106:109]
	v_mfma_f32_16x16x32_bf16 v[86:89], v[146:149], v[198:201], v[86:89]
	v_mfma_f32_16x16x32_bf16 v[82:85], v[158:161], v[198:201], v[82:85]
	v_mfma_f32_16x16x32_bf16 v[78:81], v[146:149], v[206:209], v[78:81]
	v_mfma_f32_16x16x32_bf16 v[74:77], v[158:161], v[206:209], v[74:77]
	v_mfma_f32_16x16x32_bf16 v[98:101], v[162:165], v[178:181], v[98:101]
	v_mfma_f32_16x16x32_bf16 v[102:105], v[170:173], v[178:181], v[102:105]
	v_mfma_f32_16x16x32_bf16 v[90:93], v[162:165], v[186:189], v[90:93]
	v_mfma_f32_16x16x32_bf16 v[94:97], v[170:173], v[186:189], v[94:97]
	v_mfma_f32_16x16x32_bf16 v[66:69], v[162:165], v[194:197], v[66:69]
	v_mfma_f32_16x16x32_bf16 v[70:73], v[170:173], v[194:197], v[70:73]
	v_mfma_f32_16x16x32_bf16 v[50:53], v[162:165], v[202:205], v[50:53]
	v_mfma_f32_16x16x32_bf16 v[54:57], v[170:173], v[202:205], v[54:57]
	v_mfma_f32_16x16x32_bf16 v[98:101], v[166:169], v[182:185], v[98:101]
	v_mfma_f32_16x16x32_bf16 v[102:105], v[174:177], v[182:185], v[102:105]
	v_mfma_f32_16x16x32_bf16 v[90:93], v[166:169], v[190:193], v[90:93]
	v_mfma_f32_16x16x32_bf16 v[94:97], v[174:177], v[190:193], v[94:97]
	v_mfma_f32_16x16x32_bf16 v[66:69], v[166:169], v[198:201], v[66:69]
	v_mfma_f32_16x16x32_bf16 v[70:73], v[174:177], v[198:201], v[70:73]
	v_mfma_f32_16x16x32_bf16 v[50:53], v[166:169], v[206:209], v[50:53]
	v_mfma_f32_16x16x32_bf16 v[54:57], v[174:177], v[206:209], v[54:57]
	s_setprio 0
	s_barrier
; #define PG8_STAGE(bufoff, gbase, voff) do { _Pragma("unroll") for (int _i = 0; _i < 2; ++_i) \
;         __builtin_amdgcn_global_load_lds((const unsigned*)((const char*)(gbase) + (voff)[_i]), (LAS unsigned*)(lds + (bufoff) + ldsw + _i * 8192), 16, 0, 0); } while (0)
; #define PG8_LDA(dst, b, h) do { _Pragma("unroll") for (int m = 0; m < 4; ++m) _Pragma("unroll") for (int k = 0; k < 2; ++k) dst[m][k] = *(const LAS bf16x8*)(lds + PG8_SA(b, h) + aoff + m * 2048 + k * 1024); } while (0)
; #define PG8_MMA(ai, bj, At, Bt) do { __builtin_amdgcn_s_setprio(1); _Pragma("unroll") for (int m = 0; m < 4; ++m) _Pragma("unroll") for (int n = 0; n < 2; ++n) _Pragma("unroll") for (int k = 0; k < 2; ++k) \
;         acc[ai][bj][m][n] = __builtin_amdgcn_mfma_f32_16x16x32_bf16(Bt[n][k], At[m][k], acc[ai][bj][m][n], 0, 0, 0); __builtin_amdgcn_s_setprio(0); } while (0)
; #define PG8_WAIT_V(n) asm volatile("s_waitcnt vmcnt(" #n ")" ::: "memory")
; #define PG8_WAIT_L(n) asm volatile("s_waitcnt lgkmcnt(" #n ")" ::: "memory")
; #define PG8_BAR __builtin_amdgcn_s_barrier()
; #define PG8_SCHED __builtin_amdgcn_sched_barrier(0)
; template <class Epi, class Sched, bool ALIGN_EPI, bool LAST_FUSED = false, bool PERM = false, bool CARRY = false>
; __device__ __forceinline__ void gemm_phase(LAS unsigned char* lds, const int tid, const int K, const int lda, const int ldb, const Sched& S, const Epi& E) {
;     ...
;             PG8_LDA(At, 1, 1); PG8_STAGE(PG8_SB(1, 0), b3, voffB); PG8_STAGE(PG8_SB(1, 1), b3 + hstepB, voffB); PG8_STAGE(PG8_SA(1, 0), a3, voffA);
;             PG8_WAIT_V(8); PG8_WAIT_L(0); PG8_BAR; PG8_MMA(1, 0, At, B0); PG8_MMA(1, 1, At, B1); PG8_BAR; PG8_SCHED;
;         }
;         if constexpr (ALIGN_EPI) { if (wr == 0) PG8_BAR; }
	s_add_i32 s16, s92, s95
	v_lshl_add_u64 v[154:155], v[154:155], 0, s[68:69]
	s_mov_b32 m0, s16
	ds_read_b128 v[178:181], v141 offset:49152
	ds_read_b128 v[182:185], v141 offset:50176
	ds_read_b128 v[186:189], v141 offset:51200
	ds_read_b128 v[190:193], v141 offset:52224
	ds_read_b128 v[194:197], v141 offset:53248
	ds_read_b128 v[198:201], v141 offset:54272
	ds_read_b128 v[202:205], v141 offset:55296
	ds_read_b128 v[206:209], v141 offset:56320
	global_load_lds_dwordx4 v[154:155], off
	s_add_i32 m0, s16, 0x2000
	s_add_u32 s16, s52, 0x200080
	v_lshl_add_u64 v[154:155], v[210:211], 0, s[68:69]
	s_addc_u32 s17, s53, 0
	s_add_i32 s52, s93, s95
	global_load_lds_dwordx4 v[154:155], off
	v_lshl_add_u64 v[154:155], s[16:17], 0, v[0:1]
	s_mov_b32 m0, s52
	s_nop 0
	global_load_lds_dwordx4 v[154:155], off
	v_lshl_add_u64 v[154:155], s[16:17], 0, v[122:123]
	s_add_i32 m0, s52, 0x2000
	s_nop 0
	global_load_lds_dwordx4 v[154:155], off
	v_lshl_add_u64 v[154:155], v[212:213], 0, s[68:69]
	s_mov_b32 m0, s96
	s_nop 0
	global_load_lds_dwordx4 v[154:155], off
	v_lshl_add_u64 v[154:155], v[214:215], 0, s[68:69]
	s_mov_b32 m0, s97
	s_nop 0
	global_load_lds_dwordx4 v[154:155], off
	s_waitcnt vmcnt(8)
	s_waitcnt lgkmcnt(0)
	s_barrier
	s_setprio 1
	s_waitcnt lgkmcnt(0)
	v_mfma_f32_16x16x32_bf16 v[62:65], v[142:145], v[178:181], v[62:65]
	v_mfma_f32_16x16x32_bf16 v[58:61], v[150:153], v[178:181], v[58:61]
	v_mfma_f32_16x16x32_bf16 v[38:41], v[142:145], v[186:189], v[38:41]
	v_mfma_f32_16x16x32_bf16 v[34:37], v[150:153], v[186:189], v[34:37]
	v_mfma_f32_16x16x32_bf16 v[22:25], v[142:145], v[194:197], v[22:25]
	v_mfma_f32_16x16x32_bf16 v[18:21], v[150:153], v[194:197], v[18:21]
	v_mfma_f32_16x16x32_bf16 v[134:137], v[142:145], v[202:205], v[134:137]
	v_mfma_f32_16x16x32_bf16 v[130:133], v[150:153], v[202:205], v[130:133]
	v_mfma_f32_16x16x32_bf16 v[62:65], v[146:149], v[182:185], v[62:65]
	v_mfma_f32_16x16x32_bf16 v[58:61], v[158:161], v[182:185], v[58:61]
	v_mfma_f32_16x16x32_bf16 v[38:41], v[146:149], v[190:193], v[38:41]
	v_mfma_f32_16x16x32_bf16 v[34:37], v[158:161], v[190:193], v[34:37]
	v_mfma_f32_16x16x32_bf16 v[22:25], v[146:149], v[198:201], v[22:25]
	v_mfma_f32_16x16x32_bf16 v[18:21], v[158:161], v[198:201], v[18:21]
	v_mfma_f32_16x16x32_bf16 v[134:137], v[146:149], v[206:209], v[134:137]
	v_mfma_f32_16x16x32_bf16 v[130:133], v[158:161], v[206:209], v[130:133]
	v_mfma_f32_16x16x32_bf16 v[42:45], v[162:165], v[178:181], v[42:45]
	v_mfma_f32_16x16x32_bf16 v[46:49], v[170:173], v[178:181], v[46:49]
	v_mfma_f32_16x16x32_bf16 v[26:29], v[162:165], v[186:189], v[26:29]
	v_mfma_f32_16x16x32_bf16 v[30:33], v[170:173], v[186:189], v[30:33]
	v_mfma_f32_16x16x32_bf16 v[14:17], v[162:165], v[194:197], v[14:17]
	v_mfma_f32_16x16x32_bf16 v[10:13], v[170:173], v[194:197], v[10:13]
	v_mfma_f32_16x16x32_bf16 v[6:9], v[162:165], v[202:205], v[6:9]
	v_mfma_f32_16x16x32_bf16 v[2:5], v[170:173], v[202:205], v[2:5]
	v_mfma_f32_16x16x32_bf16 v[42:45], v[166:169], v[182:185], v[42:45]
	v_mfma_f32_16x16x32_bf16 v[46:49], v[174:177], v[182:185], v[46:49]
	v_mfma_f32_16x16x32_bf16 v[26:29], v[166:169], v[190:193], v[26:29]
	v_mfma_f32_16x16x32_bf16 v[30:33], v[174:177], v[190:193], v[30:33]
	v_mfma_f32_16x16x32_bf16 v[14:17], v[166:169], v[198:201], v[14:17]
	v_mfma_f32_16x16x32_bf16 v[10:13], v[174:177], v[198:201], v[10:13]
	v_mfma_f32_16x16x32_bf16 v[6:9], v[166:169], v[206:209], v[6:9]
	v_mfma_f32_16x16x32_bf16 v[2:5], v[174:177], v[206:209], v[2:5]
	s_setprio 0
	s_barrier
	s_add_i32 s16, s60, 2
	s_add_u32 vcc_lo, vcc_lo, 0x100
	s_addc_u32 vcc_hi, vcc_hi, 0
	v_lshl_add_u64 v[138:139], v[138:139], 0, s[72:73]
	v_lshl_add_u64 v[128:129], v[128:129], 0, s[72:73]
	s_cmp_ge_i32 s60, s87
	s_mov_b32 s60, s16
	s_cbranch_scc0 .LBB0_1854
	s_and_b64 vcc, exec, s[40:41]
	s_cbranch_vccz .LBB0_1857
	s_barrier
